# K-loop: vmcnt(12) at phase 3/7 waits (legal: retired stage not read until two phases later), on top of v14
# speedup vs baseline: 1.0029x; 1.0005x over previous
; #define PG8_STAGE(bufoff, gbase, voff) do { _Pragma("unroll") for (int _i = 0; _i < 2; ++_i) \
;         __builtin_amdgcn_global_load_lds((const unsigned*)((const char*)(gbase) + (voff)[_i]), (LAS unsigned*)(lds + (bufoff) + ldsw + _i * 8192), 16, 0, 0); } while (0)
; #define PG8_LDA(dst, b, h) do { _Pragma("unroll") for (int m = 0; m < 4; ++m) _Pragma("unroll") for (int k = 0; k < 2; ++k) dst[m][k] = *(const LAS bf16x8*)(lds + PG8_SA(b, h) + aoff + m * 2048 + k * 1024); } while (0)
; #define PG8_LDB(dst, b, h) do { _Pragma("unroll") for (int n = 0; n < 2; ++n) _Pragma("unroll") for (int k = 0; k < 2; ++k) dst[n][k] = *(const LAS bf16x8*)(lds + PG8_SB(b, h) + boff + n * 2048 + k * 1024); } while (0)
; #define PG8_MMA(ai, bj, At, Bt) do { __builtin_amdgcn_s_setprio(1); _Pragma("unroll") for (int m = 0; m < 4; ++m) _Pragma("unroll") for (int n = 0; n < 2; ++n) _Pragma("unroll") for (int k = 0; k < 2; ++k) \
;         acc[ai][bj][m][n] = __builtin_amdgcn_mfma_f32_16x16x32_bf16(Bt[n][k], At[m][k], acc[ai][bj][m][n], 0, 0, 0); __builtin_amdgcn_s_setprio(0); } while (0)
; template <class Epi>
; __device__ __forceinline__ void gemm_phase(ldsp lds, const Gemm g, const StaticOrder& S, const Epi& E) {
;     ...
;             const bool last = (t == nt - 2);
;             const char* a1 = cA + (size_t)(t + 1) * kstep;
;             const char* a2 = last ? nA : cA + (size_t)(t + 2) * kstep; const char* b2 = last ? nB : cB + (size_t)(t + 2) * kstep;
;             const char* a3 = a2 + kstep; const char* b3 = b2 + kstep;
;             if constexpr (Epi::NPRE > 0) { if (last) E.pre(pre, cur, wr, fr); }
;             if constexpr (Epi::MID_T > 0) { if (t == Epi::MID_T) E.mid(acc, cur, wr, wc, fr, fq); }
;             PG8_LDB(B0, 0, 0); PG8_SCHED; PG8_LDA(At, 0, 0); PG8_STAGE(PG8_SA(1, 1), a1 + hstep, voffA);
;             PG8_WAIT_L(8); PG8_WAIT_V(10); PG8_BAR; PG8_WAIT_L(0); PG8_MMA(0, 0, At, B0); PG8_BAR; PG8_SCHED;
;             PG8_LDB(B1, 0, 1); PG8_STAGE(PG8_SB(0, 0), b2, voffB);
;             PG8_WAIT_V(10); PG8_BAR; PG8_WAIT_L(0); PG8_MMA(0, 1, At, B1); PG8_BAR;
;             PG8_LDA(At, 0, 1); PG8_STAGE(PG8_SA(0, 0), a2, voffA);
;             PG8_WAIT_V(10); PG8_BAR; PG8_WAIT_L(0); PG8_MMA(1, 0, At, B0); PG8_BAR; PG8_SCHED;
;             PG8_STAGE(PG8_SB(0, 1), b2 + hstep, voffB);
;             PG8_WAIT_V(10); PG8_BAR; PG8_MMA(1, 1, At, B1); PG8_BAR;
.LBB0_133:
	ds_read_b128 v[166:169], v247 offset:0
	ds_read_b128 v[170:173], v247 offset:1024
	ds_read_b128 v[174:177], v247 offset:2048
	ds_read_b128 v[184:187], v247 offset:3072
	s_add_u32 s38, s4, 0xfff80080
	s_addc_u32 s39, s5, -1
	s_and_b64 s[36:37], s[36:37], exec
	s_cselect_b32 s39, s7, s39
	s_cselect_b32 s38, s29, s38
	s_cselect_b32 s37, s27, s42
	s_cselect_b32 s36, s40, s41
	s_add_i32 m0, s45, 0xc000
	ds_read_b128 v[188:191], v183
	ds_read_b128 v[192:195], v183 offset:1024
	ds_read_b128 v[196:199], v183 offset:2048
	ds_read_b128 v[200:203], v183 offset:3072
	ds_read_b128 v[204:207], v183 offset:4096
	ds_read_b128 v[208:211], v183 offset:5120
	ds_read_b128 v[212:215], v183 offset:6144
	ds_read_b128 v[216:219], v183 offset:7168
	global_load_lds_dwordx4 v138, s[4:5]
	s_add_i32 m0, s45, 0xe000
	s_nop 0
	global_load_lds_dwordx4 v140, s[4:5]
	s_waitcnt lgkmcnt(8)
	s_waitcnt vmcnt(10)
	s_barrier
	s_waitcnt lgkmcnt(0)
	s_setprio 1
	s_waitcnt lgkmcnt(0)
	v_mfma_f32_16x16x32_bf16 v[60:63], v[166:169], v[188:191], v[60:63]
	v_mfma_f32_16x16x32_bf16 v[56:59], v[174:177], v[188:191], v[56:59]
	v_mfma_f32_16x16x32_bf16 v[52:55], v[166:169], v[196:199], v[52:55]
	v_mfma_f32_16x16x32_bf16 v[48:51], v[174:177], v[196:199], v[48:51]
	v_mfma_f32_16x16x32_bf16 v[44:47], v[166:169], v[204:207], v[44:47]
	v_mfma_f32_16x16x32_bf16 v[40:43], v[174:177], v[204:207], v[40:43]
	v_mfma_f32_16x16x32_bf16 v[36:39], v[166:169], v[212:215], v[36:39]
	v_mfma_f32_16x16x32_bf16 v[32:35], v[174:177], v[212:215], v[32:35]
	v_mfma_f32_16x16x32_bf16 v[60:63], v[170:173], v[192:195], v[60:63]
	v_mfma_f32_16x16x32_bf16 v[56:59], v[184:187], v[192:195], v[56:59]
	v_mfma_f32_16x16x32_bf16 v[52:55], v[170:173], v[200:203], v[52:55]
	v_mfma_f32_16x16x32_bf16 v[48:51], v[184:187], v[200:203], v[48:51]
	v_mfma_f32_16x16x32_bf16 v[44:47], v[170:173], v[208:211], v[44:47]
	v_mfma_f32_16x16x32_bf16 v[40:43], v[184:187], v[208:211], v[40:43]
	v_mfma_f32_16x16x32_bf16 v[36:39], v[170:173], v[216:219], v[36:39]
	s_barrier
	v_mfma_f32_16x16x32_bf16 v[32:35], v[184:187], v[216:219], v[32:35]
	s_setprio 0
	s_add_i32 s59, s57, s44
	s_add_u32 s98, s36, 0x80
	s_addc_u32 s99, s37, 0
	s_mov_b32 m0, s59
	ds_read_b128 v[222:225], v247 offset:16384
	ds_read_b128 v[226:229], v247 offset:17408
	ds_read_b128 v[230:233], v247 offset:18432
	ds_read_b128 v[234:237], v247 offset:19456
	global_load_lds_dwordx4 v130, s[36:37]
	s_add_i32 m0, s59, 0x2000
	s_nop 0
	global_load_lds_dwordx4 v134, s[36:37]
	s_waitcnt vmcnt(10)
	s_barrier
	s_waitcnt lgkmcnt(0)
	s_setprio 1
	s_waitcnt lgkmcnt(0)
	v_mfma_f32_16x16x32_bf16 v[124:127], v[222:225], v[188:191], v[124:127]
	v_mfma_f32_16x16x32_bf16 v[120:123], v[230:233], v[188:191], v[120:123]
	v_mfma_f32_16x16x32_bf16 v[116:119], v[222:225], v[196:199], v[116:119]
	v_mfma_f32_16x16x32_bf16 v[112:115], v[230:233], v[196:199], v[112:115]
	v_mfma_f32_16x16x32_bf16 v[108:111], v[222:225], v[204:207], v[108:111]
	v_mfma_f32_16x16x32_bf16 v[104:107], v[230:233], v[204:207], v[104:107]
	v_mfma_f32_16x16x32_bf16 v[100:103], v[222:225], v[212:215], v[100:103]
	v_mfma_f32_16x16x32_bf16 v[96:99], v[230:233], v[212:215], v[96:99]
	v_mfma_f32_16x16x32_bf16 v[124:127], v[226:229], v[192:195], v[124:127]
	v_mfma_f32_16x16x32_bf16 v[120:123], v[234:237], v[192:195], v[120:123]
	v_mfma_f32_16x16x32_bf16 v[116:119], v[226:229], v[200:203], v[116:119]
	v_mfma_f32_16x16x32_bf16 v[112:115], v[234:237], v[200:203], v[112:115]
	v_mfma_f32_16x16x32_bf16 v[108:111], v[226:229], v[208:211], v[108:111]
	v_mfma_f32_16x16x32_bf16 v[104:107], v[234:237], v[208:211], v[104:107]
	v_mfma_f32_16x16x32_bf16 v[100:103], v[226:229], v[216:219], v[100:103]
	s_barrier
	v_mfma_f32_16x16x32_bf16 v[96:99], v[234:237], v[216:219], v[96:99]
	s_setprio 0
	s_mov_b32 m0, s45
	s_add_u32 s100, s38, 0x80
	s_addc_u32 s101, s39, 0
	ds_read_b128 v[188:191], v183 offset:16384
	ds_read_b128 v[192:195], v183 offset:17408
	ds_read_b128 v[196:199], v183 offset:18432
	ds_read_b128 v[200:203], v183 offset:19456
	ds_read_b128 v[204:207], v183 offset:20480
	ds_read_b128 v[208:211], v183 offset:21504
	ds_read_b128 v[212:215], v183 offset:22528
	ds_read_b128 v[216:219], v183 offset:23552
	global_load_lds_dwordx4 v128, s[38:39]
	s_mov_b32 m0, s46
	s_nop 0
	global_load_lds_dwordx4 v132, s[38:39]
	s_waitcnt vmcnt(12)
	s_barrier
	s_waitcnt lgkmcnt(0)
	s_setprio 1
	s_waitcnt lgkmcnt(0)
	v_mfma_f32_16x16x32_bf16 v[28:31], v[166:169], v[188:191], v[28:31]
	v_mfma_f32_16x16x32_bf16 v[24:27], v[174:177], v[188:191], v[24:27]
	v_mfma_f32_16x16x32_bf16 v[20:23], v[166:169], v[196:199], v[20:23]
	v_mfma_f32_16x16x32_bf16 v[16:19], v[174:177], v[196:199], v[16:19]
	v_mfma_f32_16x16x32_bf16 v[12:15], v[166:169], v[204:207], v[12:15]
	v_mfma_f32_16x16x32_bf16 v[8:11], v[174:177], v[204:207], v[8:11]
	v_mfma_f32_16x16x32_bf16 v[4:7], v[166:169], v[212:215], v[4:7]
	v_mfma_f32_16x16x32_bf16 v[0:3], v[174:177], v[212:215], v[0:3]
	v_mfma_f32_16x16x32_bf16 v[28:31], v[170:173], v[192:195], v[28:31]
	v_mfma_f32_16x16x32_bf16 v[24:27], v[184:187], v[192:195], v[24:27]
	v_mfma_f32_16x16x32_bf16 v[20:23], v[170:173], v[200:203], v[20:23]
	v_mfma_f32_16x16x32_bf16 v[16:19], v[184:187], v[200:203], v[16:19]
	v_mfma_f32_16x16x32_bf16 v[12:15], v[170:173], v[208:211], v[12:15]
	v_mfma_f32_16x16x32_bf16 v[8:11], v[184:187], v[208:211], v[8:11]
	v_mfma_f32_16x16x32_bf16 v[4:7], v[170:173], v[216:219], v[4:7]
	s_barrier
	v_mfma_f32_16x16x32_bf16 v[0:3], v[184:187], v[216:219], v[0:3]
	s_setprio 0
	s_add_u32 s60, s36, 0x80000
	s_addc_u32 s61, s37, 0
	s_add_i32 s59, s58, s44
	s_mov_b32 m0, s59
	s_nop 0
	global_load_lds_dwordx4 v130, s[60:61]
	s_add_i32 m0, s59, 0x2000
	s_nop 0
	global_load_lds_dwordx4 v134, s[60:61]
	s_waitcnt vmcnt(10)
	s_barrier
; #define PG8_STAGE(bufoff, gbase, voff) do { _Pragma("unroll") for (int _i = 0; _i < 2; ++_i) \
;         __builtin_amdgcn_global_load_lds((const unsigned*)((const char*)(gbase) + (voff)[_i]), (LAS unsigned*)(lds + (bufoff) + ldsw + _i * 8192), 16, 0, 0); } while (0)
; #define PG8_LDA(dst, b, h) do { _Pragma("unroll") for (int m = 0; m < 4; ++m) _Pragma("unroll") for (int k = 0; k < 2; ++k) dst[m][k] = *(const LAS bf16x8*)(lds + PG8_SA(b, h) + aoff + m * 2048 + k * 1024); } while (0)
; #define PG8_LDB(dst, b, h) do { _Pragma("unroll") for (int n = 0; n < 2; ++n) _Pragma("unroll") for (int k = 0; k < 2; ++k) dst[n][k] = *(const LAS bf16x8*)(lds + PG8_SB(b, h) + boff + n * 2048 + k * 1024); } while (0)
; #define PG8_MMA(ai, bj, At, Bt) do { __builtin_amdgcn_s_setprio(1); _Pragma("unroll") for (int m = 0; m < 4; ++m) _Pragma("unroll") for (int n = 0; n < 2; ++n) _Pragma("unroll") for (int k = 0; k < 2; ++k) \
;         acc[ai][bj][m][n] = __builtin_amdgcn_mfma_f32_16x16x32_bf16(Bt[n][k], At[m][k], acc[ai][bj][m][n], 0, 0, 0); __builtin_amdgcn_s_setprio(0); } while (0)
; #define PG8_WAIT_V(n) asm volatile("s_waitcnt vmcnt(" #n ")" ::: "memory")
; #define PG8_WAIT_L(n) asm volatile("s_waitcnt lgkmcnt(" #n ")" ::: "memory")
; #define PG8_BAR __builtin_amdgcn_s_barrier()
; #define PG8_SCHED __builtin_amdgcn_sched_barrier(0)
; template <class Epi>
; __device__ __forceinline__ void gemm_phase(ldsp lds, const Gemm g, const StaticOrder& S, const Epi& E) {
;     ...
;             PG8_WAIT_V(10); PG8_BAR; PG8_MMA(1, 1, At, B1); PG8_BAR;
;             PG8_LDB(B0, 1, 0); PG8_SCHED; PG8_LDA(At, 1, 0); PG8_STAGE(PG8_SA(0, 1), a2 + hstep, voffA);
;             PG8_WAIT_L(8); PG8_WAIT_V(10); PG8_BAR; PG8_WAIT_L(0); PG8_MMA(0, 0, At, B0); PG8_BAR; PG8_SCHED;
;             PG8_LDB(B1, 1, 1); PG8_STAGE(PG8_SB(1, 0), b3, voffB);
;             PG8_WAIT_V(10); PG8_BAR; PG8_WAIT_L(0); PG8_MMA(0, 1, At, B1); PG8_BAR;
	s_nop 3
	s_setprio 1
	v_mfma_f32_16x16x32_bf16 v[92:95], v[222:225], v[188:191], v[92:95]
	v_mfma_f32_16x16x32_bf16 v[88:91], v[230:233], v[188:191], v[88:91]
	v_mfma_f32_16x16x32_bf16 v[84:87], v[222:225], v[196:199], v[84:87]
	v_mfma_f32_16x16x32_bf16 v[80:83], v[230:233], v[196:199], v[80:83]
	v_mfma_f32_16x16x32_bf16 v[76:79], v[222:225], v[204:207], v[76:79]
	v_mfma_f32_16x16x32_bf16 v[72:75], v[230:233], v[204:207], v[72:75]
	v_mfma_f32_16x16x32_bf16 v[68:71], v[222:225], v[212:215], v[68:71]
	v_mfma_f32_16x16x32_bf16 v[64:67], v[230:233], v[212:215], v[64:67]
	v_mfma_f32_16x16x32_bf16 v[92:95], v[226:229], v[192:195], v[92:95]
	v_mfma_f32_16x16x32_bf16 v[88:91], v[234:237], v[192:195], v[88:91]
	v_mfma_f32_16x16x32_bf16 v[84:87], v[226:229], v[200:203], v[84:87]
	v_mfma_f32_16x16x32_bf16 v[80:83], v[234:237], v[200:203], v[80:83]
	v_mfma_f32_16x16x32_bf16 v[76:79], v[226:229], v[208:211], v[76:79]
	v_mfma_f32_16x16x32_bf16 v[72:75], v[234:237], v[208:211], v[72:75]
	v_mfma_f32_16x16x32_bf16 v[68:71], v[226:229], v[216:219], v[68:71]
	s_barrier
	v_mfma_f32_16x16x32_bf16 v[64:67], v[234:237], v[216:219], v[64:67]
	s_setprio 0
	s_add_i32 s59, 0, 0x18000
	ds_read_b128 v[166:169], v247 offset:32768
	ds_read_b128 v[170:173], v247 offset:33792
	ds_read_b128 v[174:177], v247 offset:34816
	ds_read_b128 v[184:187], v247 offset:35840
	s_add_u32 s38, s38, 0x80000
	s_addc_u32 s39, s39, 0
	s_mov_b32 m0, s47
	ds_read_b128 v[188:191], v183 offset:32768
	ds_read_b128 v[192:195], v183 offset:33792
	ds_read_b128 v[196:199], v183 offset:34816
	ds_read_b128 v[200:203], v183 offset:35840
	ds_read_b128 v[204:207], v183 offset:36864
	ds_read_b128 v[208:211], v183 offset:37888
	ds_read_b128 v[212:215], v183 offset:38912
	ds_read_b128 v[216:219], v183 offset:39936
	global_load_lds_dwordx4 v128, s[38:39]
	s_mov_b32 m0, s50
	s_nop 0
	global_load_lds_dwordx4 v132, s[38:39]
	s_waitcnt lgkmcnt(8)
	s_waitcnt vmcnt(10)
	s_barrier
	s_waitcnt lgkmcnt(0)
	s_setprio 1
	s_waitcnt lgkmcnt(0)
	v_mfma_f32_16x16x32_bf16 v[60:63], v[166:169], v[188:191], v[60:63]
	v_mfma_f32_16x16x32_bf16 v[56:59], v[174:177], v[188:191], v[56:59]
	v_mfma_f32_16x16x32_bf16 v[52:55], v[166:169], v[196:199], v[52:55]
	v_mfma_f32_16x16x32_bf16 v[48:51], v[174:177], v[196:199], v[48:51]
	v_mfma_f32_16x16x32_bf16 v[44:47], v[166:169], v[204:207], v[44:47]
	v_mfma_f32_16x16x32_bf16 v[40:43], v[174:177], v[204:207], v[40:43]
	v_mfma_f32_16x16x32_bf16 v[36:39], v[166:169], v[212:215], v[36:39]
	v_mfma_f32_16x16x32_bf16 v[32:35], v[174:177], v[212:215], v[32:35]
	v_mfma_f32_16x16x32_bf16 v[60:63], v[170:173], v[192:195], v[60:63]
	v_mfma_f32_16x16x32_bf16 v[56:59], v[184:187], v[192:195], v[56:59]
	v_mfma_f32_16x16x32_bf16 v[52:55], v[170:173], v[200:203], v[52:55]
	v_mfma_f32_16x16x32_bf16 v[48:51], v[184:187], v[200:203], v[48:51]
	v_mfma_f32_16x16x32_bf16 v[44:47], v[170:173], v[208:211], v[44:47]
	v_mfma_f32_16x16x32_bf16 v[40:43], v[184:187], v[208:211], v[40:43]
	v_mfma_f32_16x16x32_bf16 v[36:39], v[170:173], v[216:219], v[36:39]
	s_barrier
	v_mfma_f32_16x16x32_bf16 v[32:35], v[184:187], v[216:219], v[32:35]
	s_setprio 0
	s_add_i32 s38, 0, 0x1c000
	s_add_i32 s39, s59, s44
	s_mov_b32 m0, s39
	ds_read_b128 v[222:225], v247 offset:49152
	ds_read_b128 v[226:229], v247 offset:50176
	ds_read_b128 v[230:233], v247 offset:51200
	ds_read_b128 v[234:237], v247 offset:52224
	global_load_lds_dwordx4 v130, s[98:99]
	s_add_i32 m0, s39, 0x2000
	s_nop 0
	global_load_lds_dwordx4 v134, s[98:99]
	s_waitcnt vmcnt(10)
	s_barrier
; #define PG8_STAGE(bufoff, gbase, voff) do { _Pragma("unroll") for (int _i = 0; _i < 2; ++_i) \
;         __builtin_amdgcn_global_load_lds((const unsigned*)((const char*)(gbase) + (voff)[_i]), (LAS unsigned*)(lds + (bufoff) + ldsw + _i * 8192), 16, 0, 0); } while (0)
; #define PG8_LDA(dst, b, h) do { _Pragma("unroll") for (int m = 0; m < 4; ++m) _Pragma("unroll") for (int k = 0; k < 2; ++k) dst[m][k] = *(const LAS bf16x8*)(lds + PG8_SA(b, h) + aoff + m * 2048 + k * 1024); } while (0)
; #define PG8_MMA(ai, bj, At, Bt) do { __builtin_amdgcn_s_setprio(1); _Pragma("unroll") for (int m = 0; m < 4; ++m) _Pragma("unroll") for (int n = 0; n < 2; ++n) _Pragma("unroll") for (int k = 0; k < 2; ++k) \
;         acc[ai][bj][m][n] = __builtin_amdgcn_mfma_f32_16x16x32_bf16(Bt[n][k], At[m][k], acc[ai][bj][m][n], 0, 0, 0); __builtin_amdgcn_s_setprio(0); } while (0)
; #define PG8_WAIT_V(n) asm volatile("s_waitcnt vmcnt(" #n ")" ::: "memory")
; #define PG8_WAIT_L(n) asm volatile("s_waitcnt lgkmcnt(" #n ")" ::: "memory")
; #define PG8_BAR __builtin_amdgcn_s_barrier()
; #define PG8_SCHED __builtin_amdgcn_sched_barrier(0)
; template <class Epi>
; __device__ __forceinline__ void gemm_phase(ldsp lds, const Gemm g, const StaticOrder& S, const Epi& E) {
;     ...
;             PG8_WAIT_V(10); PG8_BAR; PG8_WAIT_L(0); PG8_MMA(0, 1, At, B1); PG8_BAR;
;             PG8_LDA(At, 1, 1); PG8_STAGE(PG8_SA(1, 0), a3, voffA);
;             PG8_WAIT_V(10); PG8_BAR; PG8_WAIT_L(0); PG8_MMA(1, 0, At, B0); PG8_BAR; PG8_SCHED;
;             PG8_STAGE(PG8_SB(1, 1), b3 + hstep, voffB);
;             PG8_WAIT_V(10); PG8_BAR; PG8_MMA(1, 1, At, B1); PG8_BAR;
	s_waitcnt lgkmcnt(0)
	s_setprio 1
	s_waitcnt lgkmcnt(0)
	v_mfma_f32_16x16x32_bf16 v[124:127], v[222:225], v[188:191], v[124:127]
	v_mfma_f32_16x16x32_bf16 v[120:123], v[230:233], v[188:191], v[120:123]
	v_mfma_f32_16x16x32_bf16 v[116:119], v[222:225], v[196:199], v[116:119]
	v_mfma_f32_16x16x32_bf16 v[112:115], v[230:233], v[196:199], v[112:115]
	v_mfma_f32_16x16x32_bf16 v[108:111], v[222:225], v[204:207], v[108:111]
	v_mfma_f32_16x16x32_bf16 v[104:107], v[230:233], v[204:207], v[104:107]
	v_mfma_f32_16x16x32_bf16 v[100:103], v[222:225], v[212:215], v[100:103]
	v_mfma_f32_16x16x32_bf16 v[96:99], v[230:233], v[212:215], v[96:99]
	v_mfma_f32_16x16x32_bf16 v[124:127], v[226:229], v[192:195], v[124:127]
	v_mfma_f32_16x16x32_bf16 v[120:123], v[234:237], v[192:195], v[120:123]
	v_mfma_f32_16x16x32_bf16 v[116:119], v[226:229], v[200:203], v[116:119]
	v_mfma_f32_16x16x32_bf16 v[112:115], v[234:237], v[200:203], v[112:115]
	v_mfma_f32_16x16x32_bf16 v[108:111], v[226:229], v[208:211], v[108:111]
	v_mfma_f32_16x16x32_bf16 v[104:107], v[234:237], v[208:211], v[104:107]
	v_mfma_f32_16x16x32_bf16 v[100:103], v[226:229], v[216:219], v[100:103]
	s_barrier
	v_mfma_f32_16x16x32_bf16 v[96:99], v[234:237], v[216:219], v[96:99]
	s_setprio 0
	s_mov_b32 m0, s52
	ds_read_b128 v[188:191], v183 offset:49152
	ds_read_b128 v[192:195], v183 offset:50176
	ds_read_b128 v[196:199], v183 offset:51200
	ds_read_b128 v[200:203], v183 offset:52224
	ds_read_b128 v[204:207], v183 offset:53248
	ds_read_b128 v[208:211], v183 offset:54272
	ds_read_b128 v[212:215], v183 offset:55296
	ds_read_b128 v[216:219], v183 offset:56320
	global_load_lds_dwordx4 v128, s[100:101]
	s_mov_b32 m0, s53
	s_nop 0
	global_load_lds_dwordx4 v132, s[100:101]
	s_waitcnt vmcnt(12)
	s_barrier
	s_waitcnt lgkmcnt(0)
	s_setprio 1
	s_waitcnt lgkmcnt(0)
	v_mfma_f32_16x16x32_bf16 v[28:31], v[166:169], v[188:191], v[28:31]
	v_mfma_f32_16x16x32_bf16 v[24:27], v[174:177], v[188:191], v[24:27]
	v_mfma_f32_16x16x32_bf16 v[20:23], v[166:169], v[196:199], v[20:23]
	v_mfma_f32_16x16x32_bf16 v[16:19], v[174:177], v[196:199], v[16:19]
	v_mfma_f32_16x16x32_bf16 v[12:15], v[166:169], v[204:207], v[12:15]
	v_mfma_f32_16x16x32_bf16 v[8:11], v[174:177], v[204:207], v[8:11]
	v_mfma_f32_16x16x32_bf16 v[4:7], v[166:169], v[212:215], v[4:7]
	v_mfma_f32_16x16x32_bf16 v[0:3], v[174:177], v[212:215], v[0:3]
	v_mfma_f32_16x16x32_bf16 v[28:31], v[170:173], v[192:195], v[28:31]
	v_mfma_f32_16x16x32_bf16 v[24:27], v[184:187], v[192:195], v[24:27]
	v_mfma_f32_16x16x32_bf16 v[20:23], v[170:173], v[200:203], v[20:23]
	v_mfma_f32_16x16x32_bf16 v[16:19], v[184:187], v[200:203], v[16:19]
	v_mfma_f32_16x16x32_bf16 v[12:15], v[170:173], v[208:211], v[12:15]
	v_mfma_f32_16x16x32_bf16 v[8:11], v[184:187], v[208:211], v[8:11]
	v_mfma_f32_16x16x32_bf16 v[4:7], v[170:173], v[216:219], v[4:7]
	s_barrier
	v_mfma_f32_16x16x32_bf16 v[0:3], v[184:187], v[216:219], v[0:3]
	s_setprio 0
	s_add_u32 s36, s36, 0x80080
	s_addc_u32 s37, s37, 0
	s_add_i32 s38, s38, s44
	s_mov_b32 m0, s38
	s_nop 0
	global_load_lds_dwordx4 v130, s[36:37]
	s_add_i32 m0, s38, 0x2000
	s_nop 0
	global_load_lds_dwordx4 v134, s[36:37]
	s_waitcnt vmcnt(10)
	s_barrier
	s_nop 3
	s_setprio 1
	v_mfma_f32_16x16x32_bf16 v[92:95], v[222:225], v[188:191], v[92:95]
	v_mfma_f32_16x16x32_bf16 v[88:91], v[230:233], v[188:191], v[88:91]
	v_mfma_f32_16x16x32_bf16 v[84:87], v[222:225], v[196:199], v[84:87]
	v_mfma_f32_16x16x32_bf16 v[80:83], v[230:233], v[196:199], v[80:83]
	v_mfma_f32_16x16x32_bf16 v[76:79], v[222:225], v[204:207], v[76:79]
	v_mfma_f32_16x16x32_bf16 v[72:75], v[230:233], v[204:207], v[72:75]
	v_mfma_f32_16x16x32_bf16 v[68:71], v[222:225], v[212:215], v[68:71]
	v_mfma_f32_16x16x32_bf16 v[64:67], v[230:233], v[212:215], v[64:67]
	v_mfma_f32_16x16x32_bf16 v[92:95], v[226:229], v[192:195], v[92:95]
	v_mfma_f32_16x16x32_bf16 v[88:91], v[234:237], v[192:195], v[88:91]
	v_mfma_f32_16x16x32_bf16 v[84:87], v[226:229], v[200:203], v[84:87]
	v_mfma_f32_16x16x32_bf16 v[80:83], v[234:237], v[200:203], v[80:83]
	v_mfma_f32_16x16x32_bf16 v[76:79], v[226:229], v[208:211], v[76:79]
	v_mfma_f32_16x16x32_bf16 v[72:75], v[234:237], v[208:211], v[72:75]
	v_mfma_f32_16x16x32_bf16 v[68:71], v[226:229], v[216:219], v[68:71]
	s_barrier
	v_mfma_f32_16x16x32_bf16 v[64:67], v[234:237], v[216:219], v[64:67]
	s_setprio 0
	s_add_i32 s43, s43, 2
	s_add_u32 s4, s4, 0x100
	s_addc_u32 s5, s5, 0
	s_add_u32 s41, s41, 0x100
	s_addc_u32 s42, s42, 0
	s_cmp_gt_u32 s43, 29
	s_cbranch_scc1 .LBB0_136

; #define PG8_STAGE(bufoff, gbase, voff) do { _Pragma("unroll") for (int _i = 0; _i < 2; ++_i) \
;         __builtin_amdgcn_global_load_lds((const unsigned*)((const char*)(gbase) + (voff)[_i]), (LAS unsigned*)(lds + (bufoff) + ldsw + _i * 8192), 16, 0, 0); } while (0)
; #define PG8_LDA(dst, b, h) do { _Pragma("unroll") for (int m = 0; m < 4; ++m) _Pragma("unroll") for (int k = 0; k < 2; ++k) dst[m][k] = *(const LAS bf16x8*)(lds + PG8_SA(b, h) + aoff + m * 2048 + k * 1024); } while (0)
; #define PG8_LDB(dst, b, h) do { _Pragma("unroll") for (int n = 0; n < 2; ++n) _Pragma("unroll") for (int k = 0; k < 2; ++k) dst[n][k] = *(const LAS bf16x8*)(lds + PG8_SB(b, h) + boff + n * 2048 + k * 1024); } while (0)
; #define PG8_MMA(ai, bj, At, Bt) do { __builtin_amdgcn_s_setprio(1); _Pragma("unroll") for (int m = 0; m < 4; ++m) _Pragma("unroll") for (int n = 0; n < 2; ++n) _Pragma("unroll") for (int k = 0; k < 2; ++k) \
;         acc[ai][bj][m][n] = __builtin_amdgcn_mfma_f32_16x16x32_bf16(Bt[n][k], At[m][k], acc[ai][bj][m][n], 0, 0, 0); __builtin_amdgcn_s_setprio(0); } while (0)
; template <class Epi>
; __device__ __forceinline__ void gemm_phase(ldsp lds, const Gemm g, const StaticOrder& S, const Epi& E) {
;     ...
;             const bool last = (t == nt - 2);
;             const char* a1 = cA + (size_t)(t + 1) * kstep;
;             const char* a2 = last ? nA : cA + (size_t)(t + 2) * kstep; const char* b2 = last ? nB : cB + (size_t)(t + 2) * kstep;
;             const char* a3 = a2 + kstep; const char* b3 = b2 + kstep;
;             if constexpr (Epi::NPRE > 0) { if (last) E.pre(pre, cur, wr, fr); }
;             if constexpr (Epi::MID_T > 0) { if (t == Epi::MID_T) E.mid(acc, cur, wr, wc, fr, fq); }
;             PG8_LDB(B0, 0, 0); PG8_SCHED; PG8_LDA(At, 0, 0); PG8_STAGE(PG8_SA(1, 1), a1 + hstep, voffA);
;             PG8_WAIT_L(8); PG8_WAIT_V(10); PG8_BAR; PG8_WAIT_L(0); PG8_MMA(0, 0, At, B0); PG8_BAR; PG8_SCHED;
;             PG8_LDB(B1, 0, 1); PG8_STAGE(PG8_SB(0, 0), b2, voffB);
;             PG8_WAIT_V(10); PG8_BAR; PG8_WAIT_L(0); PG8_MMA(0, 1, At, B1); PG8_BAR;
;             PG8_LDA(At, 0, 1); PG8_STAGE(PG8_SA(0, 0), a2, voffA);
;             PG8_WAIT_V(10); PG8_BAR; PG8_WAIT_L(0); PG8_MMA(1, 0, At, B0); PG8_BAR; PG8_SCHED;
;             PG8_STAGE(PG8_SB(0, 1), b2 + hstep, voffB);
;             PG8_WAIT_V(10); PG8_BAR; PG8_MMA(1, 1, At, B1); PG8_BAR;
.LBB0_574:
	ds_read_b128 v[128:131], v219
	ds_read_b128 v[132:135], v219 offset:1024
	ds_read_b128 v[136:139], v219 offset:2048
	ds_read_b128 v[140:143], v219 offset:3072
	s_add_u32 s22, s20, 0xfffe0080
	s_addc_u32 s23, s21, -1
	s_cmp_eq_u32 s46, 4
	s_cselect_b32 s25, s13, s23
	s_cselect_b32 s24, s42, s22
	s_cselect_b32 s23, s11, s45
	s_cselect_b32 s22, s43, s44
	s_add_i32 m0, s19, 0xc000
	ds_read_b128 v[144:147], v221
	ds_read_b128 v[148:151], v221 offset:1024
	ds_read_b128 v[152:155], v221 offset:2048
	ds_read_b128 v[156:159], v221 offset:3072
	ds_read_b128 v[160:163], v221 offset:4096
	ds_read_b128 v[164:167], v221 offset:5120
	ds_read_b128 v[168:171], v221 offset:6144
	ds_read_b128 v[172:175], v221 offset:7168
	global_load_lds_dwordx4 v184, s[20:21]
	s_add_i32 m0, s19, 0xe000
	s_nop 0
	global_load_lds_dwordx4 v186, s[20:21]
	s_waitcnt lgkmcnt(8)
	s_waitcnt vmcnt(10)
	s_barrier
	s_waitcnt lgkmcnt(0)
	s_setprio 1
	s_waitcnt lgkmcnt(0)
	v_mfma_f32_16x16x32_bf16 v[124:127], v[128:131], v[144:147], v[124:127]
	v_mfma_f32_16x16x32_bf16 v[120:123], v[136:139], v[144:147], v[120:123]
	v_mfma_f32_16x16x32_bf16 v[116:119], v[128:131], v[152:155], v[116:119]
	v_mfma_f32_16x16x32_bf16 v[112:115], v[136:139], v[152:155], v[112:115]
	v_mfma_f32_16x16x32_bf16 v[108:111], v[128:131], v[160:163], v[108:111]
	v_mfma_f32_16x16x32_bf16 v[104:107], v[136:139], v[160:163], v[104:107]
	v_mfma_f32_16x16x32_bf16 v[100:103], v[128:131], v[168:171], v[100:103]
	v_mfma_f32_16x16x32_bf16 v[96:99], v[136:139], v[168:171], v[96:99]
	v_mfma_f32_16x16x32_bf16 v[124:127], v[132:135], v[148:151], v[124:127]
	v_mfma_f32_16x16x32_bf16 v[120:123], v[140:143], v[148:151], v[120:123]
	v_mfma_f32_16x16x32_bf16 v[116:119], v[132:135], v[156:159], v[116:119]
	v_mfma_f32_16x16x32_bf16 v[112:115], v[140:143], v[156:159], v[112:115]
	v_mfma_f32_16x16x32_bf16 v[108:111], v[132:135], v[164:167], v[108:111]
	v_mfma_f32_16x16x32_bf16 v[104:107], v[140:143], v[164:167], v[104:107]
	v_mfma_f32_16x16x32_bf16 v[100:103], v[132:135], v[172:175], v[100:103]
	s_barrier
	v_mfma_f32_16x16x32_bf16 v[96:99], v[140:143], v[172:175], v[96:99]
	s_setprio 0
	s_add_i32 s47, s38, s28
	s_add_u32 s98, s22, 0x80
	s_addc_u32 s99, s23, 0
	s_mov_b32 m0, s47
	ds_read_b128 v[192:195], v222
	ds_read_b128 v[196:199], v222 offset:1024
	ds_read_b128 v[200:203], v222 offset:2048
	ds_read_b128 v[204:207], v222 offset:3072
	global_load_lds_dwordx4 v178, s[22:23]
	s_add_i32 m0, s47, 0x2000
	s_nop 0
	global_load_lds_dwordx4 v182, s[22:23]
	s_waitcnt vmcnt(10)
	s_barrier
	s_waitcnt lgkmcnt(0)
	s_setprio 1
	s_waitcnt lgkmcnt(0)
	v_mfma_f32_16x16x32_bf16 v[60:63], v[192:195], v[144:147], v[60:63]
	v_mfma_f32_16x16x32_bf16 v[56:59], v[200:203], v[144:147], v[56:59]
	v_mfma_f32_16x16x32_bf16 v[52:55], v[192:195], v[152:155], v[52:55]
	v_mfma_f32_16x16x32_bf16 v[48:51], v[200:203], v[152:155], v[48:51]
	v_mfma_f32_16x16x32_bf16 v[44:47], v[192:195], v[160:163], v[44:47]
	v_mfma_f32_16x16x32_bf16 v[40:43], v[200:203], v[160:163], v[40:43]
	v_mfma_f32_16x16x32_bf16 v[36:39], v[192:195], v[168:171], v[36:39]
	v_mfma_f32_16x16x32_bf16 v[32:35], v[200:203], v[168:171], v[32:35]
	v_mfma_f32_16x16x32_bf16 v[60:63], v[196:199], v[148:151], v[60:63]
	v_mfma_f32_16x16x32_bf16 v[56:59], v[204:207], v[148:151], v[56:59]
	v_mfma_f32_16x16x32_bf16 v[52:55], v[196:199], v[156:159], v[52:55]
	v_mfma_f32_16x16x32_bf16 v[48:51], v[204:207], v[156:159], v[48:51]
	v_mfma_f32_16x16x32_bf16 v[44:47], v[196:199], v[164:167], v[44:47]
	v_mfma_f32_16x16x32_bf16 v[40:43], v[204:207], v[164:167], v[40:43]
	v_mfma_f32_16x16x32_bf16 v[36:39], v[196:199], v[172:175], v[36:39]
	s_barrier
	v_mfma_f32_16x16x32_bf16 v[32:35], v[204:207], v[172:175], v[32:35]
	s_setprio 0
	s_mov_b32 m0, s19
	s_add_u32 s100, s24, 0x80
	s_addc_u32 s101, s25, 0
	ds_read_b128 v[144:147], v221 offset:16384
	ds_read_b128 v[148:151], v221 offset:17408
	ds_read_b128 v[152:155], v221 offset:18432
	ds_read_b128 v[156:159], v221 offset:19456
	ds_read_b128 v[160:163], v221 offset:20480
	ds_read_b128 v[164:167], v221 offset:21504
	ds_read_b128 v[168:171], v221 offset:22528
	ds_read_b128 v[172:175], v221 offset:23552
	global_load_lds_dwordx4 v176, s[24:25]
	s_mov_b32 m0, s29
	s_nop 0
	global_load_lds_dwordx4 v180, s[24:25]
	s_waitcnt vmcnt(12)
	s_barrier
	s_waitcnt lgkmcnt(0)
	s_setprio 1
	s_waitcnt lgkmcnt(0)
	v_mfma_f32_16x16x32_bf16 v[92:95], v[128:131], v[144:147], v[92:95]
	v_mfma_f32_16x16x32_bf16 v[88:91], v[136:139], v[144:147], v[88:91]
	v_mfma_f32_16x16x32_bf16 v[84:87], v[128:131], v[152:155], v[84:87]
	v_mfma_f32_16x16x32_bf16 v[80:83], v[136:139], v[152:155], v[80:83]
	v_mfma_f32_16x16x32_bf16 v[76:79], v[128:131], v[160:163], v[76:79]
	v_mfma_f32_16x16x32_bf16 v[72:75], v[136:139], v[160:163], v[72:75]
	v_mfma_f32_16x16x32_bf16 v[68:71], v[128:131], v[168:171], v[68:71]
	v_mfma_f32_16x16x32_bf16 v[64:67], v[136:139], v[168:171], v[64:67]
	v_mfma_f32_16x16x32_bf16 v[92:95], v[132:135], v[148:151], v[92:95]
	v_mfma_f32_16x16x32_bf16 v[88:91], v[140:143], v[148:151], v[88:91]
	v_mfma_f32_16x16x32_bf16 v[84:87], v[132:135], v[156:159], v[84:87]
	v_mfma_f32_16x16x32_bf16 v[80:83], v[140:143], v[156:159], v[80:83]
	v_mfma_f32_16x16x32_bf16 v[76:79], v[132:135], v[164:167], v[76:79]
	v_mfma_f32_16x16x32_bf16 v[72:75], v[140:143], v[164:167], v[72:75]
	v_mfma_f32_16x16x32_bf16 v[68:71], v[132:135], v[172:175], v[68:71]
	s_barrier
	v_mfma_f32_16x16x32_bf16 v[64:67], v[140:143], v[172:175], v[64:67]
	s_setprio 0
	s_add_u32 s50, s22, 0x20000
	s_addc_u32 s51, s23, 0
	s_add_i32 s47, s39, s28
	s_mov_b32 m0, s47
	s_nop 0
	global_load_lds_dwordx4 v178, s[50:51]
	s_add_i32 m0, s47, 0x2000
	s_nop 0
	global_load_lds_dwordx4 v182, s[50:51]
	s_waitcnt vmcnt(10)
	s_barrier
; #define PG8_STAGE(bufoff, gbase, voff) do { _Pragma("unroll") for (int _i = 0; _i < 2; ++_i) \
;         __builtin_amdgcn_global_load_lds((const unsigned*)((const char*)(gbase) + (voff)[_i]), (LAS unsigned*)(lds + (bufoff) + ldsw + _i * 8192), 16, 0, 0); } while (0)
; #define PG8_LDA(dst, b, h) do { _Pragma("unroll") for (int m = 0; m < 4; ++m) _Pragma("unroll") for (int k = 0; k < 2; ++k) dst[m][k] = *(const LAS bf16x8*)(lds + PG8_SA(b, h) + aoff + m * 2048 + k * 1024); } while (0)
; #define PG8_LDB(dst, b, h) do { _Pragma("unroll") for (int n = 0; n < 2; ++n) _Pragma("unroll") for (int k = 0; k < 2; ++k) dst[n][k] = *(const LAS bf16x8*)(lds + PG8_SB(b, h) + boff + n * 2048 + k * 1024); } while (0)
; #define PG8_MMA(ai, bj, At, Bt) do { __builtin_amdgcn_s_setprio(1); _Pragma("unroll") for (int m = 0; m < 4; ++m) _Pragma("unroll") for (int n = 0; n < 2; ++n) _Pragma("unroll") for (int k = 0; k < 2; ++k) \
;         acc[ai][bj][m][n] = __builtin_amdgcn_mfma_f32_16x16x32_bf16(Bt[n][k], At[m][k], acc[ai][bj][m][n], 0, 0, 0); __builtin_amdgcn_s_setprio(0); } while (0)
; #define PG8_WAIT_V(n) asm volatile("s_waitcnt vmcnt(" #n ")" ::: "memory")
; #define PG8_WAIT_L(n) asm volatile("s_waitcnt lgkmcnt(" #n ")" ::: "memory")
; #define PG8_BAR __builtin_amdgcn_s_barrier()
; #define PG8_SCHED __builtin_amdgcn_sched_barrier(0)
; template <class Epi>
; __device__ __forceinline__ void gemm_phase(ldsp lds, const Gemm g, const StaticOrder& S, const Epi& E) {
;     ...
;             PG8_WAIT_V(10); PG8_BAR; PG8_MMA(1, 1, At, B1); PG8_BAR;
;             PG8_LDB(B0, 1, 0); PG8_SCHED; PG8_LDA(At, 1, 0); PG8_STAGE(PG8_SA(0, 1), a2 + hstep, voffA);
;             PG8_WAIT_L(8); PG8_WAIT_V(10); PG8_BAR; PG8_WAIT_L(0); PG8_MMA(0, 0, At, B0); PG8_BAR; PG8_SCHED;
;             PG8_LDB(B1, 1, 1); PG8_STAGE(PG8_SB(1, 0), b3, voffB);
;             PG8_WAIT_V(10); PG8_BAR; PG8_WAIT_L(0); PG8_MMA(0, 1, At, B1); PG8_BAR;
;             PG8_LDA(At, 1, 1); PG8_STAGE(PG8_SA(1, 0), a3, voffA);
;             PG8_WAIT_V(10); PG8_BAR; PG8_WAIT_L(0); PG8_MMA(1, 0, At, B0); PG8_BAR; PG8_SCHED;
	s_nop 3
	s_setprio 1
	v_mfma_f32_16x16x32_bf16 v[28:31], v[192:195], v[144:147], v[28:31]
	v_mfma_f32_16x16x32_bf16 v[24:27], v[200:203], v[144:147], v[24:27]
	v_mfma_f32_16x16x32_bf16 v[20:23], v[192:195], v[152:155], v[20:23]
	v_mfma_f32_16x16x32_bf16 v[16:19], v[200:203], v[152:155], v[16:19]
	v_mfma_f32_16x16x32_bf16 v[12:15], v[192:195], v[160:163], v[12:15]
	v_mfma_f32_16x16x32_bf16 v[8:11], v[200:203], v[160:163], v[8:11]
	v_mfma_f32_16x16x32_bf16 v[4:7], v[192:195], v[168:171], v[4:7]
	v_mfma_f32_16x16x32_bf16 v[0:3], v[200:203], v[168:171], v[0:3]
	v_mfma_f32_16x16x32_bf16 v[28:31], v[196:199], v[148:151], v[28:31]
	v_mfma_f32_16x16x32_bf16 v[24:27], v[204:207], v[148:151], v[24:27]
	v_mfma_f32_16x16x32_bf16 v[20:23], v[196:199], v[156:159], v[20:23]
	v_mfma_f32_16x16x32_bf16 v[16:19], v[204:207], v[156:159], v[16:19]
	v_mfma_f32_16x16x32_bf16 v[12:15], v[196:199], v[164:167], v[12:15]
	v_mfma_f32_16x16x32_bf16 v[8:11], v[204:207], v[164:167], v[8:11]
	v_mfma_f32_16x16x32_bf16 v[4:7], v[196:199], v[172:175], v[4:7]
	s_barrier
	v_mfma_f32_16x16x32_bf16 v[0:3], v[204:207], v[172:175], v[0:3]
	s_setprio 0
	s_add_i32 s47, 0, 0x18000
	ds_read_b128 v[128:131], v247 offset:32768
	ds_read_b128 v[132:135], v247 offset:33792
	ds_read_b128 v[136:139], v247 offset:34816
	ds_read_b128 v[140:143], v247 offset:35840
	s_add_u32 s24, s24, 0x20000
	s_addc_u32 s25, s25, 0
	s_mov_b32 m0, s30
	ds_read_b128 v[144:147], v221 offset:32768
	ds_read_b128 v[148:151], v221 offset:33792
	ds_read_b128 v[152:155], v221 offset:34816
	ds_read_b128 v[156:159], v221 offset:35840
	ds_read_b128 v[160:163], v221 offset:36864
	ds_read_b128 v[164:167], v221 offset:37888
	ds_read_b128 v[168:171], v221 offset:38912
	ds_read_b128 v[172:175], v221 offset:39936
	global_load_lds_dwordx4 v176, s[24:25]
	s_mov_b32 m0, s31
	s_nop 0
	global_load_lds_dwordx4 v180, s[24:25]
	s_waitcnt lgkmcnt(8)
	s_waitcnt vmcnt(10)
	s_barrier
	s_waitcnt lgkmcnt(0)
	s_setprio 1
	s_waitcnt lgkmcnt(0)
	v_mfma_f32_16x16x32_bf16 v[124:127], v[128:131], v[144:147], v[124:127]
	v_mfma_f32_16x16x32_bf16 v[120:123], v[136:139], v[144:147], v[120:123]
	v_mfma_f32_16x16x32_bf16 v[116:119], v[128:131], v[152:155], v[116:119]
	v_mfma_f32_16x16x32_bf16 v[112:115], v[136:139], v[152:155], v[112:115]
	v_mfma_f32_16x16x32_bf16 v[108:111], v[128:131], v[160:163], v[108:111]
	v_mfma_f32_16x16x32_bf16 v[104:107], v[136:139], v[160:163], v[104:107]
	v_mfma_f32_16x16x32_bf16 v[100:103], v[128:131], v[168:171], v[100:103]
	v_mfma_f32_16x16x32_bf16 v[96:99], v[136:139], v[168:171], v[96:99]
	v_mfma_f32_16x16x32_bf16 v[124:127], v[132:135], v[148:151], v[124:127]
	v_mfma_f32_16x16x32_bf16 v[120:123], v[140:143], v[148:151], v[120:123]
	v_mfma_f32_16x16x32_bf16 v[116:119], v[132:135], v[156:159], v[116:119]
	v_mfma_f32_16x16x32_bf16 v[112:115], v[140:143], v[156:159], v[112:115]
	v_mfma_f32_16x16x32_bf16 v[108:111], v[132:135], v[164:167], v[108:111]
	v_mfma_f32_16x16x32_bf16 v[104:107], v[140:143], v[164:167], v[104:107]
	v_mfma_f32_16x16x32_bf16 v[100:103], v[132:135], v[172:175], v[100:103]
	s_barrier
	v_mfma_f32_16x16x32_bf16 v[96:99], v[140:143], v[172:175], v[96:99]
	s_setprio 0
	s_add_i32 s24, 0, 0x1c000
	s_add_i32 s25, s47, s28
	s_mov_b32 m0, s25
	ds_read_b128 v[192:195], v247 offset:49152
	ds_read_b128 v[196:199], v247 offset:50176
	ds_read_b128 v[200:203], v247 offset:51200
	ds_read_b128 v[204:207], v247 offset:52224
	global_load_lds_dwordx4 v178, s[98:99]
	s_add_i32 m0, s25, 0x2000
	s_nop 0
	global_load_lds_dwordx4 v182, s[98:99]
	s_waitcnt vmcnt(10)
	s_barrier
	s_waitcnt lgkmcnt(0)
	s_setprio 1
	s_waitcnt lgkmcnt(0)
	v_mfma_f32_16x16x32_bf16 v[60:63], v[192:195], v[144:147], v[60:63]
	v_mfma_f32_16x16x32_bf16 v[56:59], v[200:203], v[144:147], v[56:59]
	v_mfma_f32_16x16x32_bf16 v[52:55], v[192:195], v[152:155], v[52:55]
	v_mfma_f32_16x16x32_bf16 v[48:51], v[200:203], v[152:155], v[48:51]
	v_mfma_f32_16x16x32_bf16 v[44:47], v[192:195], v[160:163], v[44:47]
	v_mfma_f32_16x16x32_bf16 v[40:43], v[200:203], v[160:163], v[40:43]
	v_mfma_f32_16x16x32_bf16 v[36:39], v[192:195], v[168:171], v[36:39]
	v_mfma_f32_16x16x32_bf16 v[32:35], v[200:203], v[168:171], v[32:35]
	v_mfma_f32_16x16x32_bf16 v[60:63], v[196:199], v[148:151], v[60:63]
	v_mfma_f32_16x16x32_bf16 v[56:59], v[204:207], v[148:151], v[56:59]
	v_mfma_f32_16x16x32_bf16 v[52:55], v[196:199], v[156:159], v[52:55]
	v_mfma_f32_16x16x32_bf16 v[48:51], v[204:207], v[156:159], v[48:51]
	v_mfma_f32_16x16x32_bf16 v[44:47], v[196:199], v[164:167], v[44:47]
	v_mfma_f32_16x16x32_bf16 v[40:43], v[204:207], v[164:167], v[40:43]
	v_mfma_f32_16x16x32_bf16 v[36:39], v[196:199], v[172:175], v[36:39]
	s_barrier
	v_mfma_f32_16x16x32_bf16 v[32:35], v[204:207], v[172:175], v[32:35]
	s_setprio 0
	s_mov_b32 m0, s34
	ds_read_b128 v[144:147], v221 offset:49152
	ds_read_b128 v[148:151], v221 offset:50176
	ds_read_b128 v[152:155], v221 offset:51200
	ds_read_b128 v[156:159], v221 offset:52224
	ds_read_b128 v[160:163], v221 offset:53248
	ds_read_b128 v[164:167], v221 offset:54272
	ds_read_b128 v[168:171], v221 offset:55296
	ds_read_b128 v[172:175], v221 offset:56320
	global_load_lds_dwordx4 v176, s[100:101]
	s_mov_b32 m0, s35
	s_nop 0
	global_load_lds_dwordx4 v180, s[100:101]
	s_waitcnt vmcnt(12)
	s_barrier
; #define PG8_STAGE(bufoff, gbase, voff) do { _Pragma("unroll") for (int _i = 0; _i < 2; ++_i) \
;         __builtin_amdgcn_global_load_lds((const unsigned*)((const char*)(gbase) + (voff)[_i]), (LAS unsigned*)(lds + (bufoff) + ldsw + _i * 8192), 16, 0, 0); } while (0)
; #define PG8_MMA(ai, bj, At, Bt) do { __builtin_amdgcn_s_setprio(1); _Pragma("unroll") for (int m = 0; m < 4; ++m) _Pragma("unroll") for (int n = 0; n < 2; ++n) _Pragma("unroll") for (int k = 0; k < 2; ++k) \
;         acc[ai][bj][m][n] = __builtin_amdgcn_mfma_f32_16x16x32_bf16(Bt[n][k], At[m][k], acc[ai][bj][m][n], 0, 0, 0); __builtin_amdgcn_s_setprio(0); } while (0)
; #define PG8_WAIT_V(n) asm volatile("s_waitcnt vmcnt(" #n ")" ::: "memory")
; #define PG8_WAIT_L(n) asm volatile("s_waitcnt lgkmcnt(" #n ")" ::: "memory")
; #define PG8_BAR __builtin_amdgcn_s_barrier()
; #define PG8_SCHED __builtin_amdgcn_sched_barrier(0)
; template <class Epi>
; __device__ __forceinline__ void gemm_phase(ldsp lds, const Gemm g, const StaticOrder& S, const Epi& E) {
;     ...
;             PG8_WAIT_V(10); PG8_BAR; PG8_WAIT_L(0); PG8_MMA(1, 0, At, B0); PG8_BAR; PG8_SCHED;
;             PG8_STAGE(PG8_SB(1, 1), b3 + hstep, voffB);
;             PG8_WAIT_V(10); PG8_BAR; PG8_MMA(1, 1, At, B1); PG8_BAR;
;     __device__ __forceinline__ void operator()(EPI_ARGS) const {
;         const int row0 = u.pm * 256 + wr * 64 + fr, col0 = u.pn * 256 + wc * 32 + 8 * fq;
; #pragma unroll
;         for (int bj = 0; bj < 2; ++bj) { const f32x4 b0 = *(const f32x4*)(bias + col0 + bj * 128), b1 = *(const f32x4*)(bias + col0 + bj * 128 + 4);
;             u32x4 hw[2][4];
; #pragma unroll
;             for (int ai = 0; ai < 2; ++ai)
; #pragma unroll
;                 for (int m = 0; m < 4; ++m) hw[ai][m] = *(const u32x4*)(H + (size_t)(row0 + ai * 128 + m * 16) * 512 + col0 + bj * 128);
	s_waitcnt lgkmcnt(0)
	s_setprio 1
	s_waitcnt lgkmcnt(0)
	v_mfma_f32_16x16x32_bf16 v[92:95], v[128:131], v[144:147], v[92:95]
	v_mfma_f32_16x16x32_bf16 v[88:91], v[136:139], v[144:147], v[88:91]
	v_mfma_f32_16x16x32_bf16 v[84:87], v[128:131], v[152:155], v[84:87]
	v_mfma_f32_16x16x32_bf16 v[80:83], v[136:139], v[152:155], v[80:83]
	v_mfma_f32_16x16x32_bf16 v[76:79], v[128:131], v[160:163], v[76:79]
	v_mfma_f32_16x16x32_bf16 v[72:75], v[136:139], v[160:163], v[72:75]
	v_mfma_f32_16x16x32_bf16 v[68:71], v[128:131], v[168:171], v[68:71]
	v_mfma_f32_16x16x32_bf16 v[64:67], v[136:139], v[168:171], v[64:67]
	v_mfma_f32_16x16x32_bf16 v[92:95], v[132:135], v[148:151], v[92:95]
	v_mfma_f32_16x16x32_bf16 v[88:91], v[140:143], v[148:151], v[88:91]
	v_mfma_f32_16x16x32_bf16 v[84:87], v[132:135], v[156:159], v[84:87]
	v_mfma_f32_16x16x32_bf16 v[80:83], v[140:143], v[156:159], v[80:83]
	v_mfma_f32_16x16x32_bf16 v[76:79], v[132:135], v[164:167], v[76:79]
	v_mfma_f32_16x16x32_bf16 v[72:75], v[140:143], v[164:167], v[72:75]
	v_mfma_f32_16x16x32_bf16 v[68:71], v[132:135], v[172:175], v[68:71]
	s_barrier
	v_mfma_f32_16x16x32_bf16 v[64:67], v[140:143], v[172:175], v[64:67]
	s_setprio 0
	s_add_u32 s22, s22, 0x20080
	s_addc_u32 s23, s23, 0
	s_add_i32 s24, s24, s28
	s_mov_b32 m0, s24
	s_nop 0
	global_load_lds_dwordx4 v178, s[22:23]
	s_add_i32 m0, s24, 0x2000
	s_nop 0
	global_load_lds_dwordx4 v182, s[22:23]
	s_waitcnt vmcnt(10)
	s_barrier
	s_nop 3
	s_setprio 1
	v_mfma_f32_16x16x32_bf16 v[28:31], v[192:195], v[144:147], v[28:31]
	v_mfma_f32_16x16x32_bf16 v[24:27], v[200:203], v[144:147], v[24:27]
	v_mfma_f32_16x16x32_bf16 v[20:23], v[192:195], v[152:155], v[20:23]
	v_mfma_f32_16x16x32_bf16 v[16:19], v[200:203], v[152:155], v[16:19]
	v_mfma_f32_16x16x32_bf16 v[12:15], v[192:195], v[160:163], v[12:15]
	v_mfma_f32_16x16x32_bf16 v[8:11], v[200:203], v[160:163], v[8:11]
	v_mfma_f32_16x16x32_bf16 v[4:7], v[192:195], v[168:171], v[4:7]
	v_mfma_f32_16x16x32_bf16 v[0:3], v[200:203], v[168:171], v[0:3]
	v_mfma_f32_16x16x32_bf16 v[28:31], v[196:199], v[148:151], v[28:31]
	v_mfma_f32_16x16x32_bf16 v[24:27], v[204:207], v[148:151], v[24:27]
	v_mfma_f32_16x16x32_bf16 v[20:23], v[196:199], v[156:159], v[20:23]
	v_mfma_f32_16x16x32_bf16 v[16:19], v[204:207], v[156:159], v[16:19]
	v_mfma_f32_16x16x32_bf16 v[12:15], v[196:199], v[164:167], v[12:15]
	v_mfma_f32_16x16x32_bf16 v[8:11], v[204:207], v[164:167], v[8:11]
	v_mfma_f32_16x16x32_bf16 v[4:7], v[196:199], v[172:175], v[4:7]
	s_barrier
	v_mfma_f32_16x16x32_bf16 v[0:3], v[204:207], v[172:175], v[0:3]
	s_setprio 0
	s_add_i32 s46, s46, 2
	s_add_u32 s20, s20, 0x100
	s_addc_u32 s21, s21, 0
	s_add_u32 s44, s44, 0x100
	s_addc_u32 s45, s45, 0
	s_cmp_gt_u32 s46, 5
	s_cbranch_scc0 .LBB0_574
	v_lshl_or_b32 v136, s41, 8, v218
	v_readlane_b32 s72, v246, 6
	v_ashrrev_i32_e32 v137, 31, v136
	v_readlane_b32 s86, v246, 20
	v_readlane_b32 s87, v246, 21
	v_lshl_add_u32 v140, s18, 8, v216
	v_ashrrev_i32_e32 v141, 31, v140
	v_lshl_add_u64 v[192:193], v[136:137], 2, s[86:87]
	v_lshlrev_b64 v[194:195], 1, v[136:137]
	global_load_dwordx4 v[132:135], v[192:193], off
	global_load_dwordx4 v[128:131], v[192:193], off offset:16
	v_lshlrev_b64 v[136:137], 10, v[140:141]
	v_lshl_add_u64 v[150:151], s[4:5], 0, v[194:195]
	v_lshl_add_u64 v[142:143], v[150:151], 0, v[136:137]
	global_load_dwordx4 v[136:139], v[142:143], off
	v_or_b32_e32 v210, 16, v140
	v_or_b32_e32 v206, 48, v140
	v_add_u32_e32 v204, 0x80, v140
	v_add_u32_e32 v198, 0xb0, v140
	v_ashrrev_i32_e32 v211, 31, v210
	v_ashrrev_i32_e32 v207, 31, v206
	v_ashrrev_i32_e32 v205, 31, v204
	v_ashrrev_i32_e32 v199, 31, v198
	v_lshlrev_b64 v[144:145], 10, v[210:211]
	v_lshlrev_b64 v[152:153], 10, v[206:207]
	v_lshlrev_b64 v[154:155], 10, v[204:205]
	v_lshlrev_b64 v[160:161], 10, v[198:199]
	v_lshl_add_u64 v[148:149], v[150:151], 0, v[144:145]
	v_lshl_add_u64 v[144:145], v[150:151], 0, v[152:153]
	v_lshl_add_u64 v[168:169], v[150:151], 0, v[154:155]
	v_lshl_add_u64 v[212:213], v[150:151], 0, v[160:161]
	global_load_dwordx4 v[152:155], v[148:149], off
	global_load_dwordx4 v[160:163], v[142:143], off offset:256
	v_or_b32_e32 v208, 32, v140
	v_add_u32_e32 v202, 0x90, v140
	v_add_u32_e32 v200, 0xa0, v140
	v_ashrrev_i32_e32 v209, 31, v208
	v_ashrrev_i32_e32 v203, 31, v202
	v_ashrrev_i32_e32 v201, 31, v200
	v_lshlrev_b64 v[146:147], 10, v[208:209]
	v_lshlrev_b64 v[156:157], 10, v[202:203]
	v_lshlrev_b64 v[158:159], 10, v[200:201]
	v_lshl_add_u64 v[146:147], v[150:151], 0, v[146:147]
	v_lshl_add_u64 v[166:167], v[150:151], 0, v[156:157]
	v_lshl_add_u64 v[164:165], v[150:151], 0, v[158:159]
	v_mov_b64_e32 v[196:197], s[6:7]
	s_and_b64 vcc, exec, s[2:3]
	s_mov_b32 s18, s12
	s_mov_b32 s41, s10
	s_mov_b64 s[22:23], s[16:17]
	v_readlane_b32 s73, v246, 7
	v_readlane_b32 s74, v246, 8
	v_readlane_b32 s75, v246, 9
	v_readlane_b32 s76, v246, 10
	v_readlane_b32 s77, v246, 11
	v_readlane_b32 s78, v246, 12
	v_readlane_b32 s79, v246, 13
	v_readlane_b32 s80, v246, 14
	v_readlane_b32 s81, v246, 15
	v_readlane_b32 s82, v246, 16
	v_readlane_b32 s83, v246, 17
	v_readlane_b32 s84, v246, 18
	v_readlane_b32 s85, v246, 19
	s_waitcnt vmcnt(0)
; __device__ __forceinline__ float sigm(float x) { return __builtin_amdgcn_rcpf(1.0f + __builtin_amdgcn_exp2f(-1.4426950408889634f * x)); }
;     __device__ __forceinline__ void operator()(EPI_ARGS) const {
;     ...
;             for (int ai = 0; ai < 2; ++ai)
; #pragma unroll
;                 for (int m = 0; m < 4; ++m) { const size_t off = (size_t)(row0 + ai * 128 + m * 16) * 512 + col0 + bj * 128;
;                     f32x4 h0, h1; unpack8(hw[ai][m], h0, h1);
;                     f32x4 v0 = acc[ai][bj][m][0] + b0, v1 = acc[ai][bj][m][1] + b1;
; #pragma unroll
;                     for (int j = 0; j < 4; ++j) { v0[j] = h0[j] * sigm(v0[j]); v1[j] = h1[j] * sigm(v1[j]); }
;                     *(u32x4*)(O + (size_t)(row0 + ai * 128 + m * 16) * KAB + 1024 + col0 + bj * 128) = pack8(v0, v1); } }
	v_pk_add_f32 v[124:125], v[124:125], v[132:133]
	v_pk_add_f32 v[126:127], v[126:127], v[134:135]
	v_pk_add_f32 v[122:123], v[122:123], v[130:131]
	v_pk_add_f32 v[120:121], v[120:121], v[128:129]
	v_mul_f32_e32 v124, 0xbfb8aa3b, v124
	v_mul_f32_e32 v125, 0xbfb8aa3b, v125
	v_mul_f32_e32 v120, 0xbfb8aa3b, v120
	v_mul_f32_e32 v141, 0xbfb8aa3b, v121
	v_mul_f32_e32 v126, 0xbfb8aa3b, v126
	v_mul_f32_e32 v142, 0xbfb8aa3b, v122
	v_mul_f32_e32 v127, 0xbfb8aa3b, v127
	v_mul_f32_e32 v143, 0xbfb8aa3b, v123
	v_exp_f32_e32 v150, v124
	v_exp_f32_e32 v156, v125
	v_exp_f32_e32 v151, v120
	v_lshlrev_b32_e32 v120, 16, v136
	v_and_b32_e32 v121, 0xffff0000, v136
	v_exp_f32_e32 v136, v141
	v_lshlrev_b32_e32 v122, 16, v138
	v_and_b32_e32 v123, 0xffff0000, v138
	v_exp_f32_e32 v138, v126
	v_exp_f32_e32 v141, v142
	v_exp_f32_e32 v142, v127
	v_lshlrev_b32_e32 v124, 16, v137
	v_and_b32_e32 v125, 0xffff0000, v137
	v_exp_f32_e32 v137, v143
	v_lshlrev_b32_e32 v126, 16, v139
	v_and_b32_e32 v127, 0xffff0000, v139
	v_add_f32_e32 v139, 1.0, v150
	v_add_f32_e32 v150, 1.0, v156
	v_add_f32_e32 v143, 1.0, v151
	v_add_f32_e32 v151, 1.0, v136
	v_add_f32_e32 v156, 1.0, v138
	v_add_f32_e32 v141, 1.0, v141
	v_add_f32_e32 v157, 1.0, v142
	v_add_f32_e32 v158, 1.0, v137
	v_rcp_f32_e32 v136, v139
	v_rcp_f32_e32 v137, v150
	v_rcp_f32_e32 v138, v143
	v_rcp_f32_e32 v139, v151
	v_rcp_f32_e32 v142, v156
	v_rcp_f32_e32 v150, v141
	v_rcp_f32_e32 v143, v157
	v_rcp_f32_e32 v151, v158
	v_pk_mul_f32 v[120:121], v[136:137], v[120:121]
	v_pk_mul_f32 v[122:123], v[138:139], v[122:123]
	v_pk_mul_f32 v[124:125], v[142:143], v[124:125]
	v_pk_mul_f32 v[126:127], v[150:151], v[126:127]
	v_cvt_pk_bf16_f32 v224, v120, v121
	v_mad_i64_i32 v[120:121], s[20:21], v140, s40, v[196:197]
	v_cvt_pk_bf16_f32 v225, v124, v125
	v_cvt_pk_bf16_f32 v226, v122, v123
	v_cvt_pk_bf16_f32 v227, v126, v127
	v_lshl_add_u64 v[214:215], v[120:121], 0, v[194:195]
	global_load_dwordx4 v[156:159], v[148:149], off offset:256
	global_load_dwordx4 v[228:231], v[146:147], off
	s_nop 0
	global_load_dwordx4 v[148:151], v[146:147], off offset:256
	global_load_dwordx4 v[232:235], v[144:145], off
	s_nop 0
	global_load_dwordx4 v[144:147], v[144:145], off offset:256
	s_nop 0
	global_load_dwordx4 v[236:239], v[168:169], off
	global_load_dwordx4 v[140:143], v[168:169], off offset:256
	global_load_dwordx4 v[172:175], v[166:167], off
	global_load_dwordx4 v[136:139], v[166:167], off offset:256
	s_nop 0
	global_load_dwordx4 v[168:171], v[164:165], off
	global_load_dwordx4 v[124:127], v[164:165], off offset:256
	s_nop 0
	global_load_dwordx4 v[164:167], v[212:213], off
	global_load_dwordx4 v[120:123], v[212:213], off offset:256
	v_pk_add_f32 v[116:117], v[116:117], v[132:133]
	v_pk_add_f32 v[114:115], v[114:115], v[130:131]
	v_mul_f32_e32 v116, 0xbfb8aa3b, v116
	v_mul_f32_e32 v117, 0xbfb8aa3b, v117
	v_exp_f32_e32 v116, v116
	v_exp_f32_e32 v117, v117
	v_pk_add_f32 v[118:119], v[118:119], v[134:135]
	v_pk_add_f32 v[112:113], v[112:113], v[128:129]
	v_add_f32_e32 v116, 1.0, v116
	v_add_f32_e32 v117, 1.0, v117
	v_rcp_f32_e32 v116, v116
	v_rcp_f32_e32 v117, v117
	v_mul_f32_e32 v114, 0xbfb8aa3b, v114
	v_mul_f32_e32 v112, 0xbfb8aa3b, v112
	v_mul_f32_e32 v113, 0xbfb8aa3b, v113
	v_lshlrev_b32_e32 v212, 16, v152
	v_and_b32_e32 v213, 0xffff0000, v152
	v_mul_f32_e32 v118, 0xbfb8aa3b, v118
	v_exp_f32_e32 v152, v114
	v_mul_f32_e32 v114, 0xbfb8aa3b, v119
	v_exp_f32_e32 v112, v112
	v_exp_f32_e32 v113, v113
	v_exp_f32_e32 v118, v118
	v_exp_f32_e32 v119, v114
	v_mul_f32_e32 v115, 0xbfb8aa3b, v115
	v_pk_mul_f32 v[116:117], v[116:117], v[212:213]
	v_lshlrev_b32_e32 v212, 16, v154
	v_and_b32_e32 v213, 0xffff0000, v154
	v_exp_f32_e32 v154, v115
	v_pk_add_f32 v[108:109], v[108:109], v[132:133]
	v_pk_add_f32 v[104:105], v[104:105], v[128:129]
	v_mul_f32_e32 v108, 0xbfb8aa3b, v108
	v_mul_f32_e32 v109, 0xbfb8aa3b, v109
	v_add_f32_e32 v112, 1.0, v112
	v_add_f32_e32 v113, 1.0, v113
	v_add_f32_e32 v118, 1.0, v118
	v_add_f32_e32 v119, 1.0, v119
	v_exp_f32_e32 v108, v108
	v_mul_f32_e32 v104, 0xbfb8aa3b, v104
	v_exp_f32_e32 v109, v109
	v_mul_f32_e32 v105, 0xbfb8aa3b, v105
	v_rcp_f32_e32 v112, v112
	v_rcp_f32_e32 v113, v113
	v_rcp_f32_e32 v114, v118
	v_add_f32_e32 v118, 1.0, v152
	v_rcp_f32_e32 v115, v119
	v_add_f32_e32 v119, 1.0, v154
	v_exp_f32_e32 v104, v104
	v_exp_f32_e32 v105, v105
	v_rcp_f32_e32 v118, v118
	v_rcp_f32_e32 v119, v119
	v_lshlrev_b32_e32 v152, 16, v153
	v_and_b32_e32 v153, 0xffff0000, v153
	v_add_f32_e32 v108, 1.0, v108
	v_add_f32_e32 v109, 1.0, v109
	v_pk_mul_f32 v[112:113], v[112:113], v[212:213]
	v_pk_mul_f32 v[152:153], v[114:115], v[152:153]
	v_lshlrev_b32_e32 v114, 16, v155
	v_and_b32_e32 v115, 0xffff0000, v155
	v_rcp_f32_e32 v108, v108
	v_add_f32_e32 v104, 1.0, v104
	v_rcp_f32_e32 v109, v109
	v_add_f32_e32 v105, 1.0, v105
	v_pk_mul_f32 v[118:119], v[118:119], v[114:115]
	v_cvt_pk_bf16_f32 v114, v116, v117
	v_cvt_pk_bf16_f32 v116, v112, v113
	v_mad_i64_i32 v[112:113], s[20:21], v210, s40, v[196:197]
	v_rcp_f32_e32 v104, v104
	v_rcp_f32_e32 v105, v105
	v_cvt_pk_bf16_f32 v115, v152, v153
	v_cvt_pk_bf16_f32 v117, v118, v119
	v_lshl_add_u64 v[112:113], v[112:113], 0, v[194:195]
	global_store_dwordx4 v[112:113], v[114:117], off offset:2048
	v_pk_add_f32 v[106:107], v[106:107], v[130:131]
	v_pk_add_f32 v[110:111], v[110:111], v[134:135]
	s_waitcnt vmcnt(0)
; __device__ __forceinline__ float sigm(float x) { return __builtin_amdgcn_rcpf(1.0f + __builtin_amdgcn_exp2f(-1.4426950408889634f * x)); }
;     __device__ __forceinline__ void operator()(EPI_ARGS) const {
;         const int row0 = u.pm * 256 + wr * 64 + fr, col0 = u.pn * 256 + wc * 32 + 8 * fq;
; #pragma unroll
;         for (int bj = 0; bj < 2; ++bj) { const f32x4 b0 = *(const f32x4*)(bias + col0 + bj * 128), b1 = *(const f32x4*)(bias + col0 + bj * 128 + 4);
;             u32x4 hw[2][4];
; #pragma unroll
;             for (int ai = 0; ai < 2; ++ai)
; #pragma unroll
;                 for (int m = 0; m < 4; ++m) hw[ai][m] = *(const u32x4*)(H + (size_t)(row0 + ai * 128 + m * 16) * 512 + col0 + bj * 128);
; #pragma unroll
;             for (int ai = 0; ai < 2; ++ai)
; #pragma unroll
;                 for (int m = 0; m < 4; ++m) { const size_t off = (size_t)(row0 + ai * 128 + m * 16) * 512 + col0 + bj * 128;
;                     f32x4 h0, h1; unpack8(hw[ai][m], h0, h1);
;                     f32x4 v0 = acc[ai][bj][m][0] + b0, v1 = acc[ai][bj][m][1] + b1;
; #pragma unroll
;                     for (int j = 0; j < 4; ++j) { v0[j] = h0[j] * sigm(v0[j]); v1[j] = h1[j] * sigm(v1[j]); }
;                     *(u32x4*)(O + (size_t)(row0 + ai * 128 + m * 16) * KAB + 1024 + col0 + bj * 128) = pack8(v0, v1); } }
	v_lshlrev_b32_e32 v114, 16, v228
	v_and_b32_e32 v115, 0xffff0000, v228
	v_pk_mul_f32 v[108:109], v[108:109], v[114:115]
	v_lshlrev_b32_e32 v114, 16, v230
	v_and_b32_e32 v115, 0xffff0000, v230
	v_mul_f32_e32 v106, 0xbfb8aa3b, v106
	v_mul_f32_e32 v110, 0xbfb8aa3b, v110
	v_pk_mul_f32 v[104:105], v[104:105], v[114:115]
	v_exp_f32_e32 v114, v106
	v_mul_f32_e32 v106, 0xbfb8aa3b, v111
	v_exp_f32_e32 v110, v110
	v_exp_f32_e32 v111, v106
	v_mul_f32_e32 v107, 0xbfb8aa3b, v107
	v_exp_f32_e32 v116, v107
	v_pk_add_f32 v[100:101], v[100:101], v[132:133]
	v_pk_add_f32 v[96:97], v[96:97], v[128:129]
	v_mul_f32_e32 v100, 0xbfb8aa3b, v100
	v_mul_f32_e32 v101, 0xbfb8aa3b, v101
	v_add_f32_e32 v110, 1.0, v110
	v_add_f32_e32 v111, 1.0, v111
	v_exp_f32_e32 v100, v100
	v_mul_f32_e32 v96, 0xbfb8aa3b, v96
	v_exp_f32_e32 v101, v101
	v_mul_f32_e32 v97, 0xbfb8aa3b, v97
	v_rcp_f32_e32 v106, v110
	v_add_f32_e32 v110, 1.0, v114
	v_rcp_f32_e32 v107, v111
	v_add_f32_e32 v111, 1.0, v116
	v_exp_f32_e32 v96, v96
	v_exp_f32_e32 v97, v97
	v_rcp_f32_e32 v110, v110
	v_rcp_f32_e32 v111, v111
	v_lshlrev_b32_e32 v114, 16, v229
	v_and_b32_e32 v115, 0xffff0000, v229
	v_add_f32_e32 v100, 1.0, v100
	v_add_f32_e32 v101, 1.0, v101
	v_pk_mul_f32 v[114:115], v[106:107], v[114:115]
	v_lshlrev_b32_e32 v106, 16, v231
	v_and_b32_e32 v107, 0xffff0000, v231
	v_rcp_f32_e32 v100, v100
	v_add_f32_e32 v96, 1.0, v96
	v_rcp_f32_e32 v101, v101
	v_add_f32_e32 v97, 1.0, v97
	v_pk_mul_f32 v[110:111], v[110:111], v[106:107]
	v_cvt_pk_bf16_f32 v106, v108, v109
	v_cvt_pk_bf16_f32 v108, v104, v105
	v_mad_i64_i32 v[104:105], s[20:21], v208, s40, v[196:197]
	v_rcp_f32_e32 v96, v96
	v_rcp_f32_e32 v97, v97
	v_cvt_pk_bf16_f32 v107, v114, v115
	v_cvt_pk_bf16_f32 v109, v110, v111
	v_lshl_add_u64 v[104:105], v[104:105], 0, v[194:195]
	global_store_dwordx4 v[104:105], v[106:109], off offset:2048
	v_pk_add_f32 v[98:99], v[98:99], v[130:131]
	v_pk_add_f32 v[102:103], v[102:103], v[134:135]
	v_lshlrev_b32_e32 v106, 16, v232
	v_and_b32_e32 v107, 0xffff0000, v232
	v_pk_mul_f32 v[100:101], v[100:101], v[106:107]
	v_lshlrev_b32_e32 v106, 16, v234
	v_and_b32_e32 v107, 0xffff0000, v234
	v_mul_f32_e32 v98, 0xbfb8aa3b, v98
	v_mul_f32_e32 v102, 0xbfb8aa3b, v102
	v_pk_mul_f32 v[96:97], v[96:97], v[106:107]
	v_exp_f32_e32 v106, v98
	v_mul_f32_e32 v98, 0xbfb8aa3b, v103
	v_exp_f32_e32 v102, v102
	v_exp_f32_e32 v103, v98
	v_mul_f32_e32 v99, 0xbfb8aa3b, v99
	v_exp_f32_e32 v108, v99
	v_pk_add_f32 v[92:93], v[92:93], v[132:133]
	v_pk_add_f32 v[88:89], v[88:89], v[128:129]
	v_mul_f32_e32 v92, 0xbfb8aa3b, v92
	v_mul_f32_e32 v93, 0xbfb8aa3b, v93
	v_add_f32_e32 v102, 1.0, v102
	v_add_f32_e32 v103, 1.0, v103
	v_exp_f32_e32 v92, v92
	v_mul_f32_e32 v88, 0xbfb8aa3b, v88
	v_exp_f32_e32 v93, v93
	v_mul_f32_e32 v89, 0xbfb8aa3b, v89
	v_rcp_f32_e32 v98, v102
	v_add_f32_e32 v102, 1.0, v106
	v_rcp_f32_e32 v99, v103
	v_add_f32_e32 v103, 1.0, v108
	v_exp_f32_e32 v88, v88
	v_exp_f32_e32 v89, v89
	v_rcp_f32_e32 v102, v102
	v_rcp_f32_e32 v103, v103
	v_lshlrev_b32_e32 v106, 16, v233
	v_and_b32_e32 v107, 0xffff0000, v233
	v_add_f32_e32 v92, 1.0, v92
	v_add_f32_e32 v93, 1.0, v93
	v_pk_mul_f32 v[106:107], v[98:99], v[106:107]
	v_lshlrev_b32_e32 v98, 16, v235
	v_and_b32_e32 v99, 0xffff0000, v235
	v_rcp_f32_e32 v92, v92
	v_add_f32_e32 v88, 1.0, v88
	v_rcp_f32_e32 v93, v93
	v_add_f32_e32 v89, 1.0, v89
	v_pk_mul_f32 v[102:103], v[102:103], v[98:99]
	v_cvt_pk_bf16_f32 v98, v100, v101
	v_cvt_pk_bf16_f32 v100, v96, v97
	v_mad_i64_i32 v[96:97], s[20:21], v206, s40, v[196:197]
	v_rcp_f32_e32 v88, v88
	v_rcp_f32_e32 v89, v89
	v_cvt_pk_bf16_f32 v99, v106, v107
	v_cvt_pk_bf16_f32 v101, v102, v103
	v_lshl_add_u64 v[96:97], v[96:97], 0, v[194:195]
	global_store_dwordx4 v[96:97], v[98:101], off offset:2048
	v_pk_add_f32 v[90:91], v[90:91], v[130:131]
	v_pk_add_f32 v[94:95], v[94:95], v[134:135]
	v_lshlrev_b32_e32 v98, 16, v236
	v_and_b32_e32 v99, 0xffff0000, v236
	v_pk_mul_f32 v[92:93], v[92:93], v[98:99]
	v_lshlrev_b32_e32 v98, 16, v238
	v_and_b32_e32 v99, 0xffff0000, v238
	v_mul_f32_e32 v90, 0xbfb8aa3b, v90
	v_mul_f32_e32 v94, 0xbfb8aa3b, v94
	v_pk_mul_f32 v[88:89], v[88:89], v[98:99]
	v_exp_f32_e32 v98, v90
	v_mul_f32_e32 v90, 0xbfb8aa3b, v95
	v_exp_f32_e32 v94, v94
	v_exp_f32_e32 v95, v90
	v_mul_f32_e32 v91, 0xbfb8aa3b, v91
	v_exp_f32_e32 v100, v91
	v_pk_add_f32 v[84:85], v[84:85], v[132:133]
	v_pk_add_f32 v[80:81], v[80:81], v[128:129]
	v_mul_f32_e32 v84, 0xbfb8aa3b, v84
	v_mul_f32_e32 v85, 0xbfb8aa3b, v85
	v_add_f32_e32 v94, 1.0, v94
	v_add_f32_e32 v95, 1.0, v95
	v_exp_f32_e32 v84, v84
	v_mul_f32_e32 v80, 0xbfb8aa3b, v80
	v_exp_f32_e32 v85, v85
	v_mul_f32_e32 v81, 0xbfb8aa3b, v81
	v_rcp_f32_e32 v90, v94
	v_add_f32_e32 v94, 1.0, v98
	v_rcp_f32_e32 v91, v95
	v_add_f32_e32 v95, 1.0, v100
	v_exp_f32_e32 v80, v80
	v_exp_f32_e32 v81, v81
	v_rcp_f32_e32 v94, v94
	v_rcp_f32_e32 v95, v95
	v_lshlrev_b32_e32 v98, 16, v237
	v_and_b32_e32 v99, 0xffff0000, v237
	v_add_f32_e32 v84, 1.0, v84
	v_add_f32_e32 v85, 1.0, v85
	v_pk_mul_f32 v[98:99], v[90:91], v[98:99]
	v_lshlrev_b32_e32 v90, 16, v239
	v_and_b32_e32 v91, 0xffff0000, v239
	v_rcp_f32_e32 v84, v84
	v_add_f32_e32 v80, 1.0, v80
	v_rcp_f32_e32 v85, v85
	v_add_f32_e32 v81, 1.0, v81
	v_pk_mul_f32 v[94:95], v[94:95], v[90:91]
	v_cvt_pk_bf16_f32 v90, v92, v93
	v_cvt_pk_bf16_f32 v92, v88, v89
	v_mad_i64_i32 v[88:89], s[20:21], v204, s40, v[196:197]
	v_rcp_f32_e32 v80, v80
	v_rcp_f32_e32 v81, v81
	v_cvt_pk_bf16_f32 v91, v98, v99
	v_cvt_pk_bf16_f32 v93, v94, v95
	v_lshl_add_u64 v[88:89], v[88:89], 0, v[194:195]
	global_store_dwordx4 v[88:89], v[90:93], off offset:2048
	v_pk_add_f32 v[82:83], v[82:83], v[130:131]
; __device__ __forceinline__ float sigm(float x) { return __builtin_amdgcn_rcpf(1.0f + __builtin_amdgcn_exp2f(-1.4426950408889634f * x)); }
;     __device__ __forceinline__ void operator()(EPI_ARGS) const {
;     ...
;         for (int bj = 0; bj < 2; ++bj) { const f32x4 b0 = *(const f32x4*)(bias + col0 + bj * 128), b1 = *(const f32x4*)(bias + col0 + bj * 128 + 4);
;             u32x4 hw[2][4];
; #pragma unroll
;             for (int ai = 0; ai < 2; ++ai)
; #pragma unroll
;                 for (int m = 0; m < 4; ++m) hw[ai][m] = *(const u32x4*)(H + (size_t)(row0 + ai * 128 + m * 16) * 512 + col0 + bj * 128);
; #pragma unroll
;             for (int ai = 0; ai < 2; ++ai)
; #pragma unroll
;                 for (int m = 0; m < 4; ++m) { const size_t off = (size_t)(row0 + ai * 128 + m * 16) * 512 + col0 + bj * 128;
;                     f32x4 h0, h1; unpack8(hw[ai][m], h0, h1);
;                     f32x4 v0 = acc[ai][bj][m][0] + b0, v1 = acc[ai][bj][m][1] + b1;
; #pragma unroll
;                     for (int j = 0; j < 4; ++j) { v0[j] = h0[j] * sigm(v0[j]); v1[j] = h1[j] * sigm(v1[j]); }
;                     *(u32x4*)(O + (size_t)(row0 + ai * 128 + m * 16) * KAB + 1024 + col0 + bj * 128) = pack8(v0, v1); } }
	v_pk_add_f32 v[86:87], v[86:87], v[134:135]
	v_lshlrev_b32_e32 v90, 16, v172
	v_and_b32_e32 v91, 0xffff0000, v172
	v_pk_mul_f32 v[84:85], v[84:85], v[90:91]
	v_lshlrev_b32_e32 v90, 16, v174
	v_and_b32_e32 v91, 0xffff0000, v174
	v_mul_f32_e32 v82, 0xbfb8aa3b, v82
	v_mul_f32_e32 v86, 0xbfb8aa3b, v86
	v_pk_mul_f32 v[80:81], v[80:81], v[90:91]
	v_exp_f32_e32 v90, v82
	v_mul_f32_e32 v82, 0xbfb8aa3b, v87
	v_exp_f32_e32 v86, v86
	v_exp_f32_e32 v87, v82
	v_mul_f32_e32 v83, 0xbfb8aa3b, v83
	v_exp_f32_e32 v92, v83
	v_pk_add_f32 v[76:77], v[76:77], v[132:133]
	v_pk_add_f32 v[72:73], v[72:73], v[128:129]
	v_mul_f32_e32 v76, 0xbfb8aa3b, v76
	v_mul_f32_e32 v77, 0xbfb8aa3b, v77
	v_add_f32_e32 v86, 1.0, v86
	v_add_f32_e32 v87, 1.0, v87
	v_exp_f32_e32 v76, v76
	v_mul_f32_e32 v72, 0xbfb8aa3b, v72
	v_exp_f32_e32 v77, v77
	v_mul_f32_e32 v73, 0xbfb8aa3b, v73
	v_rcp_f32_e32 v82, v86
	v_add_f32_e32 v86, 1.0, v90
	v_rcp_f32_e32 v83, v87
	v_add_f32_e32 v87, 1.0, v92
	v_exp_f32_e32 v72, v72
	v_exp_f32_e32 v73, v73
	v_rcp_f32_e32 v86, v86
	v_rcp_f32_e32 v87, v87
	v_lshlrev_b32_e32 v90, 16, v173
	v_and_b32_e32 v91, 0xffff0000, v173
	v_add_f32_e32 v76, 1.0, v76
	v_add_f32_e32 v77, 1.0, v77
	v_pk_mul_f32 v[90:91], v[82:83], v[90:91]
	v_lshlrev_b32_e32 v82, 16, v175
	v_and_b32_e32 v83, 0xffff0000, v175
	v_rcp_f32_e32 v76, v76
	v_add_f32_e32 v72, 1.0, v72
	v_rcp_f32_e32 v77, v77
	v_add_f32_e32 v73, 1.0, v73
	v_pk_mul_f32 v[86:87], v[86:87], v[82:83]
	v_cvt_pk_bf16_f32 v82, v84, v85
	v_cvt_pk_bf16_f32 v84, v80, v81
	v_mad_i64_i32 v[80:81], s[20:21], v202, s40, v[196:197]
	v_rcp_f32_e32 v72, v72
	v_rcp_f32_e32 v73, v73
	v_cvt_pk_bf16_f32 v83, v90, v91
	v_cvt_pk_bf16_f32 v85, v86, v87
	v_lshl_add_u64 v[80:81], v[80:81], 0, v[194:195]
	global_store_dwordx4 v[80:81], v[82:85], off offset:2048
	v_pk_add_f32 v[74:75], v[74:75], v[130:131]
	v_pk_add_f32 v[78:79], v[78:79], v[134:135]
	v_lshlrev_b32_e32 v82, 16, v168
	v_and_b32_e32 v83, 0xffff0000, v168
	v_pk_mul_f32 v[76:77], v[76:77], v[82:83]
	v_lshlrev_b32_e32 v82, 16, v170
	v_and_b32_e32 v83, 0xffff0000, v170
	v_mul_f32_e32 v74, 0xbfb8aa3b, v74
	v_mul_f32_e32 v78, 0xbfb8aa3b, v78
	v_pk_mul_f32 v[72:73], v[72:73], v[82:83]
	v_exp_f32_e32 v82, v74
	v_mul_f32_e32 v74, 0xbfb8aa3b, v79
	v_exp_f32_e32 v78, v78
	v_exp_f32_e32 v79, v74
	v_mul_f32_e32 v75, 0xbfb8aa3b, v75
	v_exp_f32_e32 v84, v75
	v_pk_add_f32 v[68:69], v[68:69], v[132:133]
	v_pk_add_f32 v[64:65], v[64:65], v[128:129]
	v_mul_f32_e32 v68, 0xbfb8aa3b, v68
	v_mul_f32_e32 v69, 0xbfb8aa3b, v69
	v_exp_f32_e32 v68, v68
	v_mul_f32_e32 v64, 0xbfb8aa3b, v64
	v_exp_f32_e32 v69, v69
	v_mul_f32_e32 v65, 0xbfb8aa3b, v65
	v_add_f32_e32 v78, 1.0, v78
	v_add_f32_e32 v79, 1.0, v79
	v_exp_f32_e32 v64, v64
	v_exp_f32_e32 v65, v65
	v_rcp_f32_e32 v74, v78
	v_add_f32_e32 v78, 1.0, v82
	v_rcp_f32_e32 v75, v79
	v_add_f32_e32 v79, 1.0, v84
	v_rcp_f32_e32 v78, v78
	v_rcp_f32_e32 v79, v79
	v_add_f32_e32 v68, 1.0, v68
	v_add_f32_e32 v69, 1.0, v69
	v_lshlrev_b32_e32 v82, 16, v169
	v_and_b32_e32 v83, 0xffff0000, v169
	v_rcp_f32_e32 v68, v68
	v_add_f32_e32 v64, 1.0, v64
	v_rcp_f32_e32 v69, v69
	v_add_f32_e32 v65, 1.0, v65
	v_pk_mul_f32 v[74:75], v[74:75], v[82:83]
	v_lshlrev_b32_e32 v82, 16, v171
	v_and_b32_e32 v83, 0xffff0000, v171
	v_pk_add_f32 v[70:71], v[70:71], v[134:135]
	v_rcp_f32_e32 v64, v64
	v_rcp_f32_e32 v65, v65
	v_pk_mul_f32 v[82:83], v[78:79], v[82:83]
	v_cvt_pk_bf16_f32 v78, v72, v73
	v_mad_i64_i32 v[72:73], s[20:21], v200, s40, v[196:197]
	v_mul_f32_e32 v70, 0xbfb8aa3b, v70
	v_cvt_pk_bf16_f32 v76, v76, v77
	v_cvt_pk_bf16_f32 v77, v74, v75
	v_lshl_add_u64 v[74:75], v[72:73], 0, v[194:195]
	v_lshlrev_b32_e32 v72, 16, v164
	v_and_b32_e32 v73, 0xffff0000, v164
	v_exp_f32_e32 v70, v70
	v_pk_add_f32 v[66:67], v[66:67], v[130:131]
	v_pk_mul_f32 v[68:69], v[68:69], v[72:73]
	v_lshlrev_b32_e32 v72, 16, v166
	v_and_b32_e32 v73, 0xffff0000, v166
	v_pk_mul_f32 v[72:73], v[64:65], v[72:73]
	v_mul_f32_e32 v65, 0xbfb8aa3b, v66
	v_exp_f32_e32 v65, v65
	v_mul_f32_e32 v66, 0xbfb8aa3b, v71
	v_add_f32_e32 v64, 1.0, v70
	v_exp_f32_e32 v70, v66
	v_mul_f32_e32 v67, 0xbfb8aa3b, v67
	v_exp_f32_e32 v67, v67
	v_add_f32_e32 v65, 1.0, v65
	v_rcp_f32_e32 v66, v65
	v_add_f32_e32 v65, 1.0, v70
	v_rcp_f32_e32 v64, v64
	v_rcp_f32_e32 v65, v65
	v_add_f32_e32 v67, 1.0, v67
	v_rcp_f32_e32 v67, v67
	v_lshlrev_b32_e32 v70, 16, v165
	v_and_b32_e32 v71, 0xffff0000, v165
	v_cvt_pk_bf16_f32 v79, v82, v83
	v_pk_mul_f32 v[70:71], v[64:65], v[70:71]
	v_lshlrev_b32_e32 v64, 16, v167
	v_and_b32_e32 v65, 0xffff0000, v167
	global_store_dwordx4 v[74:75], v[76:79], off offset:2048
	global_store_dwordx4 v[214:215], v[224:227], off offset:2048
	s_nop 0
	v_pk_mul_f32 v[76:77], v[66:67], v[64:65]
	v_cvt_pk_bf16_f32 v64, v68, v69
	v_mad_i64_i32 v[68:69], s[20:21], v198, s40, v[196:197]
	v_cvt_pk_bf16_f32 v65, v70, v71
	v_cvt_pk_bf16_f32 v66, v72, v73
	v_cvt_pk_bf16_f32 v67, v76, v77
	v_lshl_add_u64 v[72:73], v[68:69], 0, v[194:195]
	global_store_dwordx4 v[72:73], v[64:67], off offset:2048
	global_load_dwordx4 v[68:71], v[192:193], off offset:512
	s_nop 0
	global_load_dwordx4 v[64:67], v[192:193], off offset:528
	v_lshlrev_b32_e32 v76, 16, v160
	v_and_b32_e32 v77, 0xffff0000, v160
	s_mov_b64 s[20:21], s[14:15]
	s_waitcnt vmcnt(0)
; __device__ __forceinline__ float sigm(float x) { return __builtin_amdgcn_rcpf(1.0f + __builtin_amdgcn_exp2f(-1.4426950408889634f * x)); }
;     __device__ __forceinline__ void operator()(EPI_ARGS) const {
;     ...
;                 for (int m = 0; m < 4; ++m) { const size_t off = (size_t)(row0 + ai * 128 + m * 16) * 512 + col0 + bj * 128;
;                     f32x4 h0, h1; unpack8(hw[ai][m], h0, h1);
;                     f32x4 v0 = acc[ai][bj][m][0] + b0, v1 = acc[ai][bj][m][1] + b1;
; #pragma unroll
;                     for (int j = 0; j < 4; ++j) { v0[j] = h0[j] * sigm(v0[j]); v1[j] = h1[j] * sigm(v1[j]); }
;                     *(u32x4*)(O + (size_t)(row0 + ai * 128 + m * 16) * KAB + 1024 + col0 + bj * 128) = pack8(v0, v1); } }
	v_pk_add_f32 v[60:61], v[60:61], v[68:69]
	s_nop 0
	v_mul_f32_e32 v60, 0xbfb8aa3b, v60
	v_pk_add_f32 v[56:57], v[56:57], v[64:65]
	v_mul_f32_e32 v61, 0xbfb8aa3b, v61
	v_exp_f32_e32 v60, v60
	v_mul_f32_e32 v56, 0xbfb8aa3b, v56
	v_exp_f32_e32 v61, v61
	v_mul_f32_e32 v57, 0xbfb8aa3b, v57
	v_exp_f32_e32 v56, v56
	v_exp_f32_e32 v57, v57
	v_add_f32_e32 v60, 1.0, v60
	v_add_f32_e32 v61, 1.0, v61
	v_rcp_f32_e32 v60, v60
	v_add_f32_e32 v56, 1.0, v56
	v_rcp_f32_e32 v61, v61
	v_add_f32_e32 v57, 1.0, v57
	v_pk_add_f32 v[62:63], v[62:63], v[70:71]
	v_rcp_f32_e32 v56, v56
	v_rcp_f32_e32 v57, v57
	v_mul_f32_e32 v62, 0xbfb8aa3b, v62
	v_exp_f32_e32 v62, v62
	v_pk_add_f32 v[58:59], v[58:59], v[66:67]
	v_pk_mul_f32 v[60:61], v[60:61], v[76:77]
	v_lshlrev_b32_e32 v76, 16, v162
	v_and_b32_e32 v77, 0xffff0000, v162
	v_pk_mul_f32 v[76:77], v[56:57], v[76:77]
	v_mul_f32_e32 v57, 0xbfb8aa3b, v58
	v_exp_f32_e32 v57, v57
	v_mul_f32_e32 v58, 0xbfb8aa3b, v63
	v_add_f32_e32 v56, 1.0, v62
	v_exp_f32_e32 v62, v58
	v_mul_f32_e32 v59, 0xbfb8aa3b, v59
	v_exp_f32_e32 v59, v59
	v_pk_add_f32 v[52:53], v[52:53], v[68:69]
	v_add_f32_e32 v57, 1.0, v57
	v_mul_f32_e32 v52, 0xbfb8aa3b, v52
	v_pk_add_f32 v[48:49], v[48:49], v[64:65]
	v_mul_f32_e32 v53, 0xbfb8aa3b, v53
	v_rcp_f32_e32 v58, v57
	v_add_f32_e32 v57, 1.0, v62
	v_exp_f32_e32 v52, v52
	v_mul_f32_e32 v48, 0xbfb8aa3b, v48
	v_exp_f32_e32 v53, v53
	v_mul_f32_e32 v49, 0xbfb8aa3b, v49
	v_rcp_f32_e32 v56, v56
	v_rcp_f32_e32 v57, v57
	v_add_f32_e32 v59, 1.0, v59
	v_exp_f32_e32 v48, v48
	v_exp_f32_e32 v49, v49
	v_rcp_f32_e32 v59, v59
	v_lshlrev_b32_e32 v62, 16, v161
	v_and_b32_e32 v63, 0xffff0000, v161
	v_add_f32_e32 v52, 1.0, v52
	v_add_f32_e32 v53, 1.0, v53
	v_pk_mul_f32 v[62:63], v[56:57], v[62:63]
	v_lshlrev_b32_e32 v56, 16, v163
	v_and_b32_e32 v57, 0xffff0000, v163
	v_rcp_f32_e32 v52, v52
	v_add_f32_e32 v48, 1.0, v48
	v_rcp_f32_e32 v53, v53
	v_add_f32_e32 v49, 1.0, v49
	v_pk_mul_f32 v[78:79], v[58:59], v[56:57]
	v_pk_add_f32 v[54:55], v[54:55], v[70:71]
	v_rcp_f32_e32 v48, v48
	v_rcp_f32_e32 v49, v49
	v_cvt_pk_bf16_f32 v56, v60, v61
	v_cvt_pk_bf16_f32 v57, v62, v63
	v_cvt_pk_bf16_f32 v58, v76, v77
	v_cvt_pk_bf16_f32 v59, v78, v79
	v_mul_f32_e32 v54, 0xbfb8aa3b, v54
	global_store_dwordx4 v[214:215], v[56:59], off offset:2304
	v_exp_f32_e32 v54, v54
	v_pk_add_f32 v[50:51], v[50:51], v[66:67]
	v_lshlrev_b32_e32 v56, 16, v156
	v_and_b32_e32 v57, 0xffff0000, v156
	v_pk_mul_f32 v[52:53], v[52:53], v[56:57]
	v_lshlrev_b32_e32 v56, 16, v158
	v_and_b32_e32 v57, 0xffff0000, v158
	v_pk_mul_f32 v[56:57], v[48:49], v[56:57]
	v_mul_f32_e32 v49, 0xbfb8aa3b, v50
	v_exp_f32_e32 v49, v49
	v_mul_f32_e32 v50, 0xbfb8aa3b, v55
	v_add_f32_e32 v48, 1.0, v54
	v_exp_f32_e32 v54, v50
	v_mul_f32_e32 v51, 0xbfb8aa3b, v51
	v_exp_f32_e32 v51, v51
	v_pk_add_f32 v[44:45], v[44:45], v[68:69]
	v_add_f32_e32 v49, 1.0, v49
	v_mul_f32_e32 v44, 0xbfb8aa3b, v44
	v_pk_add_f32 v[40:41], v[40:41], v[64:65]
	v_mul_f32_e32 v45, 0xbfb8aa3b, v45
	v_rcp_f32_e32 v50, v49
	v_add_f32_e32 v49, 1.0, v54
	v_exp_f32_e32 v44, v44
	v_mul_f32_e32 v40, 0xbfb8aa3b, v40
	v_exp_f32_e32 v45, v45
	v_mul_f32_e32 v41, 0xbfb8aa3b, v41
	v_rcp_f32_e32 v48, v48
	v_rcp_f32_e32 v49, v49
	v_add_f32_e32 v51, 1.0, v51
	v_exp_f32_e32 v40, v40
	v_exp_f32_e32 v41, v41
	v_rcp_f32_e32 v51, v51
	v_lshlrev_b32_e32 v54, 16, v157
	v_and_b32_e32 v55, 0xffff0000, v157
	v_add_f32_e32 v44, 1.0, v44
	v_add_f32_e32 v45, 1.0, v45
	v_pk_mul_f32 v[54:55], v[48:49], v[54:55]
	v_lshlrev_b32_e32 v48, 16, v159
	v_and_b32_e32 v49, 0xffff0000, v159
	v_rcp_f32_e32 v44, v44
	v_add_f32_e32 v40, 1.0, v40
	v_rcp_f32_e32 v45, v45
	v_add_f32_e32 v41, 1.0, v41
	v_pk_mul_f32 v[58:59], v[50:51], v[48:49]
	v_pk_add_f32 v[46:47], v[46:47], v[70:71]
	v_rcp_f32_e32 v40, v40
	v_rcp_f32_e32 v41, v41
	v_cvt_pk_bf16_f32 v48, v52, v53
	v_cvt_pk_bf16_f32 v49, v54, v55
	v_cvt_pk_bf16_f32 v50, v56, v57
	v_cvt_pk_bf16_f32 v51, v58, v59
	v_mul_f32_e32 v46, 0xbfb8aa3b, v46
	global_store_dwordx4 v[112:113], v[48:51], off offset:2304
	v_exp_f32_e32 v46, v46
	v_pk_add_f32 v[42:43], v[42:43], v[66:67]
	v_lshlrev_b32_e32 v48, 16, v148
	v_and_b32_e32 v49, 0xffff0000, v148
	v_pk_mul_f32 v[44:45], v[44:45], v[48:49]
	v_lshlrev_b32_e32 v48, 16, v150
	v_and_b32_e32 v49, 0xffff0000, v150
	v_pk_mul_f32 v[48:49], v[40:41], v[48:49]
	v_mul_f32_e32 v41, 0xbfb8aa3b, v42
	v_exp_f32_e32 v41, v41
	v_mul_f32_e32 v42, 0xbfb8aa3b, v47
	v_add_f32_e32 v40, 1.0, v46
	v_exp_f32_e32 v46, v42
	v_mul_f32_e32 v43, 0xbfb8aa3b, v43
	v_exp_f32_e32 v43, v43
	v_pk_add_f32 v[36:37], v[36:37], v[68:69]
	v_add_f32_e32 v41, 1.0, v41
	v_mul_f32_e32 v36, 0xbfb8aa3b, v36
	v_pk_add_f32 v[32:33], v[32:33], v[64:65]
	v_mul_f32_e32 v37, 0xbfb8aa3b, v37
	v_rcp_f32_e32 v42, v41
	v_add_f32_e32 v41, 1.0, v46
	v_exp_f32_e32 v36, v36
	v_mul_f32_e32 v32, 0xbfb8aa3b, v32
	v_exp_f32_e32 v37, v37
	v_mul_f32_e32 v33, 0xbfb8aa3b, v33
	v_rcp_f32_e32 v40, v40
	v_rcp_f32_e32 v41, v41
	v_add_f32_e32 v43, 1.0, v43
	v_exp_f32_e32 v32, v32
	v_exp_f32_e32 v33, v33
	v_rcp_f32_e32 v43, v43
	v_lshlrev_b32_e32 v46, 16, v149
	v_and_b32_e32 v47, 0xffff0000, v149
	v_add_f32_e32 v36, 1.0, v36
	v_add_f32_e32 v37, 1.0, v37
	v_pk_mul_f32 v[46:47], v[40:41], v[46:47]
	v_lshlrev_b32_e32 v40, 16, v151
	v_and_b32_e32 v41, 0xffff0000, v151
	v_rcp_f32_e32 v36, v36
	v_add_f32_e32 v32, 1.0, v32
	v_rcp_f32_e32 v37, v37
	v_add_f32_e32 v33, 1.0, v33
	v_pk_mul_f32 v[50:51], v[42:43], v[40:41]
	v_pk_add_f32 v[38:39], v[38:39], v[70:71]
	v_rcp_f32_e32 v32, v32
	v_rcp_f32_e32 v33, v33
	v_cvt_pk_bf16_f32 v40, v44, v45
	v_cvt_pk_bf16_f32 v41, v46, v47
	v_cvt_pk_bf16_f32 v42, v48, v49
	v_cvt_pk_bf16_f32 v43, v50, v51
	v_mul_f32_e32 v38, 0xbfb8aa3b, v38
; __device__ __forceinline__ float sigm(float x) { return __builtin_amdgcn_rcpf(1.0f + __builtin_amdgcn_exp2f(-1.4426950408889634f * x)); }
;     __device__ __forceinline__ void operator()(EPI_ARGS) const {
;     ...
;                 for (int m = 0; m < 4; ++m) { const size_t off = (size_t)(row0 + ai * 128 + m * 16) * 512 + col0 + bj * 128;
;                     f32x4 h0, h1; unpack8(hw[ai][m], h0, h1);
;                     f32x4 v0 = acc[ai][bj][m][0] + b0, v1 = acc[ai][bj][m][1] + b1;
; #pragma unroll
;                     for (int j = 0; j < 4; ++j) { v0[j] = h0[j] * sigm(v0[j]); v1[j] = h1[j] * sigm(v1[j]); }
;                     *(u32x4*)(O + (size_t)(row0 + ai * 128 + m * 16) * KAB + 1024 + col0 + bj * 128) = pack8(v0, v1); } }
	global_store_dwordx4 v[104:105], v[40:43], off offset:2304
	v_exp_f32_e32 v38, v38
	v_pk_add_f32 v[34:35], v[34:35], v[66:67]
	v_lshlrev_b32_e32 v40, 16, v144
	v_and_b32_e32 v41, 0xffff0000, v144
	v_pk_mul_f32 v[36:37], v[36:37], v[40:41]
	v_lshlrev_b32_e32 v40, 16, v146
	v_and_b32_e32 v41, 0xffff0000, v146
	v_pk_mul_f32 v[40:41], v[32:33], v[40:41]
	v_mul_f32_e32 v33, 0xbfb8aa3b, v34
	v_exp_f32_e32 v33, v33
	v_mul_f32_e32 v34, 0xbfb8aa3b, v39
	v_add_f32_e32 v32, 1.0, v38
	v_exp_f32_e32 v38, v34
	v_mul_f32_e32 v35, 0xbfb8aa3b, v35
	v_exp_f32_e32 v35, v35
	v_pk_add_f32 v[28:29], v[28:29], v[68:69]
	v_add_f32_e32 v33, 1.0, v33
	v_mul_f32_e32 v28, 0xbfb8aa3b, v28
	v_pk_add_f32 v[24:25], v[24:25], v[64:65]
	v_mul_f32_e32 v29, 0xbfb8aa3b, v29
	v_rcp_f32_e32 v34, v33
	v_add_f32_e32 v33, 1.0, v38
	v_exp_f32_e32 v28, v28
	v_mul_f32_e32 v24, 0xbfb8aa3b, v24
	v_exp_f32_e32 v29, v29
	v_mul_f32_e32 v25, 0xbfb8aa3b, v25
	v_rcp_f32_e32 v32, v32
	v_rcp_f32_e32 v33, v33
	v_add_f32_e32 v35, 1.0, v35
	v_exp_f32_e32 v24, v24
	v_exp_f32_e32 v25, v25
	v_rcp_f32_e32 v35, v35
	v_lshlrev_b32_e32 v38, 16, v145
	v_and_b32_e32 v39, 0xffff0000, v145
	v_add_f32_e32 v28, 1.0, v28
	v_add_f32_e32 v29, 1.0, v29
	v_pk_mul_f32 v[38:39], v[32:33], v[38:39]
	v_lshlrev_b32_e32 v32, 16, v147
	v_and_b32_e32 v33, 0xffff0000, v147
	v_rcp_f32_e32 v28, v28
	v_add_f32_e32 v24, 1.0, v24
	v_rcp_f32_e32 v29, v29
	v_add_f32_e32 v25, 1.0, v25
	v_pk_mul_f32 v[42:43], v[34:35], v[32:33]
	v_pk_add_f32 v[30:31], v[30:31], v[70:71]
	v_rcp_f32_e32 v24, v24
	v_rcp_f32_e32 v25, v25
	v_cvt_pk_bf16_f32 v32, v36, v37
	v_cvt_pk_bf16_f32 v33, v38, v39
	v_cvt_pk_bf16_f32 v34, v40, v41
	v_cvt_pk_bf16_f32 v35, v42, v43
	v_mul_f32_e32 v30, 0xbfb8aa3b, v30
	global_store_dwordx4 v[96:97], v[32:35], off offset:2304
	v_exp_f32_e32 v30, v30
	v_pk_add_f32 v[26:27], v[26:27], v[66:67]
	v_lshlrev_b32_e32 v32, 16, v140
	v_and_b32_e32 v33, 0xffff0000, v140
	v_pk_mul_f32 v[28:29], v[28:29], v[32:33]
	v_lshlrev_b32_e32 v32, 16, v142
	v_and_b32_e32 v33, 0xffff0000, v142
	v_pk_mul_f32 v[32:33], v[24:25], v[32:33]
	v_mul_f32_e32 v25, 0xbfb8aa3b, v26
	v_exp_f32_e32 v25, v25
	v_mul_f32_e32 v26, 0xbfb8aa3b, v31
	v_add_f32_e32 v24, 1.0, v30
	v_exp_f32_e32 v30, v26
	v_mul_f32_e32 v27, 0xbfb8aa3b, v27
	v_exp_f32_e32 v27, v27
	v_pk_add_f32 v[20:21], v[20:21], v[68:69]
	v_add_f32_e32 v25, 1.0, v25
	v_mul_f32_e32 v20, 0xbfb8aa3b, v20
	v_pk_add_f32 v[16:17], v[16:17], v[64:65]
	v_mul_f32_e32 v21, 0xbfb8aa3b, v21
	v_rcp_f32_e32 v26, v25
	v_add_f32_e32 v25, 1.0, v30
	v_exp_f32_e32 v20, v20
	v_mul_f32_e32 v16, 0xbfb8aa3b, v16
	v_exp_f32_e32 v21, v21
	v_mul_f32_e32 v17, 0xbfb8aa3b, v17
	v_rcp_f32_e32 v24, v24
	v_rcp_f32_e32 v25, v25
	v_add_f32_e32 v27, 1.0, v27
	v_exp_f32_e32 v16, v16
	v_exp_f32_e32 v17, v17
	v_rcp_f32_e32 v27, v27
	v_lshlrev_b32_e32 v30, 16, v141
	v_and_b32_e32 v31, 0xffff0000, v141
	v_add_f32_e32 v20, 1.0, v20
	v_add_f32_e32 v21, 1.0, v21
	v_pk_mul_f32 v[30:31], v[24:25], v[30:31]
	v_lshlrev_b32_e32 v24, 16, v143
	v_and_b32_e32 v25, 0xffff0000, v143
	v_rcp_f32_e32 v20, v20
	v_add_f32_e32 v16, 1.0, v16
	v_rcp_f32_e32 v21, v21
	v_add_f32_e32 v17, 1.0, v17
	v_pk_mul_f32 v[34:35], v[26:27], v[24:25]
	v_pk_add_f32 v[22:23], v[22:23], v[70:71]
	v_rcp_f32_e32 v16, v16
	v_rcp_f32_e32 v17, v17
	v_cvt_pk_bf16_f32 v24, v28, v29
	v_cvt_pk_bf16_f32 v25, v30, v31
	v_cvt_pk_bf16_f32 v26, v32, v33
	v_cvt_pk_bf16_f32 v27, v34, v35
	v_mul_f32_e32 v22, 0xbfb8aa3b, v22
	global_store_dwordx4 v[88:89], v[24:27], off offset:2304
	v_exp_f32_e32 v22, v22
	v_pk_add_f32 v[18:19], v[18:19], v[66:67]
	v_lshlrev_b32_e32 v24, 16, v136
	v_and_b32_e32 v25, 0xffff0000, v136
	v_pk_mul_f32 v[20:21], v[20:21], v[24:25]
	v_lshlrev_b32_e32 v24, 16, v138
	v_and_b32_e32 v25, 0xffff0000, v138
	v_pk_mul_f32 v[24:25], v[16:17], v[24:25]
	v_mul_f32_e32 v17, 0xbfb8aa3b, v18
	v_exp_f32_e32 v17, v17
	v_mul_f32_e32 v18, 0xbfb8aa3b, v23
	v_add_f32_e32 v16, 1.0, v22
	v_exp_f32_e32 v22, v18
	v_mul_f32_e32 v19, 0xbfb8aa3b, v19
	v_exp_f32_e32 v19, v19
; __device__ __forceinline__ float sigm(float x) { return __builtin_amdgcn_rcpf(1.0f + __builtin_amdgcn_exp2f(-1.4426950408889634f * x)); }
; #define PG8_WAIT_V(n) asm volatile("s_waitcnt vmcnt(" #n ")" ::: "memory")
; #define PG8_BAR __builtin_amdgcn_s_barrier()
; template <class Epi>
; __device__ __forceinline__ void gemm_phase(ldsp lds, const Gemm g, const StaticOrder& S, const Epi& E) {
;     ...
;     PG8_WAIT_V(0);
;     if (wr == 0) PG8_BAR;
;     __device__ __forceinline__ void operator()(EPI_ARGS) const {
;     ...
;                 for (int m = 0; m < 4; ++m) { const size_t off = (size_t)(row0 + ai * 128 + m * 16) * 512 + col0 + bj * 128;
;                     f32x4 h0, h1; unpack8(hw[ai][m], h0, h1);
;                     f32x4 v0 = acc[ai][bj][m][0] + b0, v1 = acc[ai][bj][m][1] + b1;
; #pragma unroll
;                     for (int j = 0; j < 4; ++j) { v0[j] = h0[j] * sigm(v0[j]); v1[j] = h1[j] * sigm(v1[j]); }
;                     *(u32x4*)(O + (size_t)(row0 + ai * 128 + m * 16) * KAB + 1024 + col0 + bj * 128) = pack8(v0, v1); } }
	v_pk_add_f32 v[12:13], v[12:13], v[68:69]
	v_add_f32_e32 v17, 1.0, v17
	v_mul_f32_e32 v12, 0xbfb8aa3b, v12
	v_pk_add_f32 v[8:9], v[8:9], v[64:65]
	v_mul_f32_e32 v13, 0xbfb8aa3b, v13
	v_rcp_f32_e32 v18, v17
	v_add_f32_e32 v17, 1.0, v22
	v_exp_f32_e32 v12, v12
	v_mul_f32_e32 v8, 0xbfb8aa3b, v8
	v_exp_f32_e32 v13, v13
	v_mul_f32_e32 v9, 0xbfb8aa3b, v9
	v_rcp_f32_e32 v16, v16
	v_rcp_f32_e32 v17, v17
	v_add_f32_e32 v19, 1.0, v19
	v_exp_f32_e32 v8, v8
	v_exp_f32_e32 v9, v9
	v_rcp_f32_e32 v19, v19
	v_lshlrev_b32_e32 v22, 16, v137
	v_and_b32_e32 v23, 0xffff0000, v137
	v_add_f32_e32 v12, 1.0, v12
	v_add_f32_e32 v13, 1.0, v13
	v_pk_mul_f32 v[22:23], v[16:17], v[22:23]
	v_lshlrev_b32_e32 v16, 16, v139
	v_and_b32_e32 v17, 0xffff0000, v139
	v_rcp_f32_e32 v12, v12
	v_add_f32_e32 v8, 1.0, v8
	v_rcp_f32_e32 v13, v13
	v_add_f32_e32 v9, 1.0, v9
	v_pk_mul_f32 v[26:27], v[18:19], v[16:17]
	v_pk_add_f32 v[14:15], v[14:15], v[70:71]
	v_rcp_f32_e32 v8, v8
	v_rcp_f32_e32 v9, v9
	v_cvt_pk_bf16_f32 v16, v20, v21
	v_cvt_pk_bf16_f32 v17, v22, v23
	v_cvt_pk_bf16_f32 v18, v24, v25
	v_cvt_pk_bf16_f32 v19, v26, v27
	v_mul_f32_e32 v14, 0xbfb8aa3b, v14
	global_store_dwordx4 v[80:81], v[16:19], off offset:2304
	v_exp_f32_e32 v14, v14
	v_pk_add_f32 v[10:11], v[10:11], v[66:67]
	v_lshlrev_b32_e32 v16, 16, v124
	v_and_b32_e32 v17, 0xffff0000, v124
	v_pk_mul_f32 v[12:13], v[12:13], v[16:17]
	v_lshlrev_b32_e32 v16, 16, v126
	v_and_b32_e32 v17, 0xffff0000, v126
	v_pk_mul_f32 v[16:17], v[8:9], v[16:17]
	v_mul_f32_e32 v9, 0xbfb8aa3b, v10
	v_exp_f32_e32 v9, v9
	v_mul_f32_e32 v10, 0xbfb8aa3b, v15
	v_add_f32_e32 v8, 1.0, v14
	v_exp_f32_e32 v14, v10
	v_mul_f32_e32 v11, 0xbfb8aa3b, v11
	v_exp_f32_e32 v11, v11
	v_pk_add_f32 v[4:5], v[4:5], v[68:69]
	v_add_f32_e32 v9, 1.0, v9
	v_mul_f32_e32 v4, 0xbfb8aa3b, v4
	v_pk_add_f32 v[0:1], v[0:1], v[64:65]
	v_mul_f32_e32 v5, 0xbfb8aa3b, v5
	v_rcp_f32_e32 v10, v9
	v_add_f32_e32 v9, 1.0, v14
	v_exp_f32_e32 v4, v4
	v_mul_f32_e32 v0, 0xbfb8aa3b, v0
	v_exp_f32_e32 v5, v5
	v_mul_f32_e32 v1, 0xbfb8aa3b, v1
	v_rcp_f32_e32 v8, v8
	v_rcp_f32_e32 v9, v9
	v_add_f32_e32 v11, 1.0, v11
	v_exp_f32_e32 v0, v0
	v_exp_f32_e32 v1, v1
	v_rcp_f32_e32 v11, v11
	v_lshlrev_b32_e32 v14, 16, v125
	v_and_b32_e32 v15, 0xffff0000, v125
	v_add_f32_e32 v4, 1.0, v4
	v_add_f32_e32 v5, 1.0, v5
	v_pk_mul_f32 v[14:15], v[8:9], v[14:15]
	v_lshlrev_b32_e32 v8, 16, v127
	v_and_b32_e32 v9, 0xffff0000, v127
	v_rcp_f32_e32 v4, v4
	v_add_f32_e32 v0, 1.0, v0
	v_rcp_f32_e32 v5, v5
	v_add_f32_e32 v1, 1.0, v1
	v_pk_mul_f32 v[18:19], v[10:11], v[8:9]
	v_pk_add_f32 v[6:7], v[6:7], v[70:71]
	v_rcp_f32_e32 v0, v0
	v_rcp_f32_e32 v1, v1
	v_cvt_pk_bf16_f32 v8, v12, v13
	v_cvt_pk_bf16_f32 v9, v14, v15
	v_cvt_pk_bf16_f32 v10, v16, v17
	v_cvt_pk_bf16_f32 v11, v18, v19
	v_mul_f32_e32 v6, 0xbfb8aa3b, v6
	global_store_dwordx4 v[74:75], v[8:11], off offset:2304
	v_exp_f32_e32 v6, v6
	v_pk_add_f32 v[2:3], v[2:3], v[66:67]
	v_lshlrev_b32_e32 v8, 16, v120
	v_and_b32_e32 v9, 0xffff0000, v120
	v_pk_mul_f32 v[4:5], v[4:5], v[8:9]
	v_lshlrev_b32_e32 v8, 16, v122
	v_and_b32_e32 v9, 0xffff0000, v122
	v_pk_mul_f32 v[8:9], v[0:1], v[8:9]
	v_mul_f32_e32 v1, 0xbfb8aa3b, v2
	v_exp_f32_e32 v1, v1
	v_mul_f32_e32 v2, 0xbfb8aa3b, v7
	v_add_f32_e32 v0, 1.0, v6
	v_exp_f32_e32 v6, v2
	v_mul_f32_e32 v3, 0xbfb8aa3b, v3
	v_exp_f32_e32 v3, v3
	v_add_f32_e32 v1, 1.0, v1
	v_rcp_f32_e32 v2, v1
	v_add_f32_e32 v1, 1.0, v6
	v_rcp_f32_e32 v0, v0
	v_rcp_f32_e32 v1, v1
	v_add_f32_e32 v3, 1.0, v3
	v_rcp_f32_e32 v3, v3
	v_lshlrev_b32_e32 v6, 16, v121
	v_and_b32_e32 v7, 0xffff0000, v121
	v_pk_mul_f32 v[6:7], v[0:1], v[6:7]
	v_lshlrev_b32_e32 v0, 16, v123
	v_and_b32_e32 v1, 0xffff0000, v123
	v_pk_mul_f32 v[10:11], v[2:3], v[0:1]
	v_cvt_pk_bf16_f32 v0, v4, v5
	v_cvt_pk_bf16_f32 v1, v6, v7
	v_cvt_pk_bf16_f32 v2, v8, v9
	v_cvt_pk_bf16_f32 v3, v10, v11
	global_store_dwordx4 v[72:73], v[0:3], off offset:2304
	s_cbranch_vccz .LBB0_567
	s_waitcnt vmcnt(0)
	s_cmpk_gt_u32 s26, 0xff
	s_cbranch_scc1 .LBB0_578
	s_barrier

; #define PG8_STAGE(bufoff, gbase, voff) do { _Pragma("unroll") for (int _i = 0; _i < 2; ++_i) \
;         __builtin_amdgcn_global_load_lds((const unsigned*)((const char*)(gbase) + (voff)[_i]), (LAS unsigned*)(lds + (bufoff) + ldsw + _i * 8192), 16, 0, 0); } while (0)
; #define PG8_LDA(dst, b, h) do { _Pragma("unroll") for (int m = 0; m < 4; ++m) _Pragma("unroll") for (int k = 0; k < 2; ++k) dst[m][k] = *(const LAS bf16x8*)(lds + PG8_SA(b, h) + aoff + m * 2048 + k * 1024); } while (0)
; #define PG8_LDB(dst, b, h) do { _Pragma("unroll") for (int n = 0; n < 2; ++n) _Pragma("unroll") for (int k = 0; k < 2; ++k) dst[n][k] = *(const LAS bf16x8*)(lds + PG8_SB(b, h) + boff + n * 2048 + k * 1024); } while (0)
; #define PG8_MMA(ai, bj, At, Bt) do { __builtin_amdgcn_s_setprio(1); _Pragma("unroll") for (int m = 0; m < 4; ++m) _Pragma("unroll") for (int n = 0; n < 2; ++n) _Pragma("unroll") for (int k = 0; k < 2; ++k) \
;         acc[ai][bj][m][n] = __builtin_amdgcn_mfma_f32_16x16x32_bf16(Bt[n][k], At[m][k], acc[ai][bj][m][n], 0, 0, 0); __builtin_amdgcn_s_setprio(0); } while (0)
; #define PG8_WAIT_V(n) asm volatile("s_waitcnt vmcnt(" #n ")" ::: "memory")
; template <class Epi>
; __device__ __forceinline__ void gemm_phase(ldsp lds, const Gemm g, const StaticOrder& S, const Epi& E) {
;     ...
;         for (int t = 0; t < nt; t += 2) {
;             const bool last = (t == nt - 2);
;             const char* a1 = cA + (size_t)(t + 1) * kstep;
;             const char* a2 = last ? nA : cA + (size_t)(t + 2) * kstep; const char* b2 = last ? nB : cB + (size_t)(t + 2) * kstep;
;             const char* a3 = a2 + kstep; const char* b3 = b2 + kstep;
;             if constexpr (Epi::NPRE > 0) { if (last) E.pre(pre, cur, wr, fr); }
;             if constexpr (Epi::MID_T > 0) { if (t == Epi::MID_T) E.mid(acc, cur, wr, wc, fr, fq); }
;             PG8_LDB(B0, 0, 0); PG8_SCHED; PG8_LDA(At, 0, 0); PG8_STAGE(PG8_SA(1, 1), a1 + hstep, voffA);
;             PG8_WAIT_L(8); PG8_WAIT_V(10); PG8_BAR; PG8_WAIT_L(0); PG8_MMA(0, 0, At, B0); PG8_BAR; PG8_SCHED;
;             PG8_LDB(B1, 0, 1); PG8_STAGE(PG8_SB(0, 0), b2, voffB);
;             PG8_WAIT_V(10); PG8_BAR; PG8_WAIT_L(0); PG8_MMA(0, 1, At, B1); PG8_BAR;
;             PG8_LDA(At, 0, 1); PG8_STAGE(PG8_SA(0, 0), a2, voffA);
;             PG8_WAIT_V(10); PG8_BAR; PG8_WAIT_L(0); PG8_MMA(1, 0, At, B0); PG8_BAR; PG8_SCHED;
.LBB0_654:
	s_add_u32 s26, s22, s24
	ds_read_b128 v[128:131], v247 offset:0
	ds_read_b128 v[132:135], v247 offset:1024
	ds_read_b128 v[136:139], v247 offset:2048
	ds_read_b128 v[140:143], v247 offset:3072
	s_addc_u32 s27, s23, s25
	s_add_u32 s26, s26, 0x100
	s_addc_u32 s27, s27, 0
	s_add_u32 s54, s51, s24
	s_addc_u32 s55, s52, s25
	s_cmpk_eq_i32 s24, 0xb00
	s_cselect_b32 s29, s1, s27
	s_cselect_b32 s28, s0, s26
	s_cselect_b32 s27, s5, s55
	s_cselect_b32 s26, s4, s54
	v_lshl_add_u64 v[176:177], v[212:213], 0, s[24:25]
	s_add_i32 m0, s36, 0xc000
	s_waitcnt vmcnt(0)
	ds_read_b128 v[144:147], v224
	ds_read_b128 v[148:151], v224 offset:1024
	ds_read_b128 v[152:155], v224 offset:2048
	ds_read_b128 v[156:159], v224 offset:3072
	ds_read_b128 v[160:163], v224 offset:4096
	ds_read_b128 v[164:167], v224 offset:5120
	ds_read_b128 v[168:171], v224 offset:6144
	ds_read_b128 v[172:175], v224 offset:7168
	global_load_lds_dwordx4 v[176:177], off
	v_lshl_add_u64 v[176:177], v[214:215], 0, s[24:25]
	s_add_i32 m0, s36, 0xe000
	s_nop 0
	global_load_lds_dwordx4 v[176:177], off
	s_waitcnt lgkmcnt(8)
	s_waitcnt vmcnt(10)
	s_barrier
	s_waitcnt lgkmcnt(0)
	s_setprio 1
	s_waitcnt lgkmcnt(0)
	v_mfma_f32_16x16x32_bf16 v[124:127], v[128:131], v[144:147], v[124:127]
	v_mfma_f32_16x16x32_bf16 v[120:123], v[136:139], v[144:147], v[120:123]
	v_mfma_f32_16x16x32_bf16 v[116:119], v[128:131], v[152:155], v[116:119]
	v_mfma_f32_16x16x32_bf16 v[104:107], v[136:139], v[152:155], v[104:107]
	v_mfma_f32_16x16x32_bf16 v[96:99], v[128:131], v[160:163], v[96:99]
	v_mfma_f32_16x16x32_bf16 v[88:91], v[136:139], v[160:163], v[88:91]
	v_mfma_f32_16x16x32_bf16 v[80:83], v[128:131], v[168:171], v[80:83]
	v_mfma_f32_16x16x32_bf16 v[72:75], v[136:139], v[168:171], v[72:75]
	v_mfma_f32_16x16x32_bf16 v[124:127], v[132:135], v[148:151], v[124:127]
	v_mfma_f32_16x16x32_bf16 v[120:123], v[140:143], v[148:151], v[120:123]
	v_mfma_f32_16x16x32_bf16 v[116:119], v[132:135], v[156:159], v[116:119]
	v_mfma_f32_16x16x32_bf16 v[104:107], v[140:143], v[156:159], v[104:107]
	v_mfma_f32_16x16x32_bf16 v[96:99], v[132:135], v[164:167], v[96:99]
	v_mfma_f32_16x16x32_bf16 v[88:91], v[140:143], v[164:167], v[88:91]
	v_mfma_f32_16x16x32_bf16 v[80:83], v[132:135], v[172:175], v[80:83]
	s_barrier
	v_mfma_f32_16x16x32_bf16 v[72:75], v[140:143], v[172:175], v[72:75]
	s_setprio 0
	s_add_i32 s54, s45, s35
	s_add_u32 s98, s26, 0x80
	s_addc_u32 s99, s27, 0
	s_mov_b32 m0, s54
	ds_read_b128 v[176:179], v247 offset:16384
	ds_read_b128 v[180:183], v247 offset:17408
	ds_read_b128 v[184:187], v247 offset:18432
	ds_read_b128 v[188:191], v247 offset:19456
	global_load_lds_dwordx4 v194, s[26:27]
	s_add_i32 m0, s54, 0x2000
	s_nop 0
	global_load_lds_dwordx4 v198, s[26:27]
	s_waitcnt vmcnt(10)
	s_barrier
	s_waitcnt lgkmcnt(0)
	s_setprio 1
	s_waitcnt lgkmcnt(0)
	v_mfma_f32_16x16x32_bf16 v[112:115], v[176:179], v[144:147], v[112:115]
	v_mfma_f32_16x16x32_bf16 v[108:111], v[184:187], v[144:147], v[108:111]
	v_mfma_f32_16x16x32_bf16 v[100:103], v[176:179], v[152:155], v[100:103]
	v_mfma_f32_16x16x32_bf16 v[92:95], v[184:187], v[152:155], v[92:95]
	v_mfma_f32_16x16x32_bf16 v[84:87], v[176:179], v[160:163], v[84:87]
	v_mfma_f32_16x16x32_bf16 v[76:79], v[184:187], v[160:163], v[76:79]
	v_mfma_f32_16x16x32_bf16 v[68:71], v[176:179], v[168:171], v[68:71]
	v_mfma_f32_16x16x32_bf16 v[64:67], v[184:187], v[168:171], v[64:67]
	v_mfma_f32_16x16x32_bf16 v[112:115], v[180:183], v[148:151], v[112:115]
	v_mfma_f32_16x16x32_bf16 v[108:111], v[188:191], v[148:151], v[108:111]
	v_mfma_f32_16x16x32_bf16 v[100:103], v[180:183], v[156:159], v[100:103]
	v_mfma_f32_16x16x32_bf16 v[92:95], v[188:191], v[156:159], v[92:95]
	v_mfma_f32_16x16x32_bf16 v[84:87], v[180:183], v[164:167], v[84:87]
	v_mfma_f32_16x16x32_bf16 v[76:79], v[188:191], v[164:167], v[76:79]
	v_mfma_f32_16x16x32_bf16 v[68:71], v[180:183], v[172:175], v[68:71]
	s_barrier
	v_mfma_f32_16x16x32_bf16 v[64:67], v[188:191], v[172:175], v[64:67]
	s_setprio 0
	s_mov_b32 m0, s36
	s_add_u32 s100, s28, 0x80
	s_addc_u32 s101, s29, 0
	ds_read_b128 v[144:147], v224 offset:16384
	ds_read_b128 v[148:151], v224 offset:17408
	ds_read_b128 v[152:155], v224 offset:18432
	ds_read_b128 v[156:159], v224 offset:19456
	ds_read_b128 v[160:163], v224 offset:20480
	ds_read_b128 v[164:167], v224 offset:21504
	ds_read_b128 v[168:171], v224 offset:22528
	ds_read_b128 v[172:175], v224 offset:23552
	global_load_lds_dwordx4 v192, s[28:29]
	s_mov_b32 m0, s37
	s_nop 0
	global_load_lds_dwordx4 v196, s[28:29]
	s_waitcnt vmcnt(12)
	s_barrier
	s_waitcnt lgkmcnt(0)
	s_setprio 1
	s_waitcnt lgkmcnt(0)
	v_mfma_f32_16x16x32_bf16 v[60:63], v[128:131], v[144:147], v[60:63]
	v_mfma_f32_16x16x32_bf16 v[56:59], v[136:139], v[144:147], v[56:59]
	v_mfma_f32_16x16x32_bf16 v[48:51], v[128:131], v[152:155], v[48:51]
	v_mfma_f32_16x16x32_bf16 v[40:43], v[136:139], v[152:155], v[40:43]
	v_mfma_f32_16x16x32_bf16 v[32:35], v[128:131], v[160:163], v[32:35]
	v_mfma_f32_16x16x32_bf16 v[24:27], v[136:139], v[160:163], v[24:27]
	v_mfma_f32_16x16x32_bf16 v[16:19], v[128:131], v[168:171], v[16:19]
	v_mfma_f32_16x16x32_bf16 v[8:11], v[136:139], v[168:171], v[8:11]
	v_mfma_f32_16x16x32_bf16 v[60:63], v[132:135], v[148:151], v[60:63]
	v_mfma_f32_16x16x32_bf16 v[56:59], v[140:143], v[148:151], v[56:59]
	v_mfma_f32_16x16x32_bf16 v[48:51], v[132:135], v[156:159], v[48:51]
	v_mfma_f32_16x16x32_bf16 v[40:43], v[140:143], v[156:159], v[40:43]
	v_mfma_f32_16x16x32_bf16 v[32:35], v[132:135], v[164:167], v[32:35]
	v_mfma_f32_16x16x32_bf16 v[24:27], v[140:143], v[164:167], v[24:27]
	v_mfma_f32_16x16x32_bf16 v[16:19], v[132:135], v[172:175], v[16:19]
	s_barrier
; #define PG8_STAGE(bufoff, gbase, voff) do { _Pragma("unroll") for (int _i = 0; _i < 2; ++_i) \
;         __builtin_amdgcn_global_load_lds((const unsigned*)((const char*)(gbase) + (voff)[_i]), (LAS unsigned*)(lds + (bufoff) + ldsw + _i * 8192), 16, 0, 0); } while (0)
; #define PG8_LDA(dst, b, h) do { _Pragma("unroll") for (int m = 0; m < 4; ++m) _Pragma("unroll") for (int k = 0; k < 2; ++k) dst[m][k] = *(const LAS bf16x8*)(lds + PG8_SA(b, h) + aoff + m * 2048 + k * 1024); } while (0)
; #define PG8_LDB(dst, b, h) do { _Pragma("unroll") for (int n = 0; n < 2; ++n) _Pragma("unroll") for (int k = 0; k < 2; ++k) dst[n][k] = *(const LAS bf16x8*)(lds + PG8_SB(b, h) + boff + n * 2048 + k * 1024); } while (0)
; #define PG8_MMA(ai, bj, At, Bt) do { __builtin_amdgcn_s_setprio(1); _Pragma("unroll") for (int m = 0; m < 4; ++m) _Pragma("unroll") for (int n = 0; n < 2; ++n) _Pragma("unroll") for (int k = 0; k < 2; ++k) \
;         acc[ai][bj][m][n] = __builtin_amdgcn_mfma_f32_16x16x32_bf16(Bt[n][k], At[m][k], acc[ai][bj][m][n], 0, 0, 0); __builtin_amdgcn_s_setprio(0); } while (0)
; #define PG8_WAIT_V(n) asm volatile("s_waitcnt vmcnt(" #n ")" ::: "memory")
; #define PG8_WAIT_L(n) asm volatile("s_waitcnt lgkmcnt(" #n ")" ::: "memory")
; #define PG8_BAR __builtin_amdgcn_s_barrier()
; #define PG8_SCHED __builtin_amdgcn_sched_barrier(0)
; template <class Epi>
; __device__ __forceinline__ void gemm_phase(ldsp lds, const Gemm g, const StaticOrder& S, const Epi& E) {
;     ...
;             PG8_WAIT_V(10); PG8_BAR; PG8_MMA(1, 1, At, B1); PG8_BAR;
;             PG8_LDB(B0, 1, 0); PG8_SCHED; PG8_LDA(At, 1, 0); PG8_STAGE(PG8_SA(0, 1), a2 + hstep, voffA);
;             PG8_WAIT_L(8); PG8_WAIT_V(10); PG8_BAR; PG8_WAIT_L(0); PG8_MMA(0, 0, At, B0); PG8_BAR; PG8_SCHED;
	v_mfma_f32_16x16x32_bf16 v[8:11], v[140:143], v[172:175], v[8:11]
	s_setprio 0
	s_add_u32 s54, s26, 0x60000
	s_addc_u32 s55, s27, 0
	s_add_i32 s56, s46, s35
	s_mov_b32 m0, s56
	s_nop 0
	global_load_lds_dwordx4 v194, s[54:55]
	s_add_i32 m0, s56, 0x2000
	s_nop 0
	global_load_lds_dwordx4 v198, s[54:55]
	s_waitcnt vmcnt(10)
	s_barrier
	s_nop 3
	s_setprio 1
	v_mfma_f32_16x16x32_bf16 v[52:55], v[176:179], v[144:147], v[52:55]
	v_mfma_f32_16x16x32_bf16 v[44:47], v[184:187], v[144:147], v[44:47]
	v_mfma_f32_16x16x32_bf16 v[36:39], v[176:179], v[152:155], v[36:39]
	v_mfma_f32_16x16x32_bf16 v[28:31], v[184:187], v[152:155], v[28:31]
	v_mfma_f32_16x16x32_bf16 v[20:23], v[176:179], v[160:163], v[20:23]
	v_mfma_f32_16x16x32_bf16 v[12:15], v[184:187], v[160:163], v[12:15]
	v_mfma_f32_16x16x32_bf16 v[4:7], v[176:179], v[168:171], v[4:7]
	v_mfma_f32_16x16x32_bf16 v[0:3], v[184:187], v[168:171], v[0:3]
	v_mfma_f32_16x16x32_bf16 v[52:55], v[180:183], v[148:151], v[52:55]
	v_mfma_f32_16x16x32_bf16 v[44:47], v[188:191], v[148:151], v[44:47]
	v_mfma_f32_16x16x32_bf16 v[36:39], v[180:183], v[156:159], v[36:39]
	v_mfma_f32_16x16x32_bf16 v[28:31], v[188:191], v[156:159], v[28:31]
	v_mfma_f32_16x16x32_bf16 v[20:23], v[180:183], v[164:167], v[20:23]
	v_mfma_f32_16x16x32_bf16 v[12:15], v[188:191], v[164:167], v[12:15]
	v_mfma_f32_16x16x32_bf16 v[4:7], v[180:183], v[172:175], v[4:7]
	s_barrier
	v_mfma_f32_16x16x32_bf16 v[0:3], v[188:191], v[172:175], v[0:3]
	s_setprio 0
	s_add_i32 s54, 0, 0x18000
	ds_read_b128 v[128:131], v247 offset:32768
	ds_read_b128 v[132:135], v247 offset:33792
	ds_read_b128 v[136:139], v247 offset:34816
	ds_read_b128 v[140:143], v247 offset:35840
	s_add_u32 s28, s28, 0x60000
	s_addc_u32 s29, s29, 0
	s_mov_b32 m0, s38
	ds_read_b128 v[144:147], v224 offset:32768
	ds_read_b128 v[148:151], v224 offset:33792
	ds_read_b128 v[152:155], v224 offset:34816
	ds_read_b128 v[156:159], v224 offset:35840
	ds_read_b128 v[160:163], v224 offset:36864
	ds_read_b128 v[164:167], v224 offset:37888
	ds_read_b128 v[168:171], v224 offset:38912
	ds_read_b128 v[172:175], v224 offset:39936
	global_load_lds_dwordx4 v192, s[28:29]
	s_mov_b32 m0, s39
	s_nop 0
	global_load_lds_dwordx4 v196, s[28:29]
	s_waitcnt lgkmcnt(8)
	s_waitcnt vmcnt(10)
	s_barrier
	s_waitcnt lgkmcnt(0)
	s_setprio 1
	s_waitcnt lgkmcnt(0)
	v_mfma_f32_16x16x32_bf16 v[124:127], v[128:131], v[144:147], v[124:127]
	v_mfma_f32_16x16x32_bf16 v[120:123], v[136:139], v[144:147], v[120:123]
	v_mfma_f32_16x16x32_bf16 v[116:119], v[128:131], v[152:155], v[116:119]
	v_mfma_f32_16x16x32_bf16 v[104:107], v[136:139], v[152:155], v[104:107]
	v_mfma_f32_16x16x32_bf16 v[96:99], v[128:131], v[160:163], v[96:99]
	v_mfma_f32_16x16x32_bf16 v[88:91], v[136:139], v[160:163], v[88:91]
	v_mfma_f32_16x16x32_bf16 v[80:83], v[128:131], v[168:171], v[80:83]
	v_mfma_f32_16x16x32_bf16 v[72:75], v[136:139], v[168:171], v[72:75]
	v_mfma_f32_16x16x32_bf16 v[124:127], v[132:135], v[148:151], v[124:127]
	v_mfma_f32_16x16x32_bf16 v[120:123], v[140:143], v[148:151], v[120:123]
	v_mfma_f32_16x16x32_bf16 v[116:119], v[132:135], v[156:159], v[116:119]
	v_mfma_f32_16x16x32_bf16 v[104:107], v[140:143], v[156:159], v[104:107]
	v_mfma_f32_16x16x32_bf16 v[96:99], v[132:135], v[164:167], v[96:99]
	v_mfma_f32_16x16x32_bf16 v[88:91], v[140:143], v[164:167], v[88:91]
	v_mfma_f32_16x16x32_bf16 v[80:83], v[132:135], v[172:175], v[80:83]
	s_barrier
	v_mfma_f32_16x16x32_bf16 v[72:75], v[140:143], v[172:175], v[72:75]
	s_setprio 0
	s_add_i32 s28, 0, 0x1c000
	s_add_i32 s29, s54, s35
	s_mov_b32 m0, s29
	ds_read_b128 v[176:179], v247 offset:49152
	ds_read_b128 v[180:183], v247 offset:50176
	ds_read_b128 v[184:187], v247 offset:51200
	ds_read_b128 v[188:191], v247 offset:52224
	global_load_lds_dwordx4 v194, s[98:99]
	s_add_i32 m0, s29, 0x2000
	s_nop 0
	global_load_lds_dwordx4 v198, s[98:99]
	s_waitcnt vmcnt(10)
	s_barrier
; #define PG8_STAGE(bufoff, gbase, voff) do { _Pragma("unroll") for (int _i = 0; _i < 2; ++_i) \
;         __builtin_amdgcn_global_load_lds((const unsigned*)((const char*)(gbase) + (voff)[_i]), (LAS unsigned*)(lds + (bufoff) + ldsw + _i * 8192), 16, 0, 0); } while (0)
; #define PG8_LDA(dst, b, h) do { _Pragma("unroll") for (int m = 0; m < 4; ++m) _Pragma("unroll") for (int k = 0; k < 2; ++k) dst[m][k] = *(const LAS bf16x8*)(lds + PG8_SA(b, h) + aoff + m * 2048 + k * 1024); } while (0)
; #define PG8_LDB(dst, b, h) do { _Pragma("unroll") for (int n = 0; n < 2; ++n) _Pragma("unroll") for (int k = 0; k < 2; ++k) dst[n][k] = *(const LAS bf16x8*)(lds + PG8_SB(b, h) + boff + n * 2048 + k * 1024); } while (0)
; #define PG8_MMA(ai, bj, At, Bt) do { __builtin_amdgcn_s_setprio(1); _Pragma("unroll") for (int m = 0; m < 4; ++m) _Pragma("unroll") for (int n = 0; n < 2; ++n) _Pragma("unroll") for (int k = 0; k < 2; ++k) \
;         acc[ai][bj][m][n] = __builtin_amdgcn_mfma_f32_16x16x32_bf16(Bt[n][k], At[m][k], acc[ai][bj][m][n], 0, 0, 0); __builtin_amdgcn_s_setprio(0); } while (0)
; #define PG8_WAIT_V(n) asm volatile("s_waitcnt vmcnt(" #n ")" ::: "memory")
; #define PG8_WAIT_L(n) asm volatile("s_waitcnt lgkmcnt(" #n ")" ::: "memory")
; #define PG8_BAR __builtin_amdgcn_s_barrier()
; #define PG8_SCHED __builtin_amdgcn_sched_barrier(0)
; template <class Epi>
; __device__ __forceinline__ void gemm_phase(ldsp lds, const Gemm g, const StaticOrder& S, const Epi& E) {
;     ...
;             PG8_WAIT_L(8); PG8_WAIT_V(10); PG8_BAR; PG8_WAIT_L(0); PG8_MMA(0, 0, At, B0); PG8_BAR; PG8_SCHED;
;             PG8_LDB(B1, 1, 1); PG8_STAGE(PG8_SB(1, 0), b3, voffB);
;             PG8_WAIT_V(10); PG8_BAR; PG8_WAIT_L(0); PG8_MMA(0, 1, At, B1); PG8_BAR;
;             PG8_LDA(At, 1, 1); PG8_STAGE(PG8_SA(1, 0), a3, voffA);
;             PG8_WAIT_V(10); PG8_BAR; PG8_WAIT_L(0); PG8_MMA(1, 0, At, B0); PG8_BAR; PG8_SCHED;
;             PG8_STAGE(PG8_SB(1, 1), b3 + hstep, voffB);
;             PG8_WAIT_V(10); PG8_BAR; PG8_MMA(1, 1, At, B1); PG8_BAR;
	s_waitcnt lgkmcnt(0)
	s_setprio 1
	s_waitcnt lgkmcnt(0)
	v_mfma_f32_16x16x32_bf16 v[112:115], v[176:179], v[144:147], v[112:115]
	v_mfma_f32_16x16x32_bf16 v[108:111], v[184:187], v[144:147], v[108:111]
	v_mfma_f32_16x16x32_bf16 v[100:103], v[176:179], v[152:155], v[100:103]
	v_mfma_f32_16x16x32_bf16 v[92:95], v[184:187], v[152:155], v[92:95]
	v_mfma_f32_16x16x32_bf16 v[84:87], v[176:179], v[160:163], v[84:87]
	v_mfma_f32_16x16x32_bf16 v[76:79], v[184:187], v[160:163], v[76:79]
	v_mfma_f32_16x16x32_bf16 v[68:71], v[176:179], v[168:171], v[68:71]
	v_mfma_f32_16x16x32_bf16 v[64:67], v[184:187], v[168:171], v[64:67]
	v_mfma_f32_16x16x32_bf16 v[112:115], v[180:183], v[148:151], v[112:115]
	v_mfma_f32_16x16x32_bf16 v[108:111], v[188:191], v[148:151], v[108:111]
	v_mfma_f32_16x16x32_bf16 v[100:103], v[180:183], v[156:159], v[100:103]
	v_mfma_f32_16x16x32_bf16 v[92:95], v[188:191], v[156:159], v[92:95]
	v_mfma_f32_16x16x32_bf16 v[84:87], v[180:183], v[164:167], v[84:87]
	v_mfma_f32_16x16x32_bf16 v[76:79], v[188:191], v[164:167], v[76:79]
	v_mfma_f32_16x16x32_bf16 v[68:71], v[180:183], v[172:175], v[68:71]
	s_barrier
	v_mfma_f32_16x16x32_bf16 v[64:67], v[188:191], v[172:175], v[64:67]
	s_setprio 0
	s_mov_b32 m0, s41
	ds_read_b128 v[144:147], v224 offset:49152
	ds_read_b128 v[148:151], v224 offset:50176
	ds_read_b128 v[152:155], v224 offset:51200
	ds_read_b128 v[156:159], v224 offset:52224
	ds_read_b128 v[160:163], v224 offset:53248
	ds_read_b128 v[164:167], v224 offset:54272
	ds_read_b128 v[168:171], v224 offset:55296
	ds_read_b128 v[172:175], v224 offset:56320
	global_load_lds_dwordx4 v192, s[100:101]
	s_mov_b32 m0, s42
	s_nop 0
	global_load_lds_dwordx4 v196, s[100:101]
	s_waitcnt vmcnt(12)
	s_barrier
	s_waitcnt lgkmcnt(0)
	s_setprio 1
	s_waitcnt lgkmcnt(0)
	v_mfma_f32_16x16x32_bf16 v[60:63], v[128:131], v[144:147], v[60:63]
	v_mfma_f32_16x16x32_bf16 v[56:59], v[136:139], v[144:147], v[56:59]
	v_mfma_f32_16x16x32_bf16 v[48:51], v[128:131], v[152:155], v[48:51]
	v_mfma_f32_16x16x32_bf16 v[40:43], v[136:139], v[152:155], v[40:43]
	v_mfma_f32_16x16x32_bf16 v[32:35], v[128:131], v[160:163], v[32:35]
	v_mfma_f32_16x16x32_bf16 v[24:27], v[136:139], v[160:163], v[24:27]
	v_mfma_f32_16x16x32_bf16 v[16:19], v[128:131], v[168:171], v[16:19]
	v_mfma_f32_16x16x32_bf16 v[8:11], v[136:139], v[168:171], v[8:11]
	v_mfma_f32_16x16x32_bf16 v[60:63], v[132:135], v[148:151], v[60:63]
	v_mfma_f32_16x16x32_bf16 v[56:59], v[140:143], v[148:151], v[56:59]
	v_mfma_f32_16x16x32_bf16 v[48:51], v[132:135], v[156:159], v[48:51]
	v_mfma_f32_16x16x32_bf16 v[40:43], v[140:143], v[156:159], v[40:43]
	v_mfma_f32_16x16x32_bf16 v[32:35], v[132:135], v[164:167], v[32:35]
	v_mfma_f32_16x16x32_bf16 v[24:27], v[140:143], v[164:167], v[24:27]
	v_mfma_f32_16x16x32_bf16 v[16:19], v[132:135], v[172:175], v[16:19]
	s_barrier
	v_mfma_f32_16x16x32_bf16 v[8:11], v[140:143], v[172:175], v[8:11]
	s_setprio 0
	s_add_u32 s26, s26, 0x60080
	s_addc_u32 s27, s27, 0
	s_add_i32 s28, s28, s35
	s_mov_b32 m0, s28
	s_nop 0
	global_load_lds_dwordx4 v194, s[26:27]
	s_add_i32 m0, s28, 0x2000
	s_nop 0
	global_load_lds_dwordx4 v198, s[26:27]
	s_waitcnt vmcnt(10)
	s_barrier
	s_nop 3
	s_setprio 1
	v_mfma_f32_16x16x32_bf16 v[52:55], v[176:179], v[144:147], v[52:55]
	v_mfma_f32_16x16x32_bf16 v[44:47], v[184:187], v[144:147], v[44:47]
	v_mfma_f32_16x16x32_bf16 v[36:39], v[176:179], v[152:155], v[36:39]
	v_mfma_f32_16x16x32_bf16 v[28:31], v[184:187], v[152:155], v[28:31]
	v_mfma_f32_16x16x32_bf16 v[20:23], v[176:179], v[160:163], v[20:23]
	v_mfma_f32_16x16x32_bf16 v[12:15], v[184:187], v[160:163], v[12:15]
	v_mfma_f32_16x16x32_bf16 v[4:7], v[176:179], v[168:171], v[4:7]
	v_mfma_f32_16x16x32_bf16 v[0:3], v[184:187], v[168:171], v[0:3]
	v_mfma_f32_16x16x32_bf16 v[52:55], v[180:183], v[148:151], v[52:55]
	v_mfma_f32_16x16x32_bf16 v[44:47], v[188:191], v[148:151], v[44:47]
	v_mfma_f32_16x16x32_bf16 v[36:39], v[180:183], v[156:159], v[36:39]
	v_mfma_f32_16x16x32_bf16 v[28:31], v[188:191], v[156:159], v[28:31]
	v_mfma_f32_16x16x32_bf16 v[20:23], v[180:183], v[164:167], v[20:23]
	v_mfma_f32_16x16x32_bf16 v[12:15], v[188:191], v[164:167], v[12:15]
	v_mfma_f32_16x16x32_bf16 v[4:7], v[180:183], v[172:175], v[4:7]
	s_barrier
	v_mfma_f32_16x16x32_bf16 v[0:3], v[188:191], v[172:175], v[0:3]
	s_setprio 0
	s_add_i32 s53, s53, 2
	s_add_u32 s24, s24, 0x100
	s_addc_u32 s25, s25, 0
	s_cmp_gt_u32 s53, 21
	s_cbranch_scc1 .LBB0_642

; #define PG8_STAGE(bufoff, gbase, voff) do { _Pragma("unroll") for (int _i = 0; _i < 2; ++_i) \
;         __builtin_amdgcn_global_load_lds((const unsigned*)((const char*)(gbase) + (voff)[_i]), (LAS unsigned*)(lds + (bufoff) + ldsw + _i * 8192), 16, 0, 0); } while (0)
; #define PG8_LDA(dst, b, h) do { _Pragma("unroll") for (int m = 0; m < 4; ++m) _Pragma("unroll") for (int k = 0; k < 2; ++k) dst[m][k] = *(const LAS bf16x8*)(lds + PG8_SA(b, h) + aoff + m * 2048 + k * 1024); } while (0)
; #define PG8_LDB(dst, b, h) do { _Pragma("unroll") for (int n = 0; n < 2; ++n) _Pragma("unroll") for (int k = 0; k < 2; ++k) dst[n][k] = *(const LAS bf16x8*)(lds + PG8_SB(b, h) + boff + n * 2048 + k * 1024); } while (0)
; #define PG8_MMA(ai, bj, At, Bt) do { __builtin_amdgcn_s_setprio(1); _Pragma("unroll") for (int m = 0; m < 4; ++m) _Pragma("unroll") for (int n = 0; n < 2; ++n) _Pragma("unroll") for (int k = 0; k < 2; ++k) \
;         acc[ai][bj][m][n] = __builtin_amdgcn_mfma_f32_16x16x32_bf16(Bt[n][k], At[m][k], acc[ai][bj][m][n], 0, 0, 0); __builtin_amdgcn_s_setprio(0); } while (0)
; #define PG8_WAIT_V(n) asm volatile("s_waitcnt vmcnt(" #n ")" ::: "memory")
; template <class Epi>
; __device__ __forceinline__ void gemm_phase(ldsp lds, const Gemm g, const StaticOrder& S, const Epi& E) {
;     ...
;         for (int t = 0; t < nt; t += 2) {
;             const bool last = (t == nt - 2);
;             const char* a1 = cA + (size_t)(t + 1) * kstep;
;             const char* a2 = last ? nA : cA + (size_t)(t + 2) * kstep; const char* b2 = last ? nB : cB + (size_t)(t + 2) * kstep;
;             const char* a3 = a2 + kstep; const char* b3 = b2 + kstep;
;             if constexpr (Epi::NPRE > 0) { if (last) E.pre(pre, cur, wr, fr); }
;             if constexpr (Epi::MID_T > 0) { if (t == Epi::MID_T) E.mid(acc, cur, wr, wc, fr, fq); }
;             PG8_LDB(B0, 0, 0); PG8_SCHED; PG8_LDA(At, 0, 0); PG8_STAGE(PG8_SA(1, 1), a1 + hstep, voffA);
;             PG8_WAIT_L(8); PG8_WAIT_V(10); PG8_BAR; PG8_WAIT_L(0); PG8_MMA(0, 0, At, B0); PG8_BAR; PG8_SCHED;
;             PG8_LDB(B1, 0, 1); PG8_STAGE(PG8_SB(0, 0), b2, voffB);
;             PG8_WAIT_V(10); PG8_BAR; PG8_WAIT_L(0); PG8_MMA(0, 1, At, B1); PG8_BAR;
;             PG8_LDA(At, 0, 1); PG8_STAGE(PG8_SA(0, 0), a2, voffA);
;             PG8_WAIT_V(10); PG8_BAR; PG8_WAIT_L(0); PG8_MMA(1, 0, At, B0); PG8_BAR; PG8_SCHED;
.LBB0_733:
	ds_read_b128 v[128:131], v211
	ds_read_b128 v[132:135], v211 offset:1024
	ds_read_b128 v[136:139], v211 offset:2048
	ds_read_b128 v[140:143], v211 offset:3072
	s_add_u32 s24, s22, 0xfff80080
	s_addc_u32 s25, s23, -1
	s_cmp_eq_u32 s46, 28
	s_cselect_b32 s27, s13, s25
	s_cselect_b32 s26, s19, s24
	s_cselect_b32 s25, s11, s45
	s_cselect_b32 s24, s43, s44
	s_add_i32 m0, s21, 0xc000
	ds_read_b128 v[144:147], v212
	ds_read_b128 v[148:151], v212 offset:1024
	ds_read_b128 v[152:155], v212 offset:2048
	ds_read_b128 v[156:159], v212 offset:3072
	ds_read_b128 v[160:163], v212 offset:4096
	ds_read_b128 v[164:167], v212 offset:5120
	ds_read_b128 v[168:171], v212 offset:6144
	ds_read_b128 v[172:175], v212 offset:7168
	global_load_lds_dwordx4 v184, s[22:23]
	s_add_i32 m0, s21, 0xe000
	s_nop 0
	global_load_lds_dwordx4 v186, s[22:23]
	s_waitcnt lgkmcnt(8)
	s_waitcnt vmcnt(10)
	s_barrier
	s_waitcnt lgkmcnt(0)
	s_setprio 1
	s_waitcnt lgkmcnt(0)
	v_mfma_f32_16x16x32_bf16 v[124:127], v[128:131], v[144:147], v[124:127]
	v_mfma_f32_16x16x32_bf16 v[120:123], v[136:139], v[144:147], v[120:123]
	v_mfma_f32_16x16x32_bf16 v[108:111], v[128:131], v[152:155], v[108:111]
	v_mfma_f32_16x16x32_bf16 v[104:107], v[136:139], v[152:155], v[104:107]
	v_mfma_f32_16x16x32_bf16 v[92:95], v[128:131], v[160:163], v[92:95]
	v_mfma_f32_16x16x32_bf16 v[88:91], v[136:139], v[160:163], v[88:91]
	v_mfma_f32_16x16x32_bf16 v[76:79], v[128:131], v[168:171], v[76:79]
	v_mfma_f32_16x16x32_bf16 v[72:75], v[136:139], v[168:171], v[72:75]
	v_mfma_f32_16x16x32_bf16 v[124:127], v[132:135], v[148:151], v[124:127]
	v_mfma_f32_16x16x32_bf16 v[120:123], v[140:143], v[148:151], v[120:123]
	v_mfma_f32_16x16x32_bf16 v[108:111], v[132:135], v[156:159], v[108:111]
	v_mfma_f32_16x16x32_bf16 v[104:107], v[140:143], v[156:159], v[104:107]
	v_mfma_f32_16x16x32_bf16 v[92:95], v[132:135], v[164:167], v[92:95]
	v_mfma_f32_16x16x32_bf16 v[88:91], v[140:143], v[164:167], v[88:91]
	v_mfma_f32_16x16x32_bf16 v[76:79], v[132:135], v[172:175], v[76:79]
	s_barrier
	v_mfma_f32_16x16x32_bf16 v[72:75], v[140:143], v[172:175], v[72:75]
	s_setprio 0
	s_add_i32 s47, s40, s29
	s_add_u32 s98, s24, 0x80
	s_addc_u32 s99, s25, 0
	s_mov_b32 m0, s47
	ds_read_b128 v[192:195], v213
	ds_read_b128 v[196:199], v213 offset:1024
	ds_read_b128 v[200:203], v213 offset:2048
	ds_read_b128 v[204:207], v213 offset:3072
	global_load_lds_dwordx4 v178, s[24:25]
	s_add_i32 m0, s47, 0x2000
	s_nop 0
	global_load_lds_dwordx4 v182, s[24:25]
	s_waitcnt vmcnt(10)
	s_barrier
	s_waitcnt lgkmcnt(0)
	s_setprio 1
	s_waitcnt lgkmcnt(0)
	v_mfma_f32_16x16x32_bf16 v[116:119], v[192:195], v[144:147], v[116:119]
	v_mfma_f32_16x16x32_bf16 v[112:115], v[200:203], v[144:147], v[112:115]
	v_mfma_f32_16x16x32_bf16 v[100:103], v[192:195], v[152:155], v[100:103]
	v_mfma_f32_16x16x32_bf16 v[96:99], v[200:203], v[152:155], v[96:99]
	v_mfma_f32_16x16x32_bf16 v[84:87], v[192:195], v[160:163], v[84:87]
	v_mfma_f32_16x16x32_bf16 v[80:83], v[200:203], v[160:163], v[80:83]
	v_mfma_f32_16x16x32_bf16 v[68:71], v[192:195], v[168:171], v[68:71]
	v_mfma_f32_16x16x32_bf16 v[64:67], v[200:203], v[168:171], v[64:67]
	v_mfma_f32_16x16x32_bf16 v[116:119], v[196:199], v[148:151], v[116:119]
	v_mfma_f32_16x16x32_bf16 v[112:115], v[204:207], v[148:151], v[112:115]
	v_mfma_f32_16x16x32_bf16 v[100:103], v[196:199], v[156:159], v[100:103]
	v_mfma_f32_16x16x32_bf16 v[96:99], v[204:207], v[156:159], v[96:99]
	v_mfma_f32_16x16x32_bf16 v[84:87], v[196:199], v[164:167], v[84:87]
	v_mfma_f32_16x16x32_bf16 v[80:83], v[204:207], v[164:167], v[80:83]
	v_mfma_f32_16x16x32_bf16 v[68:71], v[196:199], v[172:175], v[68:71]
	s_barrier
	v_mfma_f32_16x16x32_bf16 v[64:67], v[204:207], v[172:175], v[64:67]
	s_setprio 0
	s_mov_b32 m0, s21
	s_add_u32 s100, s26, 0x80
	s_addc_u32 s101, s27, 0
	ds_read_b128 v[144:147], v212 offset:16384
	ds_read_b128 v[148:151], v212 offset:17408
	ds_read_b128 v[152:155], v212 offset:18432
	ds_read_b128 v[156:159], v212 offset:19456
	ds_read_b128 v[160:163], v212 offset:20480
	ds_read_b128 v[164:167], v212 offset:21504
	ds_read_b128 v[168:171], v212 offset:22528
	ds_read_b128 v[172:175], v212 offset:23552
	global_load_lds_dwordx4 v176, s[26:27]
	s_mov_b32 m0, s30
	s_nop 0
	global_load_lds_dwordx4 v180, s[26:27]
	s_waitcnt vmcnt(12)
	s_barrier
	s_waitcnt lgkmcnt(0)
	s_setprio 1
	s_waitcnt lgkmcnt(0)
	v_mfma_f32_16x16x32_bf16 v[60:63], v[128:131], v[144:147], v[60:63]
	v_mfma_f32_16x16x32_bf16 v[56:59], v[136:139], v[144:147], v[56:59]
	v_mfma_f32_16x16x32_bf16 v[44:47], v[128:131], v[152:155], v[44:47]
	v_mfma_f32_16x16x32_bf16 v[40:43], v[136:139], v[152:155], v[40:43]
	v_mfma_f32_16x16x32_bf16 v[28:31], v[128:131], v[160:163], v[28:31]
	v_mfma_f32_16x16x32_bf16 v[24:27], v[136:139], v[160:163], v[24:27]
	v_mfma_f32_16x16x32_bf16 v[12:15], v[128:131], v[168:171], v[12:15]
	v_mfma_f32_16x16x32_bf16 v[8:11], v[136:139], v[168:171], v[8:11]
	v_mfma_f32_16x16x32_bf16 v[60:63], v[132:135], v[148:151], v[60:63]
	v_mfma_f32_16x16x32_bf16 v[56:59], v[140:143], v[148:151], v[56:59]
	v_mfma_f32_16x16x32_bf16 v[44:47], v[132:135], v[156:159], v[44:47]
	v_mfma_f32_16x16x32_bf16 v[40:43], v[140:143], v[156:159], v[40:43]
	v_mfma_f32_16x16x32_bf16 v[28:31], v[132:135], v[164:167], v[28:31]
	v_mfma_f32_16x16x32_bf16 v[24:27], v[140:143], v[164:167], v[24:27]
	v_mfma_f32_16x16x32_bf16 v[12:15], v[132:135], v[172:175], v[12:15]
	s_barrier
	v_mfma_f32_16x16x32_bf16 v[8:11], v[140:143], v[172:175], v[8:11]
	s_setprio 0
	s_add_u32 s50, s24, 0x80000
	s_addc_u32 s51, s25, 0
	s_add_i32 s47, s41, s29
	s_mov_b32 m0, s47
	s_nop 0
	global_load_lds_dwordx4 v178, s[50:51]
	s_add_i32 m0, s47, 0x2000
	s_nop 0
	global_load_lds_dwordx4 v182, s[50:51]
	s_waitcnt vmcnt(10)
	s_barrier
; #define PG8_STAGE(bufoff, gbase, voff) do { _Pragma("unroll") for (int _i = 0; _i < 2; ++_i) \
;         __builtin_amdgcn_global_load_lds((const unsigned*)((const char*)(gbase) + (voff)[_i]), (LAS unsigned*)(lds + (bufoff) + ldsw + _i * 8192), 16, 0, 0); } while (0)
; #define PG8_LDA(dst, b, h) do { _Pragma("unroll") for (int m = 0; m < 4; ++m) _Pragma("unroll") for (int k = 0; k < 2; ++k) dst[m][k] = *(const LAS bf16x8*)(lds + PG8_SA(b, h) + aoff + m * 2048 + k * 1024); } while (0)
; #define PG8_LDB(dst, b, h) do { _Pragma("unroll") for (int n = 0; n < 2; ++n) _Pragma("unroll") for (int k = 0; k < 2; ++k) dst[n][k] = *(const LAS bf16x8*)(lds + PG8_SB(b, h) + boff + n * 2048 + k * 1024); } while (0)
; #define PG8_MMA(ai, bj, At, Bt) do { __builtin_amdgcn_s_setprio(1); _Pragma("unroll") for (int m = 0; m < 4; ++m) _Pragma("unroll") for (int n = 0; n < 2; ++n) _Pragma("unroll") for (int k = 0; k < 2; ++k) \
;         acc[ai][bj][m][n] = __builtin_amdgcn_mfma_f32_16x16x32_bf16(Bt[n][k], At[m][k], acc[ai][bj][m][n], 0, 0, 0); __builtin_amdgcn_s_setprio(0); } while (0)
; #define PG8_WAIT_V(n) asm volatile("s_waitcnt vmcnt(" #n ")" ::: "memory")
; #define PG8_WAIT_L(n) asm volatile("s_waitcnt lgkmcnt(" #n ")" ::: "memory")
; #define PG8_BAR __builtin_amdgcn_s_barrier()
; #define PG8_SCHED __builtin_amdgcn_sched_barrier(0)
; template <class Epi>
; __device__ __forceinline__ void gemm_phase(ldsp lds, const Gemm g, const StaticOrder& S, const Epi& E) {
;     ...
;             PG8_WAIT_V(10); PG8_BAR; PG8_MMA(1, 1, At, B1); PG8_BAR;
;             PG8_LDB(B0, 1, 0); PG8_SCHED; PG8_LDA(At, 1, 0); PG8_STAGE(PG8_SA(0, 1), a2 + hstep, voffA);
;             PG8_WAIT_L(8); PG8_WAIT_V(10); PG8_BAR; PG8_WAIT_L(0); PG8_MMA(0, 0, At, B0); PG8_BAR; PG8_SCHED;
;             PG8_LDB(B1, 1, 1); PG8_STAGE(PG8_SB(1, 0), b3, voffB);
;             PG8_WAIT_V(10); PG8_BAR; PG8_WAIT_L(0); PG8_MMA(0, 1, At, B1); PG8_BAR;
;             PG8_LDA(At, 1, 1); PG8_STAGE(PG8_SA(1, 0), a3, voffA);
;             PG8_WAIT_V(10); PG8_BAR; PG8_WAIT_L(0); PG8_MMA(1, 0, At, B0); PG8_BAR; PG8_SCHED;
;             PG8_STAGE(PG8_SB(1, 1), b3 + hstep, voffB);
;             PG8_WAIT_V(10); PG8_BAR; PG8_MMA(1, 1, At, B1); PG8_BAR;
	s_nop 3
	s_setprio 1
	v_mfma_f32_16x16x32_bf16 v[52:55], v[192:195], v[144:147], v[52:55]
	v_mfma_f32_16x16x32_bf16 v[48:51], v[200:203], v[144:147], v[48:51]
	v_mfma_f32_16x16x32_bf16 v[36:39], v[192:195], v[152:155], v[36:39]
	v_mfma_f32_16x16x32_bf16 v[32:35], v[200:203], v[152:155], v[32:35]
	v_mfma_f32_16x16x32_bf16 v[20:23], v[192:195], v[160:163], v[20:23]
	v_mfma_f32_16x16x32_bf16 v[16:19], v[200:203], v[160:163], v[16:19]
	v_mfma_f32_16x16x32_bf16 v[4:7], v[192:195], v[168:171], v[4:7]
	v_mfma_f32_16x16x32_bf16 v[0:3], v[200:203], v[168:171], v[0:3]
	v_mfma_f32_16x16x32_bf16 v[52:55], v[196:199], v[148:151], v[52:55]
	v_mfma_f32_16x16x32_bf16 v[48:51], v[204:207], v[148:151], v[48:51]
	v_mfma_f32_16x16x32_bf16 v[36:39], v[196:199], v[156:159], v[36:39]
	v_mfma_f32_16x16x32_bf16 v[32:35], v[204:207], v[156:159], v[32:35]
	v_mfma_f32_16x16x32_bf16 v[20:23], v[196:199], v[164:167], v[20:23]
	v_mfma_f32_16x16x32_bf16 v[16:19], v[204:207], v[164:167], v[16:19]
	v_mfma_f32_16x16x32_bf16 v[4:7], v[196:199], v[172:175], v[4:7]
	s_barrier
	v_mfma_f32_16x16x32_bf16 v[0:3], v[204:207], v[172:175], v[0:3]
	s_setprio 0
	s_add_i32 s47, 0, 0x18000
	ds_read_b128 v[128:131], v247 offset:32768
	ds_read_b128 v[132:135], v247 offset:33792
	ds_read_b128 v[136:139], v247 offset:34816
	ds_read_b128 v[140:143], v247 offset:35840
	s_add_u32 s26, s26, 0x80000
	s_addc_u32 s27, s27, 0
	s_mov_b32 m0, s31
	ds_read_b128 v[144:147], v212 offset:32768
	ds_read_b128 v[148:151], v212 offset:33792
	ds_read_b128 v[152:155], v212 offset:34816
	ds_read_b128 v[156:159], v212 offset:35840
	ds_read_b128 v[160:163], v212 offset:36864
	ds_read_b128 v[164:167], v212 offset:37888
	ds_read_b128 v[168:171], v212 offset:38912
	ds_read_b128 v[172:175], v212 offset:39936
	global_load_lds_dwordx4 v176, s[26:27]
	s_mov_b32 m0, s33
	s_nop 0
	global_load_lds_dwordx4 v180, s[26:27]
	s_waitcnt lgkmcnt(8)
	s_waitcnt vmcnt(10)
	s_barrier
	s_waitcnt lgkmcnt(0)
	s_setprio 1
	s_waitcnt lgkmcnt(0)
	v_mfma_f32_16x16x32_bf16 v[124:127], v[128:131], v[144:147], v[124:127]
	v_mfma_f32_16x16x32_bf16 v[120:123], v[136:139], v[144:147], v[120:123]
	v_mfma_f32_16x16x32_bf16 v[108:111], v[128:131], v[152:155], v[108:111]
	v_mfma_f32_16x16x32_bf16 v[104:107], v[136:139], v[152:155], v[104:107]
	v_mfma_f32_16x16x32_bf16 v[92:95], v[128:131], v[160:163], v[92:95]
	v_mfma_f32_16x16x32_bf16 v[88:91], v[136:139], v[160:163], v[88:91]
	v_mfma_f32_16x16x32_bf16 v[76:79], v[128:131], v[168:171], v[76:79]
	v_mfma_f32_16x16x32_bf16 v[72:75], v[136:139], v[168:171], v[72:75]
	v_mfma_f32_16x16x32_bf16 v[124:127], v[132:135], v[148:151], v[124:127]
	v_mfma_f32_16x16x32_bf16 v[120:123], v[140:143], v[148:151], v[120:123]
	v_mfma_f32_16x16x32_bf16 v[108:111], v[132:135], v[156:159], v[108:111]
	v_mfma_f32_16x16x32_bf16 v[104:107], v[140:143], v[156:159], v[104:107]
	v_mfma_f32_16x16x32_bf16 v[92:95], v[132:135], v[164:167], v[92:95]
	v_mfma_f32_16x16x32_bf16 v[88:91], v[140:143], v[164:167], v[88:91]
	v_mfma_f32_16x16x32_bf16 v[76:79], v[132:135], v[172:175], v[76:79]
	s_barrier
	v_mfma_f32_16x16x32_bf16 v[72:75], v[140:143], v[172:175], v[72:75]
	s_setprio 0
	s_add_i32 s26, 0, 0x1c000
	s_add_i32 s27, s47, s29
	s_mov_b32 m0, s27
	ds_read_b128 v[192:195], v247 offset:49152
	ds_read_b128 v[196:199], v247 offset:50176
	ds_read_b128 v[200:203], v247 offset:51200
	ds_read_b128 v[204:207], v247 offset:52224
	global_load_lds_dwordx4 v178, s[98:99]
	s_add_i32 m0, s27, 0x2000
	s_nop 0
	global_load_lds_dwordx4 v182, s[98:99]
	s_waitcnt vmcnt(10)
	s_barrier
	s_waitcnt lgkmcnt(0)
	s_setprio 1
	s_waitcnt lgkmcnt(0)
	v_mfma_f32_16x16x32_bf16 v[116:119], v[192:195], v[144:147], v[116:119]
	v_mfma_f32_16x16x32_bf16 v[112:115], v[200:203], v[144:147], v[112:115]
	v_mfma_f32_16x16x32_bf16 v[100:103], v[192:195], v[152:155], v[100:103]
	v_mfma_f32_16x16x32_bf16 v[96:99], v[200:203], v[152:155], v[96:99]
	v_mfma_f32_16x16x32_bf16 v[84:87], v[192:195], v[160:163], v[84:87]
	v_mfma_f32_16x16x32_bf16 v[80:83], v[200:203], v[160:163], v[80:83]
	v_mfma_f32_16x16x32_bf16 v[68:71], v[192:195], v[168:171], v[68:71]
	v_mfma_f32_16x16x32_bf16 v[64:67], v[200:203], v[168:171], v[64:67]
	v_mfma_f32_16x16x32_bf16 v[116:119], v[196:199], v[148:151], v[116:119]
	v_mfma_f32_16x16x32_bf16 v[112:115], v[204:207], v[148:151], v[112:115]
	v_mfma_f32_16x16x32_bf16 v[100:103], v[196:199], v[156:159], v[100:103]
	v_mfma_f32_16x16x32_bf16 v[96:99], v[204:207], v[156:159], v[96:99]
	v_mfma_f32_16x16x32_bf16 v[84:87], v[196:199], v[164:167], v[84:87]
	v_mfma_f32_16x16x32_bf16 v[80:83], v[204:207], v[164:167], v[80:83]
	v_mfma_f32_16x16x32_bf16 v[68:71], v[196:199], v[172:175], v[68:71]
	s_barrier
	v_mfma_f32_16x16x32_bf16 v[64:67], v[204:207], v[172:175], v[64:67]
	s_setprio 0
	s_mov_b32 m0, s35
	ds_read_b128 v[144:147], v212 offset:49152
	ds_read_b128 v[148:151], v212 offset:50176
	ds_read_b128 v[152:155], v212 offset:51200
	ds_read_b128 v[156:159], v212 offset:52224
	ds_read_b128 v[160:163], v212 offset:53248
	ds_read_b128 v[164:167], v212 offset:54272
	ds_read_b128 v[168:171], v212 offset:55296
	ds_read_b128 v[172:175], v212 offset:56320
	global_load_lds_dwordx4 v176, s[100:101]
	s_mov_b32 m0, s36
	s_nop 0
	global_load_lds_dwordx4 v180, s[100:101]
	s_waitcnt vmcnt(12)
	s_barrier
; #define PG8_STAGE(bufoff, gbase, voff) do { _Pragma("unroll") for (int _i = 0; _i < 2; ++_i) \
;         __builtin_amdgcn_global_load_lds((const unsigned*)((const char*)(gbase) + (voff)[_i]), (LAS unsigned*)(lds + (bufoff) + ldsw + _i * 8192), 16, 0, 0); } while (0)
; #define PG8_MMA(ai, bj, At, Bt) do { __builtin_amdgcn_s_setprio(1); _Pragma("unroll") for (int m = 0; m < 4; ++m) _Pragma("unroll") for (int n = 0; n < 2; ++n) _Pragma("unroll") for (int k = 0; k < 2; ++k) \
;         acc[ai][bj][m][n] = __builtin_amdgcn_mfma_f32_16x16x32_bf16(Bt[n][k], At[m][k], acc[ai][bj][m][n], 0, 0, 0); __builtin_amdgcn_s_setprio(0); } while (0)
; #define PG8_WAIT_V(n) asm volatile("s_waitcnt vmcnt(" #n ")" ::: "memory")
; #define PG8_WAIT_L(n) asm volatile("s_waitcnt lgkmcnt(" #n ")" ::: "memory")
; #define PG8_BAR __builtin_amdgcn_s_barrier()
; #define PG8_SCHED __builtin_amdgcn_sched_barrier(0)
; template <class Epi>
; __device__ __forceinline__ void gemm_phase(ldsp lds, const Gemm g, const StaticOrder& S, const Epi& E) {
;     ...
;             PG8_WAIT_V(10); PG8_BAR; PG8_WAIT_L(0); PG8_MMA(1, 0, At, B0); PG8_BAR; PG8_SCHED;
;             PG8_STAGE(PG8_SB(1, 1), b3 + hstep, voffB);
;             PG8_WAIT_V(10); PG8_BAR; PG8_MMA(1, 1, At, B1); PG8_BAR;
	s_waitcnt lgkmcnt(0)
	s_setprio 1
	s_waitcnt lgkmcnt(0)
	v_mfma_f32_16x16x32_bf16 v[60:63], v[128:131], v[144:147], v[60:63]
	v_mfma_f32_16x16x32_bf16 v[56:59], v[136:139], v[144:147], v[56:59]
	v_mfma_f32_16x16x32_bf16 v[44:47], v[128:131], v[152:155], v[44:47]
	v_mfma_f32_16x16x32_bf16 v[40:43], v[136:139], v[152:155], v[40:43]
	v_mfma_f32_16x16x32_bf16 v[28:31], v[128:131], v[160:163], v[28:31]
	v_mfma_f32_16x16x32_bf16 v[24:27], v[136:139], v[160:163], v[24:27]
	v_mfma_f32_16x16x32_bf16 v[12:15], v[128:131], v[168:171], v[12:15]
	v_mfma_f32_16x16x32_bf16 v[8:11], v[136:139], v[168:171], v[8:11]
	v_mfma_f32_16x16x32_bf16 v[60:63], v[132:135], v[148:151], v[60:63]
	v_mfma_f32_16x16x32_bf16 v[56:59], v[140:143], v[148:151], v[56:59]
	v_mfma_f32_16x16x32_bf16 v[44:47], v[132:135], v[156:159], v[44:47]
	v_mfma_f32_16x16x32_bf16 v[40:43], v[140:143], v[156:159], v[40:43]
	v_mfma_f32_16x16x32_bf16 v[28:31], v[132:135], v[164:167], v[28:31]
	v_mfma_f32_16x16x32_bf16 v[24:27], v[140:143], v[164:167], v[24:27]
	v_mfma_f32_16x16x32_bf16 v[12:15], v[132:135], v[172:175], v[12:15]
	s_barrier
	v_mfma_f32_16x16x32_bf16 v[8:11], v[140:143], v[172:175], v[8:11]
	s_setprio 0
	s_add_u32 s24, s24, 0x80080
	s_addc_u32 s25, s25, 0
	s_add_i32 s26, s26, s29
	s_mov_b32 m0, s26
	s_nop 0
	global_load_lds_dwordx4 v178, s[24:25]
	s_add_i32 m0, s26, 0x2000
	s_nop 0
	global_load_lds_dwordx4 v182, s[24:25]
	s_waitcnt vmcnt(10)
	s_barrier
	s_nop 3
	s_setprio 1
	v_mfma_f32_16x16x32_bf16 v[52:55], v[192:195], v[144:147], v[52:55]
	v_mfma_f32_16x16x32_bf16 v[48:51], v[200:203], v[144:147], v[48:51]
	v_mfma_f32_16x16x32_bf16 v[36:39], v[192:195], v[152:155], v[36:39]
	v_mfma_f32_16x16x32_bf16 v[32:35], v[200:203], v[152:155], v[32:35]
	v_mfma_f32_16x16x32_bf16 v[20:23], v[192:195], v[160:163], v[20:23]
	v_mfma_f32_16x16x32_bf16 v[16:19], v[200:203], v[160:163], v[16:19]
	v_mfma_f32_16x16x32_bf16 v[4:7], v[192:195], v[168:171], v[4:7]
	v_mfma_f32_16x16x32_bf16 v[0:3], v[200:203], v[168:171], v[0:3]
	v_mfma_f32_16x16x32_bf16 v[52:55], v[196:199], v[148:151], v[52:55]
	v_mfma_f32_16x16x32_bf16 v[48:51], v[204:207], v[148:151], v[48:51]
	v_mfma_f32_16x16x32_bf16 v[36:39], v[196:199], v[156:159], v[36:39]
	v_mfma_f32_16x16x32_bf16 v[32:35], v[204:207], v[156:159], v[32:35]
	v_mfma_f32_16x16x32_bf16 v[20:23], v[196:199], v[164:167], v[20:23]
	v_mfma_f32_16x16x32_bf16 v[16:19], v[204:207], v[164:167], v[16:19]
	v_mfma_f32_16x16x32_bf16 v[4:7], v[196:199], v[172:175], v[4:7]
	s_barrier
	v_mfma_f32_16x16x32_bf16 v[0:3], v[204:207], v[172:175], v[0:3]
	s_setprio 0
	s_add_i32 s46, s46, 2
	s_add_u32 s22, s22, 0x100
	s_addc_u32 s23, s23, 0
	s_add_u32 s44, s44, 0x100
	s_addc_u32 s45, s45, 0
	s_cmp_gt_u32 s46, 29
	s_cbranch_scc0 .LBB0_733
;     __device__ __forceinline__ void ld(f32x4 (&xv)[2][2][2], int row0, int col0, int ai, int mh) const {
; #pragma unroll
;         for (int mm = 0; mm < 2; ++mm)
; #pragma unroll
;             for (int bj = 0; bj < 2; ++bj) { const size_t off = (size_t)(row0 + ai * 128 + (2 * mh + mm) * 16) * 2048 + col0 + bj * 128;
;                 xv[mm][bj][0] = *(const f32x4*)(base + off); xv[mm][bj][1] = *(const f32x4*)(base + off + 4); }
;     }
;     __device__ __forceinline__ void fin(const f32x4 (&acc)[2][2][4][2], const f32x4 (&xv)[2][2][2], int row0, int col0, int fq, int ai, int mh) const {
; #pragma unroll
;         for (int mm = 0; mm < 2; ++mm) { const int m = 2 * mh + mm; const int row = row0 + ai * 128 + m * 16; float sq = 0.f;
; #pragma unroll
;             for (int bj = 0; bj < 2; ++bj) { const size_t off = (size_t)row * 2048 + col0 + bj * 128;
;                 const f32x4 y0 = xv[mm][bj][0] + acc[ai][bj][m][0], y1 = xv[mm][bj][1] + acc[ai][bj][m][1];
;                 *(f32x4*)(out + off) = y0; *(f32x4*)(out + off + 4) = y1;
;                 if (ob) *(u32x4*)(ob + off) = pack8(y0, y1);
;                 sq += (y0[0] * y0[0] + y0[1] * y0[1]) + (y0[2] * y0[2] + y0[3] * y0[3]) + (y1[0] * y1[0] + y1[1] * y1[1]) + (y1[2] * y1[2] + y1[3] * y1[3]); }
;             sq += __shfl_xor(sq, 16); sq += __shfl_xor(sq, 32);
;             if (fq == 0) atomicAdd(ssq + row, (unsigned long long)(sq * 16777216.0f + 0.5f)); }
;     }
	v_lshl_add_u32 v194, s18, 8, v208
	v_lshl_or_b32 v192, s20, 8, v210
	v_ashrrev_i32_e32 v195, 31, v194
	v_ashrrev_i32_e32 v193, 31, v192
	v_lshlrev_b64 v[128:129], 11, v[194:195]
	v_lshl_add_u64 v[218:219], v[128:129], 0, v[192:193]
	v_lshlrev_b64 v[238:239], 2, v[218:219]
	v_lshl_add_u64 v[128:129], s[64:65], 0, v[238:239]
	global_load_dwordx4 v[222:225], v[128:129], off
	global_load_dwordx4 v[226:229], v[128:129], off offset:16
	global_load_dwordx4 v[230:233], v[128:129], off offset:512
	global_load_dwordx4 v[234:237], v[128:129], off offset:528
	v_or_b32_e32 v204, 16, v194
	v_or_b32_e32 v200, 32, v194
	v_or_b32_e32 v196, 48, v194
	v_ashrrev_i32_e32 v205, 31, v204
	v_ashrrev_i32_e32 v201, 31, v200
	v_ashrrev_i32_e32 v197, 31, v196
	v_lshlrev_b64 v[128:129], 11, v[204:205]
	v_lshlrev_b64 v[130:131], 11, v[200:201]
	v_lshlrev_b64 v[132:133], 11, v[196:197]
	v_lshl_add_u64 v[206:207], v[128:129], 0, v[192:193]
	v_lshl_add_u64 v[202:203], v[130:131], 0, v[192:193]
	v_lshl_add_u64 v[198:199], v[132:133], 0, v[192:193]
	v_lshl_add_u64 v[128:129], v[206:207], 2, s[64:65]
	v_lshl_add_u64 v[130:131], v[202:203], 2, s[64:65]
	v_lshl_add_u64 v[132:133], v[198:199], 2, s[64:65]
	global_load_dwordx4 v[168:171], v[128:129], off offset:16
	global_load_dwordx4 v[172:175], v[128:129], off
	global_load_dwordx4 v[160:163], v[128:129], off offset:528
	global_load_dwordx4 v[164:167], v[128:129], off offset:512
	global_load_dwordx4 v[152:155], v[130:131], off offset:16
	global_load_dwordx4 v[156:159], v[130:131], off
	global_load_dwordx4 v[144:147], v[130:131], off offset:528
	global_load_dwordx4 v[148:151], v[130:131], off offset:512
	global_load_dwordx4 v[136:139], v[132:133], off offset:16
	global_load_dwordx4 v[140:143], v[132:133], off
	s_nop 0
	global_load_dwordx4 v[128:131], v[132:133], off offset:528
	s_nop 0
	global_load_dwordx4 v[132:135], v[132:133], off offset:512
	v_and_b32_e32 v216, 64, v214
	v_xor_b32_e32 v215, 16, v214
	v_add_u32_e32 v216, 64, v216
	v_xor_b32_e32 v217, 32, v214
	v_cmp_lt_i32_e32 vcc, v215, v216
	v_lshl_add_u64 v[238:239], s[70:71], 0, v[238:239]
	v_lshlrev_b64 v[218:219], 1, v[218:219]
	v_cndmask_b32_e32 v215, v214, v215, vcc
	v_cmp_lt_i32_e32 vcc, v217, v216
	v_lshlrev_b32_e32 v216, 2, v215
	v_lshl_add_u64 v[240:241], s[58:59], 0, v[218:219]
	v_cndmask_b32_e32 v217, v214, v217, vcc
	v_lshlrev_b32_e32 v215, 2, v217
	v_or_b32_e32 v218, 0x100, v218
	s_waitcnt vmcnt(0)
	v_pk_add_f32 v[126:127], v[126:127], v[224:225]
	v_pk_add_f32 v[124:125], v[124:125], v[222:223]
	v_pk_add_f32 v[118:119], v[118:119], v[232:233]
	v_pk_add_f32 v[116:117], v[116:117], v[230:231]
	v_pk_add_f32 v[122:123], v[122:123], v[228:229]
	v_pk_add_f32 v[120:121], v[120:121], v[226:227]
	v_pk_add_f32 v[112:113], v[112:113], v[234:235]
	global_store_dwordx4 v[238:239], v[124:127], off
	global_store_dwordx4 v[238:239], v[120:123], off offset:16
	v_cvt_pk_bf16_f32 v222, v124, v125
	v_cvt_pk_bf16_f32 v223, v126, v127
	v_mul_f32_e32 v125, v125, v125
	v_mul_f32_e32 v127, v127, v127
	v_mul_f32_e32 v217, v117, v117
	v_mul_f32_e32 v221, v119, v119
	v_pk_add_f32 v[114:115], v[114:115], v[236:237]
	v_cvt_pk_bf16_f32 v224, v120, v121
	v_cvt_pk_bf16_f32 v225, v122, v123
	v_mul_f32_e32 v121, v121, v121
	v_mul_f32_e32 v123, v123, v123
	v_mul_f32_e32 v226, v113, v113
	v_fmac_f32_e32 v125, v124, v124
	v_fmac_f32_e32 v127, v126, v126
	v_fmac_f32_e32 v217, v116, v116
	v_fmac_f32_e32 v221, v118, v118
	v_mul_f32_e32 v227, v115, v115
	v_fmac_f32_e32 v121, v120, v120
	v_fmac_f32_e32 v123, v122, v122
	v_fmac_f32_e32 v226, v112, v112
	v_add_f32_e32 v120, v125, v127
	v_add_f32_e32 v122, v217, v221
	v_fmac_f32_e32 v227, v114, v114
	v_add_f32_e32 v120, v120, v121
	v_add_f32_e32 v121, v122, v226
	v_add_f32_e32 v120, v123, v120
	v_add_f32_e32 v121, v227, v121
	v_add_f32_e32 v120, v120, v121
	ds_bpermute_b32 v121, v216, v120
	global_store_dwordx4 v[240:241], v[222:225], off
	global_store_dwordx4 v[238:239], v[116:119], off offset:512
	global_store_dwordx4 v[238:239], v[112:115], off offset:528
	s_nop 0
	v_cvt_pk_bf16_f32 v116, v116, v117
	v_cvt_pk_bf16_f32 v117, v118, v119
	v_cvt_pk_bf16_f32 v118, v112, v113
	s_waitcnt lgkmcnt(0)
	v_add_f32_e32 v112, v120, v121
	ds_bpermute_b32 v113, v215, v112
	v_cvt_pk_bf16_f32 v119, v114, v115
	v_lshl_add_u64 v[114:115], s[58:59], 0, v[218:219]
	global_store_dwordx4 v[114:115], v[116:119], off
	s_and_saveexec_b64 s[18:19], s[2:3]
	s_cbranch_execz .LBB0_736
	s_waitcnt lgkmcnt(0)
	v_add_f32_e32 v112, v112, v113
	v_fma_f32 v112, v112, s42, 0.5
	v_trunc_f32_e32 v112, v112
	v_mul_f32_e32 v113, 0x2f800000, v112
	v_floor_f32_e32 v113, v113
	v_fmac_f32_e32 v112, 0xcf800000, v113
	v_cvt_u32_f32_e32 v112, v112
	v_cvt_u32_f32_e32 v113, v113
	v_lshl_add_u64 v[114:115], v[194:195], 3, s[0:1]
	global_atomic_add_x2 v[114:115], v[112:113], off

; #define PG8_STAGE(bufoff, gbase, voff) do { _Pragma("unroll") for (int _i = 0; _i < 2; ++_i) \
;         __builtin_amdgcn_global_load_lds((const unsigned*)((const char*)(gbase) + (voff)[_i]), (LAS unsigned*)(lds + (bufoff) + ldsw + _i * 8192), 16, 0, 0); } while (0)
; #define PG8_LDA(dst, b, h) do { _Pragma("unroll") for (int m = 0; m < 4; ++m) _Pragma("unroll") for (int k = 0; k < 2; ++k) dst[m][k] = *(const LAS bf16x8*)(lds + PG8_SA(b, h) + aoff + m * 2048 + k * 1024); } while (0)
; #define PG8_LDB(dst, b, h) do { _Pragma("unroll") for (int n = 0; n < 2; ++n) _Pragma("unroll") for (int k = 0; k < 2; ++k) dst[n][k] = *(const LAS bf16x8*)(lds + PG8_SB(b, h) + boff + n * 2048 + k * 1024); } while (0)
; #define PG8_MMA(ai, bj, At, Bt) do { __builtin_amdgcn_s_setprio(1); _Pragma("unroll") for (int m = 0; m < 4; ++m) _Pragma("unroll") for (int n = 0; n < 2; ++n) _Pragma("unroll") for (int k = 0; k < 2; ++k) \
;         acc[ai][bj][m][n] = __builtin_amdgcn_mfma_f32_16x16x32_bf16(Bt[n][k], At[m][k], acc[ai][bj][m][n], 0, 0, 0); __builtin_amdgcn_s_setprio(0); } while (0)
; #define PG8_WAIT_V(n) asm volatile("s_waitcnt vmcnt(" #n ")" ::: "memory")
; template <class Epi>
; __device__ __forceinline__ void gemm_phase(ldsp lds, const Gemm g, const StaticOrder& S, const Epi& E) {
;     ...
;         for (int t = 0; t < nt; t += 2) {
;             const bool last = (t == nt - 2);
;             const char* a1 = cA + (size_t)(t + 1) * kstep;
;             const char* a2 = last ? nA : cA + (size_t)(t + 2) * kstep; const char* b2 = last ? nB : cB + (size_t)(t + 2) * kstep;
;             const char* a3 = a2 + kstep; const char* b3 = b2 + kstep;
;             if constexpr (Epi::NPRE > 0) { if (last) E.pre(pre, cur, wr, fr); }
;             if constexpr (Epi::MID_T > 0) { if (t == Epi::MID_T) E.mid(acc, cur, wr, wc, fr, fq); }
;             PG8_LDB(B0, 0, 0); PG8_SCHED; PG8_LDA(At, 0, 0); PG8_STAGE(PG8_SA(1, 1), a1 + hstep, voffA);
;             PG8_WAIT_L(8); PG8_WAIT_V(10); PG8_BAR; PG8_WAIT_L(0); PG8_MMA(0, 0, At, B0); PG8_BAR; PG8_SCHED;
;             PG8_LDB(B1, 0, 1); PG8_STAGE(PG8_SB(0, 0), b2, voffB);
;             PG8_WAIT_V(10); PG8_BAR; PG8_WAIT_L(0); PG8_MMA(0, 1, At, B1); PG8_BAR;
;             PG8_LDA(At, 0, 1); PG8_STAGE(PG8_SA(0, 0), a2, voffA);
;             PG8_WAIT_V(10); PG8_BAR; PG8_WAIT_L(0); PG8_MMA(1, 0, At, B0); PG8_BAR; PG8_SCHED;
.LBB0_816:
	ds_read_b128 v[164:167], v247 offset:0
	ds_read_b128 v[168:171], v247 offset:1024
	ds_read_b128 v[178:181], v247 offset:2048
	ds_read_b128 v[182:185], v247 offset:3072
	s_add_u32 s26, s22, 0xfff80080
	s_addc_u32 s27, s23, -1
	s_and_b64 s[24:25], s[24:25], exec
	s_cselect_b32 s27, s17, s27
	s_cselect_b32 s26, s44, s26
	s_cselect_b32 s25, s15, s47
	s_cselect_b32 s24, s45, s46
	s_add_i32 m0, s29, 0xc000
	ds_read_b128 v[186:189], v177
	ds_read_b128 v[190:193], v177 offset:1024
	ds_read_b128 v[194:197], v177 offset:2048
	ds_read_b128 v[198:201], v177 offset:3072
	ds_read_b128 v[202:205], v177 offset:4096
	ds_read_b128 v[206:209], v177 offset:5120
	ds_read_b128 v[210:213], v177 offset:6144
	ds_read_b128 v[214:217], v177 offset:7168
	global_load_lds_dwordx4 v136, s[22:23]
	s_add_i32 m0, s29, 0xe000
	s_nop 0
	global_load_lds_dwordx4 v138, s[22:23]
	s_waitcnt lgkmcnt(8)
	s_waitcnt vmcnt(10)
	s_barrier
	s_waitcnt lgkmcnt(0)
	s_setprio 1
	s_waitcnt lgkmcnt(0)
	v_mfma_f32_16x16x32_bf16 v[124:127], v[164:167], v[186:189], v[124:127]
	v_mfma_f32_16x16x32_bf16 v[120:123], v[178:181], v[186:189], v[120:123]
	v_mfma_f32_16x16x32_bf16 v[112:115], v[164:167], v[194:197], v[112:115]
	v_mfma_f32_16x16x32_bf16 v[104:107], v[178:181], v[194:197], v[104:107]
	v_mfma_f32_16x16x32_bf16 v[92:95], v[164:167], v[202:205], v[92:95]
	v_mfma_f32_16x16x32_bf16 v[88:91], v[178:181], v[202:205], v[88:91]
	v_mfma_f32_16x16x32_bf16 v[80:83], v[164:167], v[210:213], v[80:83]
	v_mfma_f32_16x16x32_bf16 v[72:75], v[178:181], v[210:213], v[72:75]
	v_mfma_f32_16x16x32_bf16 v[124:127], v[168:171], v[190:193], v[124:127]
	v_mfma_f32_16x16x32_bf16 v[120:123], v[182:185], v[190:193], v[120:123]
	v_mfma_f32_16x16x32_bf16 v[112:115], v[168:171], v[198:201], v[112:115]
	v_mfma_f32_16x16x32_bf16 v[104:107], v[182:185], v[198:201], v[104:107]
	v_mfma_f32_16x16x32_bf16 v[92:95], v[168:171], v[206:209], v[92:95]
	v_mfma_f32_16x16x32_bf16 v[88:91], v[182:185], v[206:209], v[88:91]
	v_mfma_f32_16x16x32_bf16 v[80:83], v[168:171], v[214:217], v[80:83]
	s_barrier
	v_mfma_f32_16x16x32_bf16 v[72:75], v[182:185], v[214:217], v[72:75]
	s_setprio 0
	s_add_i32 s51, s39, s11
	s_add_u32 s98, s24, 0x80
	s_addc_u32 s99, s25, 0
	s_mov_b32 m0, s51
	ds_read_b128 v[222:225], v247 offset:16384
	ds_read_b128 v[226:229], v247 offset:17408
	ds_read_b128 v[230:233], v247 offset:18432
	ds_read_b128 v[234:237], v247 offset:19456
	global_load_lds_dwordx4 v132, s[24:25]
	s_add_i32 m0, s51, 0x2000
	s_nop 0
	global_load_lds_dwordx4 v128, s[24:25]
	s_waitcnt vmcnt(10)
	s_barrier
	s_waitcnt lgkmcnt(0)
	s_setprio 1
	s_waitcnt lgkmcnt(0)
	v_mfma_f32_16x16x32_bf16 v[116:119], v[222:225], v[186:189], v[116:119]
	v_mfma_f32_16x16x32_bf16 v[108:111], v[230:233], v[186:189], v[108:111]
	v_mfma_f32_16x16x32_bf16 v[100:103], v[222:225], v[194:197], v[100:103]
	v_mfma_f32_16x16x32_bf16 v[96:99], v[230:233], v[194:197], v[96:99]
	v_mfma_f32_16x16x32_bf16 v[84:87], v[222:225], v[202:205], v[84:87]
	v_mfma_f32_16x16x32_bf16 v[76:79], v[230:233], v[202:205], v[76:79]
	v_mfma_f32_16x16x32_bf16 v[68:71], v[222:225], v[210:213], v[68:71]
	v_mfma_f32_16x16x32_bf16 v[64:67], v[230:233], v[210:213], v[64:67]
	v_mfma_f32_16x16x32_bf16 v[116:119], v[226:229], v[190:193], v[116:119]
	v_mfma_f32_16x16x32_bf16 v[108:111], v[234:237], v[190:193], v[108:111]
	v_mfma_f32_16x16x32_bf16 v[100:103], v[226:229], v[198:201], v[100:103]
	v_mfma_f32_16x16x32_bf16 v[96:99], v[234:237], v[198:201], v[96:99]
	v_mfma_f32_16x16x32_bf16 v[84:87], v[226:229], v[206:209], v[84:87]
	v_mfma_f32_16x16x32_bf16 v[76:79], v[234:237], v[206:209], v[76:79]
	v_mfma_f32_16x16x32_bf16 v[68:71], v[226:229], v[214:217], v[68:71]
	s_barrier
	v_mfma_f32_16x16x32_bf16 v[64:67], v[234:237], v[214:217], v[64:67]
	s_setprio 0
	s_mov_b32 m0, s29
	s_add_u32 s100, s26, 0x80
	s_addc_u32 s101, s27, 0
	ds_read_b128 v[186:189], v177 offset:16384
	ds_read_b128 v[190:193], v177 offset:17408
	ds_read_b128 v[194:197], v177 offset:18432
	ds_read_b128 v[198:201], v177 offset:19456
	ds_read_b128 v[202:205], v177 offset:20480
	ds_read_b128 v[206:209], v177 offset:21504
	ds_read_b128 v[210:213], v177 offset:22528
	ds_read_b128 v[214:217], v177 offset:23552
	global_load_lds_dwordx4 v134, s[26:27]
	s_mov_b32 m0, s30
	s_nop 0
	global_load_lds_dwordx4 v130, s[26:27]
	s_waitcnt vmcnt(12)
	s_barrier
	s_waitcnt lgkmcnt(0)
	s_setprio 1
	s_waitcnt lgkmcnt(0)
	v_mfma_f32_16x16x32_bf16 v[60:63], v[164:167], v[186:189], v[60:63]
	v_mfma_f32_16x16x32_bf16 v[56:59], v[178:181], v[186:189], v[56:59]
	v_mfma_f32_16x16x32_bf16 v[48:51], v[164:167], v[194:197], v[48:51]
	v_mfma_f32_16x16x32_bf16 v[40:43], v[178:181], v[194:197], v[40:43]
	v_mfma_f32_16x16x32_bf16 v[28:31], v[164:167], v[202:205], v[28:31]
	v_mfma_f32_16x16x32_bf16 v[24:27], v[178:181], v[202:205], v[24:27]
	v_mfma_f32_16x16x32_bf16 v[16:19], v[164:167], v[210:213], v[16:19]
	v_mfma_f32_16x16x32_bf16 v[8:11], v[178:181], v[210:213], v[8:11]
	v_mfma_f32_16x16x32_bf16 v[60:63], v[168:171], v[190:193], v[60:63]
	v_mfma_f32_16x16x32_bf16 v[56:59], v[182:185], v[190:193], v[56:59]
	v_mfma_f32_16x16x32_bf16 v[48:51], v[168:171], v[198:201], v[48:51]
	v_mfma_f32_16x16x32_bf16 v[40:43], v[182:185], v[198:201], v[40:43]
	v_mfma_f32_16x16x32_bf16 v[28:31], v[168:171], v[206:209], v[28:31]
	v_mfma_f32_16x16x32_bf16 v[24:27], v[182:185], v[206:209], v[24:27]
	v_mfma_f32_16x16x32_bf16 v[16:19], v[168:171], v[214:217], v[16:19]
	s_barrier
	v_mfma_f32_16x16x32_bf16 v[8:11], v[182:185], v[214:217], v[8:11]
	s_setprio 0
	s_add_u32 s52, s24, 0x80000
	s_addc_u32 s53, s25, 0
	s_add_i32 s51, s40, s11
	s_mov_b32 m0, s51
	s_nop 0
	global_load_lds_dwordx4 v132, s[52:53]
	s_add_i32 m0, s51, 0x2000
	s_nop 0
	global_load_lds_dwordx4 v128, s[52:53]
	s_waitcnt vmcnt(10)
	s_barrier
; #define PG8_STAGE(bufoff, gbase, voff) do { _Pragma("unroll") for (int _i = 0; _i < 2; ++_i) \
;         __builtin_amdgcn_global_load_lds((const unsigned*)((const char*)(gbase) + (voff)[_i]), (LAS unsigned*)(lds + (bufoff) + ldsw + _i * 8192), 16, 0, 0); } while (0)
; #define PG8_LDA(dst, b, h) do { _Pragma("unroll") for (int m = 0; m < 4; ++m) _Pragma("unroll") for (int k = 0; k < 2; ++k) dst[m][k] = *(const LAS bf16x8*)(lds + PG8_SA(b, h) + aoff + m * 2048 + k * 1024); } while (0)
; #define PG8_LDB(dst, b, h) do { _Pragma("unroll") for (int n = 0; n < 2; ++n) _Pragma("unroll") for (int k = 0; k < 2; ++k) dst[n][k] = *(const LAS bf16x8*)(lds + PG8_SB(b, h) + boff + n * 2048 + k * 1024); } while (0)
; #define PG8_MMA(ai, bj, At, Bt) do { __builtin_amdgcn_s_setprio(1); _Pragma("unroll") for (int m = 0; m < 4; ++m) _Pragma("unroll") for (int n = 0; n < 2; ++n) _Pragma("unroll") for (int k = 0; k < 2; ++k) \
;         acc[ai][bj][m][n] = __builtin_amdgcn_mfma_f32_16x16x32_bf16(Bt[n][k], At[m][k], acc[ai][bj][m][n], 0, 0, 0); __builtin_amdgcn_s_setprio(0); } while (0)
; #define PG8_WAIT_V(n) asm volatile("s_waitcnt vmcnt(" #n ")" ::: "memory")
; #define PG8_WAIT_L(n) asm volatile("s_waitcnt lgkmcnt(" #n ")" ::: "memory")
; #define PG8_BAR __builtin_amdgcn_s_barrier()
; #define PG8_SCHED __builtin_amdgcn_sched_barrier(0)
; template <class Epi>
; __device__ __forceinline__ void gemm_phase(ldsp lds, const Gemm g, const StaticOrder& S, const Epi& E) {
;     ...
;             PG8_WAIT_V(10); PG8_BAR; PG8_MMA(1, 1, At, B1); PG8_BAR;
;             PG8_LDB(B0, 1, 0); PG8_SCHED; PG8_LDA(At, 1, 0); PG8_STAGE(PG8_SA(0, 1), a2 + hstep, voffA);
;             PG8_WAIT_L(8); PG8_WAIT_V(10); PG8_BAR; PG8_WAIT_L(0); PG8_MMA(0, 0, At, B0); PG8_BAR; PG8_SCHED;
;             PG8_LDB(B1, 1, 1); PG8_STAGE(PG8_SB(1, 0), b3, voffB);
;             PG8_WAIT_V(10); PG8_BAR; PG8_WAIT_L(0); PG8_MMA(0, 1, At, B1); PG8_BAR;
	s_nop 3
	s_setprio 1
	v_mfma_f32_16x16x32_bf16 v[52:55], v[222:225], v[186:189], v[52:55]
	v_mfma_f32_16x16x32_bf16 v[44:47], v[230:233], v[186:189], v[44:47]
	v_mfma_f32_16x16x32_bf16 v[36:39], v[222:225], v[194:197], v[36:39]
	v_mfma_f32_16x16x32_bf16 v[32:35], v[230:233], v[194:197], v[32:35]
	v_mfma_f32_16x16x32_bf16 v[20:23], v[222:225], v[202:205], v[20:23]
	v_mfma_f32_16x16x32_bf16 v[12:15], v[230:233], v[202:205], v[12:15]
	v_mfma_f32_16x16x32_bf16 v[4:7], v[222:225], v[210:213], v[4:7]
	v_mfma_f32_16x16x32_bf16 v[0:3], v[230:233], v[210:213], v[0:3]
	v_mfma_f32_16x16x32_bf16 v[52:55], v[226:229], v[190:193], v[52:55]
	v_mfma_f32_16x16x32_bf16 v[44:47], v[234:237], v[190:193], v[44:47]
	v_mfma_f32_16x16x32_bf16 v[36:39], v[226:229], v[198:201], v[36:39]
	v_mfma_f32_16x16x32_bf16 v[32:35], v[234:237], v[198:201], v[32:35]
	v_mfma_f32_16x16x32_bf16 v[20:23], v[226:229], v[206:209], v[20:23]
	v_mfma_f32_16x16x32_bf16 v[12:15], v[234:237], v[206:209], v[12:15]
	v_mfma_f32_16x16x32_bf16 v[4:7], v[226:229], v[214:217], v[4:7]
	s_barrier
	v_mfma_f32_16x16x32_bf16 v[0:3], v[234:237], v[214:217], v[0:3]
	s_setprio 0
	s_add_i32 s51, 0, 0x18000
	ds_read_b128 v[164:167], v247 offset:32768
	ds_read_b128 v[168:171], v247 offset:33792
	ds_read_b128 v[178:181], v247 offset:34816
	ds_read_b128 v[182:185], v247 offset:35840
	s_add_u32 s26, s26, 0x80000
	s_addc_u32 s27, s27, 0
	s_mov_b32 m0, s31
	ds_read_b128 v[186:189], v177 offset:32768
	ds_read_b128 v[190:193], v177 offset:33792
	ds_read_b128 v[194:197], v177 offset:34816
	ds_read_b128 v[198:201], v177 offset:35840
	ds_read_b128 v[202:205], v177 offset:36864
	ds_read_b128 v[206:209], v177 offset:37888
	ds_read_b128 v[210:213], v177 offset:38912
	ds_read_b128 v[214:217], v177 offset:39936
	global_load_lds_dwordx4 v134, s[26:27]
	s_mov_b32 m0, s33
	s_nop 0
	global_load_lds_dwordx4 v130, s[26:27]
	s_waitcnt lgkmcnt(8)
	s_waitcnt vmcnt(10)
	s_barrier
	s_waitcnt lgkmcnt(0)
	s_setprio 1
	s_waitcnt lgkmcnt(0)
	v_mfma_f32_16x16x32_bf16 v[124:127], v[164:167], v[186:189], v[124:127]
	v_mfma_f32_16x16x32_bf16 v[120:123], v[178:181], v[186:189], v[120:123]
	v_mfma_f32_16x16x32_bf16 v[112:115], v[164:167], v[194:197], v[112:115]
	v_mfma_f32_16x16x32_bf16 v[104:107], v[178:181], v[194:197], v[104:107]
	v_mfma_f32_16x16x32_bf16 v[92:95], v[164:167], v[202:205], v[92:95]
	v_mfma_f32_16x16x32_bf16 v[88:91], v[178:181], v[202:205], v[88:91]
	v_mfma_f32_16x16x32_bf16 v[80:83], v[164:167], v[210:213], v[80:83]
	v_mfma_f32_16x16x32_bf16 v[72:75], v[178:181], v[210:213], v[72:75]
	v_mfma_f32_16x16x32_bf16 v[124:127], v[168:171], v[190:193], v[124:127]
	v_mfma_f32_16x16x32_bf16 v[120:123], v[182:185], v[190:193], v[120:123]
	v_mfma_f32_16x16x32_bf16 v[112:115], v[168:171], v[198:201], v[112:115]
	v_mfma_f32_16x16x32_bf16 v[104:107], v[182:185], v[198:201], v[104:107]
	v_mfma_f32_16x16x32_bf16 v[92:95], v[168:171], v[206:209], v[92:95]
	v_mfma_f32_16x16x32_bf16 v[88:91], v[182:185], v[206:209], v[88:91]
	v_mfma_f32_16x16x32_bf16 v[80:83], v[168:171], v[214:217], v[80:83]
	s_barrier
	v_mfma_f32_16x16x32_bf16 v[72:75], v[182:185], v[214:217], v[72:75]
	s_setprio 0
	s_add_i32 s26, 0, 0x1c000
	s_add_i32 s27, s51, s11
	s_mov_b32 m0, s27
	ds_read_b128 v[222:225], v247 offset:49152
	ds_read_b128 v[226:229], v247 offset:50176
	ds_read_b128 v[230:233], v247 offset:51200
	ds_read_b128 v[234:237], v247 offset:52224
	global_load_lds_dwordx4 v132, s[98:99]
	s_add_i32 m0, s27, 0x2000
	s_nop 0
	global_load_lds_dwordx4 v128, s[98:99]
	s_waitcnt vmcnt(10)
	s_barrier
; #define PG8_STAGE(bufoff, gbase, voff) do { _Pragma("unroll") for (int _i = 0; _i < 2; ++_i) \
;         __builtin_amdgcn_global_load_lds((const unsigned*)((const char*)(gbase) + (voff)[_i]), (LAS unsigned*)(lds + (bufoff) + ldsw + _i * 8192), 16, 0, 0); } while (0)
; #define PG8_LDA(dst, b, h) do { _Pragma("unroll") for (int m = 0; m < 4; ++m) _Pragma("unroll") for (int k = 0; k < 2; ++k) dst[m][k] = *(const LAS bf16x8*)(lds + PG8_SA(b, h) + aoff + m * 2048 + k * 1024); } while (0)
; #define PG8_LDB(dst, b, h) do { _Pragma("unroll") for (int n = 0; n < 2; ++n) _Pragma("unroll") for (int k = 0; k < 2; ++k) dst[n][k] = *(const LAS bf16x8*)(lds + PG8_SB(b, h) + boff + n * 2048 + k * 1024); } while (0)
; #define PG8_MMA(ai, bj, At, Bt) do { __builtin_amdgcn_s_setprio(1); _Pragma("unroll") for (int m = 0; m < 4; ++m) _Pragma("unroll") for (int n = 0; n < 2; ++n) _Pragma("unroll") for (int k = 0; k < 2; ++k) \
;         acc[ai][bj][m][n] = __builtin_amdgcn_mfma_f32_16x16x32_bf16(Bt[n][k], At[m][k], acc[ai][bj][m][n], 0, 0, 0); __builtin_amdgcn_s_setprio(0); } while (0)
; #define PG8_WAIT_V(n) asm volatile("s_waitcnt vmcnt(" #n ")" ::: "memory")
; #define PG8_WAIT_L(n) asm volatile("s_waitcnt lgkmcnt(" #n ")" ::: "memory")
; #define PG8_BAR __builtin_amdgcn_s_barrier()
; #define PG8_SCHED __builtin_amdgcn_sched_barrier(0)
; template <class Epi>
; __device__ __forceinline__ void gemm_phase(ldsp lds, const Gemm g, const StaticOrder& S, const Epi& E) {
;     ...
;             PG8_LDB(B1, 1, 1); PG8_STAGE(PG8_SB(1, 0), b3, voffB);
;             PG8_WAIT_V(10); PG8_BAR; PG8_WAIT_L(0); PG8_MMA(0, 1, At, B1); PG8_BAR;
;             PG8_LDA(At, 1, 1); PG8_STAGE(PG8_SA(1, 0), a3, voffA);
;             PG8_WAIT_V(10); PG8_BAR; PG8_WAIT_L(0); PG8_MMA(1, 0, At, B0); PG8_BAR; PG8_SCHED;
;             PG8_STAGE(PG8_SB(1, 1), b3 + hstep, voffB);
;             PG8_WAIT_V(10); PG8_BAR; PG8_MMA(1, 1, At, B1); PG8_BAR;
	s_waitcnt lgkmcnt(0)
	s_setprio 1
	s_waitcnt lgkmcnt(0)
	v_mfma_f32_16x16x32_bf16 v[116:119], v[222:225], v[186:189], v[116:119]
	v_mfma_f32_16x16x32_bf16 v[108:111], v[230:233], v[186:189], v[108:111]
	v_mfma_f32_16x16x32_bf16 v[100:103], v[222:225], v[194:197], v[100:103]
	v_mfma_f32_16x16x32_bf16 v[96:99], v[230:233], v[194:197], v[96:99]
	v_mfma_f32_16x16x32_bf16 v[84:87], v[222:225], v[202:205], v[84:87]
	v_mfma_f32_16x16x32_bf16 v[76:79], v[230:233], v[202:205], v[76:79]
	v_mfma_f32_16x16x32_bf16 v[68:71], v[222:225], v[210:213], v[68:71]
	v_mfma_f32_16x16x32_bf16 v[64:67], v[230:233], v[210:213], v[64:67]
	v_mfma_f32_16x16x32_bf16 v[116:119], v[226:229], v[190:193], v[116:119]
	v_mfma_f32_16x16x32_bf16 v[108:111], v[234:237], v[190:193], v[108:111]
	v_mfma_f32_16x16x32_bf16 v[100:103], v[226:229], v[198:201], v[100:103]
	v_mfma_f32_16x16x32_bf16 v[96:99], v[234:237], v[198:201], v[96:99]
	v_mfma_f32_16x16x32_bf16 v[84:87], v[226:229], v[206:209], v[84:87]
	v_mfma_f32_16x16x32_bf16 v[76:79], v[234:237], v[206:209], v[76:79]
	v_mfma_f32_16x16x32_bf16 v[68:71], v[226:229], v[214:217], v[68:71]
	s_barrier
	v_mfma_f32_16x16x32_bf16 v[64:67], v[234:237], v[214:217], v[64:67]
	s_setprio 0
	s_mov_b32 m0, s35
	ds_read_b128 v[186:189], v177 offset:49152
	ds_read_b128 v[190:193], v177 offset:50176
	ds_read_b128 v[194:197], v177 offset:51200
	ds_read_b128 v[198:201], v177 offset:52224
	ds_read_b128 v[202:205], v177 offset:53248
	ds_read_b128 v[206:209], v177 offset:54272
	ds_read_b128 v[210:213], v177 offset:55296
	ds_read_b128 v[214:217], v177 offset:56320
	global_load_lds_dwordx4 v134, s[100:101]
	s_mov_b32 m0, s36
	s_nop 0
	global_load_lds_dwordx4 v130, s[100:101]
	s_waitcnt vmcnt(12)
	s_barrier
	s_waitcnt lgkmcnt(0)
	s_setprio 1
	s_waitcnt lgkmcnt(0)
	v_mfma_f32_16x16x32_bf16 v[60:63], v[164:167], v[186:189], v[60:63]
	v_mfma_f32_16x16x32_bf16 v[56:59], v[178:181], v[186:189], v[56:59]
	v_mfma_f32_16x16x32_bf16 v[48:51], v[164:167], v[194:197], v[48:51]
	v_mfma_f32_16x16x32_bf16 v[40:43], v[178:181], v[194:197], v[40:43]
	v_mfma_f32_16x16x32_bf16 v[28:31], v[164:167], v[202:205], v[28:31]
	v_mfma_f32_16x16x32_bf16 v[24:27], v[178:181], v[202:205], v[24:27]
	v_mfma_f32_16x16x32_bf16 v[16:19], v[164:167], v[210:213], v[16:19]
	v_mfma_f32_16x16x32_bf16 v[8:11], v[178:181], v[210:213], v[8:11]
	v_mfma_f32_16x16x32_bf16 v[60:63], v[168:171], v[190:193], v[60:63]
	v_mfma_f32_16x16x32_bf16 v[56:59], v[182:185], v[190:193], v[56:59]
	v_mfma_f32_16x16x32_bf16 v[48:51], v[168:171], v[198:201], v[48:51]
	v_mfma_f32_16x16x32_bf16 v[40:43], v[182:185], v[198:201], v[40:43]
	v_mfma_f32_16x16x32_bf16 v[28:31], v[168:171], v[206:209], v[28:31]
	v_mfma_f32_16x16x32_bf16 v[24:27], v[182:185], v[206:209], v[24:27]
	v_mfma_f32_16x16x32_bf16 v[16:19], v[168:171], v[214:217], v[16:19]
	s_barrier
	v_mfma_f32_16x16x32_bf16 v[8:11], v[182:185], v[214:217], v[8:11]
	s_setprio 0
	s_add_u32 s24, s24, 0x80080
	s_addc_u32 s25, s25, 0
	s_add_i32 s26, s26, s11
	s_mov_b32 m0, s26
	s_nop 0
	global_load_lds_dwordx4 v132, s[24:25]
	s_add_i32 m0, s26, 0x2000
	s_nop 0
	global_load_lds_dwordx4 v128, s[24:25]
	s_waitcnt vmcnt(10)
	s_barrier
	s_nop 3
	s_setprio 1
	v_mfma_f32_16x16x32_bf16 v[52:55], v[222:225], v[186:189], v[52:55]
	v_mfma_f32_16x16x32_bf16 v[44:47], v[230:233], v[186:189], v[44:47]
	v_mfma_f32_16x16x32_bf16 v[36:39], v[222:225], v[194:197], v[36:39]
	v_mfma_f32_16x16x32_bf16 v[32:35], v[230:233], v[194:197], v[32:35]
	v_mfma_f32_16x16x32_bf16 v[20:23], v[222:225], v[202:205], v[20:23]
	v_mfma_f32_16x16x32_bf16 v[12:15], v[230:233], v[202:205], v[12:15]
	v_mfma_f32_16x16x32_bf16 v[4:7], v[222:225], v[210:213], v[4:7]
	v_mfma_f32_16x16x32_bf16 v[0:3], v[230:233], v[210:213], v[0:3]
	v_mfma_f32_16x16x32_bf16 v[52:55], v[226:229], v[190:193], v[52:55]
	v_mfma_f32_16x16x32_bf16 v[44:47], v[234:237], v[190:193], v[44:47]
	v_mfma_f32_16x16x32_bf16 v[36:39], v[226:229], v[198:201], v[36:39]
	v_mfma_f32_16x16x32_bf16 v[32:35], v[234:237], v[198:201], v[32:35]
	v_mfma_f32_16x16x32_bf16 v[20:23], v[226:229], v[206:209], v[20:23]
	v_mfma_f32_16x16x32_bf16 v[12:15], v[234:237], v[206:209], v[12:15]
	v_mfma_f32_16x16x32_bf16 v[4:7], v[226:229], v[214:217], v[4:7]
	s_barrier
	v_mfma_f32_16x16x32_bf16 v[0:3], v[234:237], v[214:217], v[0:3]
	s_setprio 0
	s_add_i32 s50, s50, 2
	s_add_u32 s22, s22, 0x100
	s_addc_u32 s23, s23, 0
	s_add_u32 s46, s46, 0x100
	s_addc_u32 s47, s47, 0
	s_cmp_gt_u32 s50, 29
	s_cbranch_scc1 .LBB0_812

; #define PG8_STAGE(bufoff, gbase, voff) do { _Pragma("unroll") for (int _i = 0; _i < 2; ++_i) \
;         __builtin_amdgcn_global_load_lds((const unsigned*)((const char*)(gbase) + (voff)[_i]), (LAS unsigned*)(lds + (bufoff) + ldsw + _i * 8192), 16, 0, 0); } while (0)
; #define PG8_LDA(dst, b, h) do { _Pragma("unroll") for (int m = 0; m < 4; ++m) _Pragma("unroll") for (int k = 0; k < 2; ++k) dst[m][k] = *(const LAS bf16x8*)(lds + PG8_SA(b, h) + aoff + m * 2048 + k * 1024); } while (0)
; #define PG8_LDB(dst, b, h) do { _Pragma("unroll") for (int n = 0; n < 2; ++n) _Pragma("unroll") for (int k = 0; k < 2; ++k) dst[n][k] = *(const LAS bf16x8*)(lds + PG8_SB(b, h) + boff + n * 2048 + k * 1024); } while (0)
; #define PG8_MMA(ai, bj, At, Bt) do { __builtin_amdgcn_s_setprio(1); _Pragma("unroll") for (int m = 0; m < 4; ++m) _Pragma("unroll") for (int n = 0; n < 2; ++n) _Pragma("unroll") for (int k = 0; k < 2; ++k) \
;         acc[ai][bj][m][n] = __builtin_amdgcn_mfma_f32_16x16x32_bf16(Bt[n][k], At[m][k], acc[ai][bj][m][n], 0, 0, 0); __builtin_amdgcn_s_setprio(0); } while (0)
; #define PG8_WAIT_V(n) asm volatile("s_waitcnt vmcnt(" #n ")" ::: "memory")
; template <class Epi>
; __device__ __forceinline__ void gemm_phase(ldsp lds, const Gemm g, const StaticOrder& S, const Epi& E) {
;     ...
;         for (int t = 0; t < nt; t += 2) {
;             const bool last = (t == nt - 2);
;             const char* a1 = cA + (size_t)(t + 1) * kstep;
;             const char* a2 = last ? nA : cA + (size_t)(t + 2) * kstep; const char* b2 = last ? nB : cB + (size_t)(t + 2) * kstep;
;             const char* a3 = a2 + kstep; const char* b3 = b2 + kstep;
;             if constexpr (Epi::NPRE > 0) { if (last) E.pre(pre, cur, wr, fr); }
;             if constexpr (Epi::MID_T > 0) { if (t == Epi::MID_T) E.mid(acc, cur, wr, wc, fr, fq); }
;             PG8_LDB(B0, 0, 0); PG8_SCHED; PG8_LDA(At, 0, 0); PG8_STAGE(PG8_SA(1, 1), a1 + hstep, voffA);
;             PG8_WAIT_L(8); PG8_WAIT_V(10); PG8_BAR; PG8_WAIT_L(0); PG8_MMA(0, 0, At, B0); PG8_BAR; PG8_SCHED;
;             PG8_LDB(B1, 0, 1); PG8_STAGE(PG8_SB(0, 0), b2, voffB);
;             PG8_WAIT_V(10); PG8_BAR; PG8_WAIT_L(0); PG8_MMA(0, 1, At, B1); PG8_BAR;
;             PG8_LDA(At, 0, 1); PG8_STAGE(PG8_SA(0, 0), a2, voffA);
;             PG8_WAIT_V(10); PG8_BAR; PG8_WAIT_L(0); PG8_MMA(1, 0, At, B0); PG8_BAR; PG8_SCHED;
.LBB0_899:
	ds_read_b128 v[128:131], v211
	ds_read_b128 v[132:135], v211 offset:1024
	ds_read_b128 v[136:139], v211 offset:2048
	ds_read_b128 v[140:143], v211 offset:3072
	s_add_u32 s16, s14, 0xffea0080
	s_addc_u32 s17, s15, -1
	s_cmpk_eq_i32 s42, 0x54
	s_cselect_b32 s19, s1, s17
	s_cselect_b32 s18, s0, s16
	s_cselect_b32 s17, s7, s41
	s_cselect_b32 s16, s6, s40
	s_add_i32 m0, s22, 0xc000
	ds_read_b128 v[144:147], v212
	ds_read_b128 v[148:151], v212 offset:1024
	ds_read_b128 v[152:155], v212 offset:2048
	ds_read_b128 v[156:159], v212 offset:3072
	ds_read_b128 v[160:163], v212 offset:4096
	ds_read_b128 v[164:167], v212 offset:5120
	ds_read_b128 v[168:171], v212 offset:6144
	ds_read_b128 v[172:175], v212 offset:7168
	global_load_lds_dwordx4 v184, s[14:15]
	s_add_i32 m0, s22, 0xe000
	s_nop 0
	global_load_lds_dwordx4 v186, s[14:15]
	s_waitcnt lgkmcnt(8)
	s_waitcnt vmcnt(10)
	s_barrier
	s_waitcnt lgkmcnt(0)
	s_setprio 1
	s_waitcnt lgkmcnt(0)
	v_mfma_f32_16x16x32_bf16 v[124:127], v[128:131], v[144:147], v[124:127]
	v_mfma_f32_16x16x32_bf16 v[120:123], v[136:139], v[144:147], v[120:123]
	v_mfma_f32_16x16x32_bf16 v[108:111], v[128:131], v[152:155], v[108:111]
	v_mfma_f32_16x16x32_bf16 v[104:107], v[136:139], v[152:155], v[104:107]
	v_mfma_f32_16x16x32_bf16 v[92:95], v[128:131], v[160:163], v[92:95]
	v_mfma_f32_16x16x32_bf16 v[88:91], v[136:139], v[160:163], v[88:91]
	v_mfma_f32_16x16x32_bf16 v[76:79], v[128:131], v[168:171], v[76:79]
	v_mfma_f32_16x16x32_bf16 v[72:75], v[136:139], v[168:171], v[72:75]
	v_mfma_f32_16x16x32_bf16 v[124:127], v[132:135], v[148:151], v[124:127]
	v_mfma_f32_16x16x32_bf16 v[120:123], v[140:143], v[148:151], v[120:123]
	v_mfma_f32_16x16x32_bf16 v[108:111], v[132:135], v[156:159], v[108:111]
	v_mfma_f32_16x16x32_bf16 v[104:107], v[140:143], v[156:159], v[104:107]
	v_mfma_f32_16x16x32_bf16 v[92:95], v[132:135], v[164:167], v[92:95]
	v_mfma_f32_16x16x32_bf16 v[88:91], v[140:143], v[164:167], v[88:91]
	v_mfma_f32_16x16x32_bf16 v[76:79], v[132:135], v[172:175], v[76:79]
	s_barrier
	v_mfma_f32_16x16x32_bf16 v[72:75], v[140:143], v[172:175], v[72:75]
	s_setprio 0
	s_add_i32 s43, s33, s21
	s_add_u32 s98, s16, 0x80
	s_addc_u32 s99, s17, 0
	s_mov_b32 m0, s43
	ds_read_b128 v[192:195], v213
	ds_read_b128 v[196:199], v213 offset:1024
	ds_read_b128 v[200:203], v213 offset:2048
	ds_read_b128 v[204:207], v213 offset:3072
	global_load_lds_dwordx4 v178, s[16:17]
	s_add_i32 m0, s43, 0x2000
	s_nop 0
	global_load_lds_dwordx4 v182, s[16:17]
	s_waitcnt vmcnt(10)
	s_barrier
	s_waitcnt lgkmcnt(0)
	s_setprio 1
	s_waitcnt lgkmcnt(0)
	v_mfma_f32_16x16x32_bf16 v[116:119], v[192:195], v[144:147], v[116:119]
	v_mfma_f32_16x16x32_bf16 v[112:115], v[200:203], v[144:147], v[112:115]
	v_mfma_f32_16x16x32_bf16 v[100:103], v[192:195], v[152:155], v[100:103]
	v_mfma_f32_16x16x32_bf16 v[96:99], v[200:203], v[152:155], v[96:99]
	v_mfma_f32_16x16x32_bf16 v[84:87], v[192:195], v[160:163], v[84:87]
	v_mfma_f32_16x16x32_bf16 v[80:83], v[200:203], v[160:163], v[80:83]
	v_mfma_f32_16x16x32_bf16 v[68:71], v[192:195], v[168:171], v[68:71]
	v_mfma_f32_16x16x32_bf16 v[64:67], v[200:203], v[168:171], v[64:67]
	v_mfma_f32_16x16x32_bf16 v[116:119], v[196:199], v[148:151], v[116:119]
	v_mfma_f32_16x16x32_bf16 v[112:115], v[204:207], v[148:151], v[112:115]
	v_mfma_f32_16x16x32_bf16 v[100:103], v[196:199], v[156:159], v[100:103]
	v_mfma_f32_16x16x32_bf16 v[96:99], v[204:207], v[156:159], v[96:99]
	v_mfma_f32_16x16x32_bf16 v[84:87], v[196:199], v[164:167], v[84:87]
	v_mfma_f32_16x16x32_bf16 v[80:83], v[204:207], v[164:167], v[80:83]
	v_mfma_f32_16x16x32_bf16 v[68:71], v[196:199], v[172:175], v[68:71]
	s_barrier
	v_mfma_f32_16x16x32_bf16 v[64:67], v[204:207], v[172:175], v[64:67]
	s_setprio 0
	s_mov_b32 m0, s22
	s_add_u32 s100, s18, 0x80
	s_addc_u32 s101, s19, 0
	ds_read_b128 v[144:147], v212 offset:16384
	ds_read_b128 v[148:151], v212 offset:17408
	ds_read_b128 v[152:155], v212 offset:18432
	ds_read_b128 v[156:159], v212 offset:19456
	ds_read_b128 v[160:163], v212 offset:20480
	ds_read_b128 v[164:167], v212 offset:21504
	ds_read_b128 v[168:171], v212 offset:22528
	ds_read_b128 v[172:175], v212 offset:23552
	global_load_lds_dwordx4 v176, s[18:19]
	s_mov_b32 m0, s23
	s_nop 0
	global_load_lds_dwordx4 v180, s[18:19]
	s_waitcnt vmcnt(12)
	s_barrier
	s_waitcnt lgkmcnt(0)
	s_setprio 1
	s_waitcnt lgkmcnt(0)
	v_mfma_f32_16x16x32_bf16 v[60:63], v[128:131], v[144:147], v[60:63]
	v_mfma_f32_16x16x32_bf16 v[56:59], v[136:139], v[144:147], v[56:59]
	v_mfma_f32_16x16x32_bf16 v[44:47], v[128:131], v[152:155], v[44:47]
	v_mfma_f32_16x16x32_bf16 v[40:43], v[136:139], v[152:155], v[40:43]
	v_mfma_f32_16x16x32_bf16 v[28:31], v[128:131], v[160:163], v[28:31]
	v_mfma_f32_16x16x32_bf16 v[24:27], v[136:139], v[160:163], v[24:27]
	v_mfma_f32_16x16x32_bf16 v[12:15], v[128:131], v[168:171], v[12:15]
	v_mfma_f32_16x16x32_bf16 v[8:11], v[136:139], v[168:171], v[8:11]
	v_mfma_f32_16x16x32_bf16 v[60:63], v[132:135], v[148:151], v[60:63]
	v_mfma_f32_16x16x32_bf16 v[56:59], v[140:143], v[148:151], v[56:59]
	v_mfma_f32_16x16x32_bf16 v[44:47], v[132:135], v[156:159], v[44:47]
	v_mfma_f32_16x16x32_bf16 v[40:43], v[140:143], v[156:159], v[40:43]
	v_mfma_f32_16x16x32_bf16 v[28:31], v[132:135], v[164:167], v[28:31]
	v_mfma_f32_16x16x32_bf16 v[24:27], v[140:143], v[164:167], v[24:27]
	v_mfma_f32_16x16x32_bf16 v[12:15], v[132:135], v[172:175], v[12:15]
	s_barrier
	v_mfma_f32_16x16x32_bf16 v[8:11], v[140:143], v[172:175], v[8:11]
	s_setprio 0
	s_add_u32 s44, s16, 0x160000
	s_addc_u32 s45, s17, 0
	s_add_i32 s43, s34, s21
	s_mov_b32 m0, s43
	s_nop 0
	global_load_lds_dwordx4 v178, s[44:45]
	s_add_i32 m0, s43, 0x2000
	s_nop 0
	global_load_lds_dwordx4 v182, s[44:45]
	s_waitcnt vmcnt(10)
	s_barrier
; #define PG8_STAGE(bufoff, gbase, voff) do { _Pragma("unroll") for (int _i = 0; _i < 2; ++_i) \
;         __builtin_amdgcn_global_load_lds((const unsigned*)((const char*)(gbase) + (voff)[_i]), (LAS unsigned*)(lds + (bufoff) + ldsw + _i * 8192), 16, 0, 0); } while (0)
; #define PG8_LDA(dst, b, h) do { _Pragma("unroll") for (int m = 0; m < 4; ++m) _Pragma("unroll") for (int k = 0; k < 2; ++k) dst[m][k] = *(const LAS bf16x8*)(lds + PG8_SA(b, h) + aoff + m * 2048 + k * 1024); } while (0)
; #define PG8_LDB(dst, b, h) do { _Pragma("unroll") for (int n = 0; n < 2; ++n) _Pragma("unroll") for (int k = 0; k < 2; ++k) dst[n][k] = *(const LAS bf16x8*)(lds + PG8_SB(b, h) + boff + n * 2048 + k * 1024); } while (0)
; #define PG8_MMA(ai, bj, At, Bt) do { __builtin_amdgcn_s_setprio(1); _Pragma("unroll") for (int m = 0; m < 4; ++m) _Pragma("unroll") for (int n = 0; n < 2; ++n) _Pragma("unroll") for (int k = 0; k < 2; ++k) \
;         acc[ai][bj][m][n] = __builtin_amdgcn_mfma_f32_16x16x32_bf16(Bt[n][k], At[m][k], acc[ai][bj][m][n], 0, 0, 0); __builtin_amdgcn_s_setprio(0); } while (0)
; #define PG8_WAIT_V(n) asm volatile("s_waitcnt vmcnt(" #n ")" ::: "memory")
; #define PG8_WAIT_L(n) asm volatile("s_waitcnt lgkmcnt(" #n ")" ::: "memory")
; #define PG8_BAR __builtin_amdgcn_s_barrier()
; #define PG8_SCHED __builtin_amdgcn_sched_barrier(0)
; template <class Epi>
; __device__ __forceinline__ void gemm_phase(ldsp lds, const Gemm g, const StaticOrder& S, const Epi& E) {
;     ...
;             PG8_WAIT_V(10); PG8_BAR; PG8_MMA(1, 1, At, B1); PG8_BAR;
;             PG8_LDB(B0, 1, 0); PG8_SCHED; PG8_LDA(At, 1, 0); PG8_STAGE(PG8_SA(0, 1), a2 + hstep, voffA);
;             PG8_WAIT_L(8); PG8_WAIT_V(10); PG8_BAR; PG8_WAIT_L(0); PG8_MMA(0, 0, At, B0); PG8_BAR; PG8_SCHED;
;             PG8_LDB(B1, 1, 1); PG8_STAGE(PG8_SB(1, 0), b3, voffB);
;             PG8_WAIT_V(10); PG8_BAR; PG8_WAIT_L(0); PG8_MMA(0, 1, At, B1); PG8_BAR;
	s_nop 3
	s_setprio 1
	v_mfma_f32_16x16x32_bf16 v[52:55], v[192:195], v[144:147], v[52:55]
	v_mfma_f32_16x16x32_bf16 v[48:51], v[200:203], v[144:147], v[48:51]
	v_mfma_f32_16x16x32_bf16 v[36:39], v[192:195], v[152:155], v[36:39]
	v_mfma_f32_16x16x32_bf16 v[32:35], v[200:203], v[152:155], v[32:35]
	v_mfma_f32_16x16x32_bf16 v[20:23], v[192:195], v[160:163], v[20:23]
	v_mfma_f32_16x16x32_bf16 v[16:19], v[200:203], v[160:163], v[16:19]
	v_mfma_f32_16x16x32_bf16 v[4:7], v[192:195], v[168:171], v[4:7]
	v_mfma_f32_16x16x32_bf16 v[0:3], v[200:203], v[168:171], v[0:3]
	v_mfma_f32_16x16x32_bf16 v[52:55], v[196:199], v[148:151], v[52:55]
	v_mfma_f32_16x16x32_bf16 v[48:51], v[204:207], v[148:151], v[48:51]
	v_mfma_f32_16x16x32_bf16 v[36:39], v[196:199], v[156:159], v[36:39]
	v_mfma_f32_16x16x32_bf16 v[32:35], v[204:207], v[156:159], v[32:35]
	v_mfma_f32_16x16x32_bf16 v[20:23], v[196:199], v[164:167], v[20:23]
	v_mfma_f32_16x16x32_bf16 v[16:19], v[204:207], v[164:167], v[16:19]
	v_mfma_f32_16x16x32_bf16 v[4:7], v[196:199], v[172:175], v[4:7]
	s_barrier
	v_mfma_f32_16x16x32_bf16 v[0:3], v[204:207], v[172:175], v[0:3]
	s_setprio 0
	s_add_i32 s43, 0, 0x18000
	ds_read_b128 v[128:131], v247 offset:32768
	ds_read_b128 v[132:135], v247 offset:33792
	ds_read_b128 v[136:139], v247 offset:34816
	ds_read_b128 v[140:143], v247 offset:35840
	s_add_u32 s18, s18, 0x160000
	s_addc_u32 s19, s19, 0
	s_mov_b32 m0, s24
	ds_read_b128 v[144:147], v212 offset:32768
	ds_read_b128 v[148:151], v212 offset:33792
	ds_read_b128 v[152:155], v212 offset:34816
	ds_read_b128 v[156:159], v212 offset:35840
	ds_read_b128 v[160:163], v212 offset:36864
	ds_read_b128 v[164:167], v212 offset:37888
	ds_read_b128 v[168:171], v212 offset:38912
	ds_read_b128 v[172:175], v212 offset:39936
	global_load_lds_dwordx4 v176, s[18:19]
	s_mov_b32 m0, s25
	s_nop 0
	global_load_lds_dwordx4 v180, s[18:19]
	s_waitcnt lgkmcnt(8)
	s_waitcnt vmcnt(10)
	s_barrier
	s_waitcnt lgkmcnt(0)
	s_setprio 1
	s_waitcnt lgkmcnt(0)
	v_mfma_f32_16x16x32_bf16 v[124:127], v[128:131], v[144:147], v[124:127]
	v_mfma_f32_16x16x32_bf16 v[120:123], v[136:139], v[144:147], v[120:123]
	v_mfma_f32_16x16x32_bf16 v[108:111], v[128:131], v[152:155], v[108:111]
	v_mfma_f32_16x16x32_bf16 v[104:107], v[136:139], v[152:155], v[104:107]
	v_mfma_f32_16x16x32_bf16 v[92:95], v[128:131], v[160:163], v[92:95]
	v_mfma_f32_16x16x32_bf16 v[88:91], v[136:139], v[160:163], v[88:91]
	v_mfma_f32_16x16x32_bf16 v[76:79], v[128:131], v[168:171], v[76:79]
	v_mfma_f32_16x16x32_bf16 v[72:75], v[136:139], v[168:171], v[72:75]
	v_mfma_f32_16x16x32_bf16 v[124:127], v[132:135], v[148:151], v[124:127]
	v_mfma_f32_16x16x32_bf16 v[120:123], v[140:143], v[148:151], v[120:123]
	v_mfma_f32_16x16x32_bf16 v[108:111], v[132:135], v[156:159], v[108:111]
	v_mfma_f32_16x16x32_bf16 v[104:107], v[140:143], v[156:159], v[104:107]
	v_mfma_f32_16x16x32_bf16 v[92:95], v[132:135], v[164:167], v[92:95]
	v_mfma_f32_16x16x32_bf16 v[88:91], v[140:143], v[164:167], v[88:91]
	v_mfma_f32_16x16x32_bf16 v[76:79], v[132:135], v[172:175], v[76:79]
	s_barrier
	v_mfma_f32_16x16x32_bf16 v[72:75], v[140:143], v[172:175], v[72:75]
	s_setprio 0
	s_add_i32 s18, 0, 0x1c000
	s_add_i32 s19, s43, s21
	s_mov_b32 m0, s19
	ds_read_b128 v[192:195], v247 offset:49152
	ds_read_b128 v[196:199], v247 offset:50176
	ds_read_b128 v[200:203], v247 offset:51200
	ds_read_b128 v[204:207], v247 offset:52224
	global_load_lds_dwordx4 v178, s[98:99]
	s_add_i32 m0, s19, 0x2000
	s_nop 0
	global_load_lds_dwordx4 v182, s[98:99]
	s_waitcnt vmcnt(10)
	s_barrier
	s_waitcnt lgkmcnt(0)
	s_setprio 1
	s_waitcnt lgkmcnt(0)
	v_mfma_f32_16x16x32_bf16 v[116:119], v[192:195], v[144:147], v[116:119]
	v_mfma_f32_16x16x32_bf16 v[112:115], v[200:203], v[144:147], v[112:115]
	v_mfma_f32_16x16x32_bf16 v[100:103], v[192:195], v[152:155], v[100:103]
	v_mfma_f32_16x16x32_bf16 v[96:99], v[200:203], v[152:155], v[96:99]
	v_mfma_f32_16x16x32_bf16 v[84:87], v[192:195], v[160:163], v[84:87]
	v_mfma_f32_16x16x32_bf16 v[80:83], v[200:203], v[160:163], v[80:83]
	v_mfma_f32_16x16x32_bf16 v[68:71], v[192:195], v[168:171], v[68:71]
	v_mfma_f32_16x16x32_bf16 v[64:67], v[200:203], v[168:171], v[64:67]
	v_mfma_f32_16x16x32_bf16 v[116:119], v[196:199], v[148:151], v[116:119]
	v_mfma_f32_16x16x32_bf16 v[112:115], v[204:207], v[148:151], v[112:115]
	v_mfma_f32_16x16x32_bf16 v[100:103], v[196:199], v[156:159], v[100:103]
	v_mfma_f32_16x16x32_bf16 v[96:99], v[204:207], v[156:159], v[96:99]
	v_mfma_f32_16x16x32_bf16 v[84:87], v[196:199], v[164:167], v[84:87]
	v_mfma_f32_16x16x32_bf16 v[80:83], v[204:207], v[164:167], v[80:83]
	v_mfma_f32_16x16x32_bf16 v[68:71], v[196:199], v[172:175], v[68:71]
	s_barrier
	v_mfma_f32_16x16x32_bf16 v[64:67], v[204:207], v[172:175], v[64:67]
	s_setprio 0
	s_mov_b32 m0, s27
	ds_read_b128 v[144:147], v212 offset:49152
	ds_read_b128 v[148:151], v212 offset:50176
	ds_read_b128 v[152:155], v212 offset:51200
	ds_read_b128 v[156:159], v212 offset:52224
	ds_read_b128 v[160:163], v212 offset:53248
	ds_read_b128 v[164:167], v212 offset:54272
	ds_read_b128 v[168:171], v212 offset:55296
	ds_read_b128 v[172:175], v212 offset:56320
	global_load_lds_dwordx4 v176, s[100:101]
	s_mov_b32 m0, s28
	s_nop 0
	global_load_lds_dwordx4 v180, s[100:101]
	s_waitcnt vmcnt(12)
	s_barrier
; #define PG8_STAGE(bufoff, gbase, voff) do { _Pragma("unroll") for (int _i = 0; _i < 2; ++_i) \
;         __builtin_amdgcn_global_load_lds((const unsigned*)((const char*)(gbase) + (voff)[_i]), (LAS unsigned*)(lds + (bufoff) + ldsw + _i * 8192), 16, 0, 0); } while (0)
; #define PG8_WAIT_V(n) asm volatile("s_waitcnt vmcnt(" #n ")" ::: "memory")
; #define PG8_WAIT_L(n) asm volatile("s_waitcnt lgkmcnt(" #n ")" ::: "memory")
; #define PG8_BAR __builtin_amdgcn_s_barrier()
; #define PG8_SCHED __builtin_amdgcn_sched_barrier(0)
; template <class Epi>
; __device__ __forceinline__ void gemm_phase(ldsp lds, const Gemm g, const StaticOrder& S, const Epi& E) {
;     ...
;             PG8_WAIT_V(10); PG8_BAR; PG8_WAIT_L(0); PG8_MMA(1, 0, At, B0); PG8_BAR; PG8_SCHED;
;             PG8_STAGE(PG8_SB(1, 1), b3 + hstep, voffB);
;             PG8_WAIT_V(10); PG8_BAR; PG8_MMA(1, 1, At, B1); PG8_BAR;
;     __device__ __forceinline__ void ld(f32x4 (&xv)[2][2][2], int row0, int col0, int ai, int mh) const {
; #pragma unroll
;         for (int mm = 0; mm < 2; ++mm)
; #pragma unroll
;             for (int bj = 0; bj < 2; ++bj) { const size_t off = (size_t)(row0 + ai * 128 + (2 * mh + mm) * 16) * 2048 + col0 + bj * 128;
;                 xv[mm][bj][0] = *(const f32x4*)(base + off); xv[mm][bj][1] = *(const f32x4*)(base + off + 4); }
;     }
;     __device__ __forceinline__ void fin(const f32x4 (&acc)[2][2][4][2], const f32x4 (&xv)[2][2][2], int row0, int col0, int fq, int ai, int mh) const {
; #pragma unroll
;         for (int mm = 0; mm < 2; ++mm) { const int m = 2 * mh + mm; const int row = row0 + ai * 128 + m * 16; float sq = 0.f;
; #pragma unroll
;             for (int bj = 0; bj < 2; ++bj) { const size_t off = (size_t)row * 2048 + col0 + bj * 128;
;                 const f32x4 y0 = xv[mm][bj][0] + acc[ai][bj][m][0], y1 = xv[mm][bj][1] + acc[ai][bj][m][1];
;                 *(f32x4*)(out + off) = y0; *(f32x4*)(out + off + 4) = y1;
;                 if (ob) *(u32x4*)(ob + off) = pack8(y0, y1);
;                 sq += (y0[0] * y0[0] + y0[1] * y0[1]) + (y0[2] * y0[2] + y0[3] * y0[3]) + (y1[0] * y1[0] + y1[1] * y1[1]) + (y1[2] * y1[2] + y1[3] * y1[3]); }
;             sq += __shfl_xor(sq, 16); sq += __shfl_xor(sq, 32);
;             if (fq == 0) atomicAdd(ssq + row, (unsigned long long)(sq * 16777216.0f + 0.5f)); }
	s_waitcnt lgkmcnt(0)
	s_setprio 1
	s_waitcnt lgkmcnt(0)
	v_mfma_f32_16x16x32_bf16 v[60:63], v[128:131], v[144:147], v[60:63]
	v_mfma_f32_16x16x32_bf16 v[56:59], v[136:139], v[144:147], v[56:59]
	v_mfma_f32_16x16x32_bf16 v[44:47], v[128:131], v[152:155], v[44:47]
	v_mfma_f32_16x16x32_bf16 v[40:43], v[136:139], v[152:155], v[40:43]
	v_mfma_f32_16x16x32_bf16 v[28:31], v[128:131], v[160:163], v[28:31]
	v_mfma_f32_16x16x32_bf16 v[24:27], v[136:139], v[160:163], v[24:27]
	v_mfma_f32_16x16x32_bf16 v[12:15], v[128:131], v[168:171], v[12:15]
	v_mfma_f32_16x16x32_bf16 v[8:11], v[136:139], v[168:171], v[8:11]
	v_mfma_f32_16x16x32_bf16 v[60:63], v[132:135], v[148:151], v[60:63]
	v_mfma_f32_16x16x32_bf16 v[56:59], v[140:143], v[148:151], v[56:59]
	v_mfma_f32_16x16x32_bf16 v[44:47], v[132:135], v[156:159], v[44:47]
	v_mfma_f32_16x16x32_bf16 v[40:43], v[140:143], v[156:159], v[40:43]
	v_mfma_f32_16x16x32_bf16 v[28:31], v[132:135], v[164:167], v[28:31]
	v_mfma_f32_16x16x32_bf16 v[24:27], v[140:143], v[164:167], v[24:27]
	v_mfma_f32_16x16x32_bf16 v[12:15], v[132:135], v[172:175], v[12:15]
	s_barrier
	v_mfma_f32_16x16x32_bf16 v[8:11], v[140:143], v[172:175], v[8:11]
	s_setprio 0
	s_add_u32 s16, s16, 0x160080
	s_addc_u32 s17, s17, 0
	s_add_i32 s18, s18, s21
	s_mov_b32 m0, s18
	s_nop 0
	global_load_lds_dwordx4 v178, s[16:17]
	s_add_i32 m0, s18, 0x2000
	s_nop 0
	global_load_lds_dwordx4 v182, s[16:17]
	s_waitcnt vmcnt(10)
	s_barrier
	s_nop 3
	s_setprio 1
	v_mfma_f32_16x16x32_bf16 v[52:55], v[192:195], v[144:147], v[52:55]
	v_mfma_f32_16x16x32_bf16 v[48:51], v[200:203], v[144:147], v[48:51]
	v_mfma_f32_16x16x32_bf16 v[36:39], v[192:195], v[152:155], v[36:39]
	v_mfma_f32_16x16x32_bf16 v[32:35], v[200:203], v[152:155], v[32:35]
	v_mfma_f32_16x16x32_bf16 v[20:23], v[192:195], v[160:163], v[20:23]
	v_mfma_f32_16x16x32_bf16 v[16:19], v[200:203], v[160:163], v[16:19]
	v_mfma_f32_16x16x32_bf16 v[4:7], v[192:195], v[168:171], v[4:7]
	v_mfma_f32_16x16x32_bf16 v[0:3], v[200:203], v[168:171], v[0:3]
	v_mfma_f32_16x16x32_bf16 v[52:55], v[196:199], v[148:151], v[52:55]
	v_mfma_f32_16x16x32_bf16 v[48:51], v[204:207], v[148:151], v[48:51]
	v_mfma_f32_16x16x32_bf16 v[36:39], v[196:199], v[156:159], v[36:39]
	v_mfma_f32_16x16x32_bf16 v[32:35], v[204:207], v[156:159], v[32:35]
	v_mfma_f32_16x16x32_bf16 v[20:23], v[196:199], v[164:167], v[20:23]
	v_mfma_f32_16x16x32_bf16 v[16:19], v[204:207], v[164:167], v[16:19]
	v_mfma_f32_16x16x32_bf16 v[4:7], v[196:199], v[172:175], v[4:7]
	s_barrier
	v_mfma_f32_16x16x32_bf16 v[0:3], v[204:207], v[172:175], v[0:3]
	s_setprio 0
	s_add_i32 s42, s42, 2
	s_add_u32 s14, s14, 0x100
	s_addc_u32 s15, s15, 0
	s_add_u32 s40, s40, 0x100
	s_addc_u32 s41, s41, 0
	s_cmpk_gt_u32 s42, 0x55
	s_cbranch_scc0 .LBB0_899
	v_lshl_add_u32 v192, s38, 8, v208
	v_lshl_or_b32 v128, s39, 8, v210
	v_ashrrev_i32_e32 v193, 31, v192
	v_ashrrev_i32_e32 v129, 31, v128
	v_lshlrev_b64 v[130:131], 13, v[192:193]
	v_lshl_add_u64 v[130:131], s[70:71], 0, v[130:131]
	v_lshlrev_b64 v[194:195], 2, v[128:129]
	v_lshl_add_u64 v[234:235], v[130:131], 0, v[194:195]
	global_load_dwordx4 v[216:219], v[234:235], off
	global_load_dwordx4 v[222:225], v[234:235], off offset:16
	global_load_dwordx4 v[226:229], v[234:235], off offset:512
	global_load_dwordx4 v[230:233], v[234:235], off offset:528
	v_or_b32_e32 v204, 16, v192
	v_or_b32_e32 v200, 32, v192
	v_or_b32_e32 v196, 48, v192
	v_ashrrev_i32_e32 v205, 31, v204
	v_ashrrev_i32_e32 v201, 31, v200
	v_ashrrev_i32_e32 v197, 31, v196
	v_lshlrev_b64 v[128:129], 13, v[204:205]
	v_lshlrev_b64 v[130:131], 13, v[200:201]
	v_lshlrev_b64 v[132:133], 13, v[196:197]
	v_lshl_add_u64 v[128:129], s[70:71], 0, v[128:129]
	v_lshl_add_u64 v[130:131], s[70:71], 0, v[130:131]
	v_lshl_add_u64 v[132:133], s[70:71], 0, v[132:133]
	v_lshl_add_u64 v[206:207], v[128:129], 0, v[194:195]
	v_lshl_add_u64 v[202:203], v[130:131], 0, v[194:195]
	v_lshl_add_u64 v[198:199], v[132:133], 0, v[194:195]
	global_load_dwordx4 v[168:171], v[206:207], off offset:16
	global_load_dwordx4 v[172:175], v[206:207], off
	global_load_dwordx4 v[160:163], v[206:207], off offset:528
	global_load_dwordx4 v[164:167], v[206:207], off offset:512
	global_load_dwordx4 v[152:155], v[202:203], off offset:16
	global_load_dwordx4 v[156:159], v[202:203], off
	global_load_dwordx4 v[144:147], v[202:203], off offset:528
	global_load_dwordx4 v[148:151], v[202:203], off offset:512
	global_load_dwordx4 v[136:139], v[198:199], off offset:16
	global_load_dwordx4 v[140:143], v[198:199], off
	global_load_dwordx4 v[128:131], v[198:199], off offset:528
	global_load_dwordx4 v[132:135], v[198:199], off offset:512
	v_and_b32_e32 v221, 64, v214
	v_xor_b32_e32 v215, 16, v214
	v_add_u32_e32 v221, 64, v221
	v_cmp_lt_i32_e32 vcc, v215, v221
	s_waitcnt vmcnt(0)
	v_pk_add_f32 v[126:127], v[126:127], v[218:219]
	v_pk_add_f32 v[124:125], v[124:125], v[216:217]
	v_pk_add_f32 v[118:119], v[118:119], v[228:229]
	v_pk_add_f32 v[116:117], v[116:117], v[226:227]
	v_pk_add_f32 v[120:121], v[120:121], v[222:223]
	v_pk_add_f32 v[222:223], v[112:113], v[230:231]
	v_mul_f32_e32 v112, v125, v125
	v_mul_f32_e32 v113, v127, v127
	v_mul_f32_e32 v216, v117, v117
	v_mul_f32_e32 v217, v119, v119
	v_pk_add_f32 v[122:123], v[122:123], v[224:225]
	v_pk_add_f32 v[224:225], v[114:115], v[232:233]
	v_mul_f32_e32 v114, v121, v121
	v_mul_f32_e32 v218, v223, v223
	v_fmac_f32_e32 v112, v124, v124
	v_fmac_f32_e32 v113, v126, v126
	v_fmac_f32_e32 v216, v116, v116
	v_fmac_f32_e32 v217, v118, v118
	v_mul_f32_e32 v115, v123, v123
	v_mul_f32_e32 v219, v225, v225
	v_fmac_f32_e32 v114, v120, v120
	v_fmac_f32_e32 v218, v222, v222
	v_add_f32_e32 v112, v112, v113
	v_add_f32_e32 v113, v216, v217
	v_fmac_f32_e32 v115, v122, v122
	v_fmac_f32_e32 v219, v224, v224
	v_add_f32_e32 v112, v112, v114
	v_add_f32_e32 v113, v113, v218
	v_cndmask_b32_e32 v215, v214, v215, vcc
	v_add_f32_e32 v112, v115, v112
	v_add_f32_e32 v113, v219, v113
	v_lshlrev_b32_e32 v215, 2, v215
	v_add_f32_e32 v112, v112, v113
	ds_bpermute_b32 v113, v215, v112
	v_xor_b32_e32 v114, 32, v214
	v_cmp_lt_i32_e32 vcc, v114, v221
	global_store_dwordx4 v[234:235], v[124:127], off
	global_store_dwordx4 v[234:235], v[120:123], off offset:16
	global_store_dwordx4 v[234:235], v[116:119], off offset:512
	global_store_dwordx4 v[234:235], v[222:225], off offset:528
	v_cndmask_b32_e32 v114, v214, v114, vcc
	v_lshlrev_b32_e32 v216, 2, v114
	s_waitcnt lgkmcnt(0)
	v_add_f32_e32 v112, v112, v113
	ds_bpermute_b32 v113, v216, v112
	s_and_saveexec_b64 s[14:15], s[2:3]
	s_cbranch_execz .LBB0_902
	s_waitcnt lgkmcnt(0)
	v_add_f32_e32 v112, v112, v113
	v_fma_f32 v112, v112, s35, 0.5
	v_trunc_f32_e32 v112, v112
	v_mul_f32_e32 v113, 0x2f800000, v112
	v_floor_f32_e32 v113, v113
	v_fmac_f32_e32 v112, 0xcf800000, v113
	v_cvt_u32_f32_e32 v112, v112
	v_cvt_u32_f32_e32 v113, v113
	v_lshl_add_u64 v[114:115], v[192:193], 3, s[8:9]
	global_atomic_add_x2 v[114:115], v[112:113], off
